# P4 prompt scan rewritten by hand: 4 consumer waves (4 rows x16 lanes x4 keys), 2 producer waves with step x channel-octet lane map (8-lane reductions), converter waves unchanged
# speedup vs baseline: 1.0849x; 1.0849x over previous
; __global__ void __launch_bounds__(NTHR) hymba_fwd(Params P) {
;     ...
;             const int wv = __builtin_amdgcn_readfirstlane(tid >> 6);
;             if (wv < 2) {
;     ...
;               const int pw = (wv & 1) + ((wv >> 2) << 1), ch = h * 64 + lane;
;               const float c_kk = k_k[ch], c_ka = k_a[ch], c_rk = r_k[ch], mu_r = mu_shift[ch], mu_k = mu_shift[CW + ch], mu_v = mu_shift[2 * CW + ch];
;               const bf16_t* pbase = Proj + (size_t)(b * TT) * PJP + PW + h * 64; const float* dbase = Dec + (size_t)(b * TT) * CW + h * 64; const bf16_t* abase = Ab + (size_t)(b * TT) * CW + h * 64;
;               constexpr int PD = 2;
;               unsigned short rr[PD][NPS + 1], kr_[PD][NPS + 1], vr[PD][NPS + 1], aa[PD][NPS]; float dd[PD][NPS];
;     ...
;               SCAN_LOAD(0, 0); SCAN_LOAD(1, 1);
;               SCAN_PRODUCE(0, 0); SCAN_LOAD(2, 0);
.LBB0_673:
	s_ashr_i32 s35, s34, 6
	s_bfe_u32 s92, s34, 0x40002
	s_and_b32 s93, s34, 3
	v_readfirstlane_b32 s95, v137
	s_cmp_gt_i32 s95, 3
	s_mov_b64 s[4:5], -1
	s_cbranch_scc0 .LBB0_851
	s_and_b32 s8, s95, 0x7ffffffe
	s_cmp_lg_u32 s8, 4
	v_lshlrev_b32_e32 v98, 2, v136
	s_cbranch_scc0 .LBB0_755
	s_add_i32 s15, s95, -6
	v_and_b32_e32 v230, 7, v136
	v_lshrrev_b32_e32 v231, 3, v136
	v_readlane_b32 s4, v234, 0
	v_readlane_b32 s5, v234, 1
	s_nop 3
	s_sub_u32 s4, s4, 0xe8
	s_subb_u32 s5, s5, 0
	s_load_dwordx2 s[22:23], s[4:5], 0x48
	s_load_dwordx4 s[8:11], s[4:5], 0x78
	s_load_dwordx2 s[26:27], s[4:5], 0x88
	s_lshl_b32 s33, s92, 8
	v_lshl_add_u32 v232, v230, 5, s33
	s_waitcnt lgkmcnt(0)
	s_add_u32 s60, s22, 0x1000
	s_addc_u32 s61, s23, 0
	s_add_u32 s62, s22, 0x2000
	s_addc_u32 s63, s23, 0
	global_load_dwordx4 v[2:5], v232, s[22:23]
	global_load_dwordx4 v[6:9], v232, s[22:23] offset:16
	global_load_dwordx4 v[10:13], v232, s[60:61]
	global_load_dwordx4 v[14:17], v232, s[60:61] offset:16
	global_load_dwordx4 v[18:21], v232, s[62:63]
	global_load_dwordx4 v[22:25], v232, s[62:63] offset:16
	global_load_dwordx4 v[26:29], v232, s[8:9]
	global_load_dwordx4 v[30:33], v232, s[8:9] offset:16
	global_load_dwordx4 v[34:37], v232, s[10:11]
	global_load_dwordx4 v[38:41], v232, s[10:11] offset:16
	global_load_dwordx4 v[50:53], v232, s[26:27]
	global_load_dwordx4 v[54:57], v232, s[26:27] offset:16
	s_lshl_b32 s4, s35, 11
	s_lshl_b32 s5, s15, 4
	s_add_i32 s4, s4, s5
	s_mul_i32 s5, s4, 0x2400
	s_lshl_b32 s33, s92, 7
	s_add_i32 s33, s33, 0x800
	s_add_u32 s56, s90, 0x7f00000
	s_addc_u32 s57, s91, 0
	s_add_u32 s56, s56, s5
	s_addc_u32 s57, s57, 0
	s_add_u32 s56, s56, s33
	s_addc_u32 s57, s57, 0
	s_sub_u32 s56, s56, 0x2400
	s_subb_u32 s57, s57, 0
	s_add_u32 s58, s56, 0x1000
	s_addc_u32 s59, s57, 0
	s_lshl_b32 s5, s4, 11
	s_lshl_b32 s33, s92, 7
	s_add_u32 s60, s90, 0xc940000
	s_addc_u32 s61, s91, 0
	s_add_u32 s60, s60, s5
	s_addc_u32 s61, s61, 0
	s_add_u32 s60, s60, s33
	s_addc_u32 s61, s61, 0
	s_lshl_b32 s5, s4, 12
	s_lshl_b32 s33, s92, 8
	s_add_u32 s62, s88, 0x2000000
	s_addc_u32 s63, s89, 0
	s_add_u32 s62, s62, s5
	s_addc_u32 s63, s63, 0
	s_add_u32 s62, s62, s33
	s_addc_u32 s63, s63, 0
	s_lshl_b32 s5, s4, 6
	s_lshl_b32 s33, s92, 2
	s_add_u32 s64, s90, 0x10b50800
	s_addc_u32 s65, s91, 0
	s_add_u32 s64, s64, s5
	s_addc_u32 s65, s65, 0
	s_add_u32 s64, s64, s33
	s_addc_u32 s65, s65, 0
	s_mov_b32 s52, 0x1010101
	s_mov_b32 s53, 0x1010101
	v_mul_u32_u24_e32 v155, 0x2400, v231
	v_lshl_add_u32 v155, v230, 4, v155
	v_add_u32_e32 v0, 0x2400, v155
	v_lshlrev_b32_e32 v197, 11, v231
	v_lshl_add_u32 v197, v230, 4, v197
	v_lshlrev_b32_e32 v226, 12, v231
	v_lshl_add_u32 v226, v230, 5, v226
	v_lshlrev_b32_e32 v227, 6, v231
	v_lshl_add_u32 v228, s15, 4, v231
	v_mul_u32_u24_e32 v228, 0x610, v228
	v_lshl_add_u32 v228, v230, 5, v228
	v_add_u32_e32 v229, 0xc200, v228
	global_load_dwordx4 v[58:61], v0, s[56:57]
	global_load_dwordx4 v[62:65], v0, s[56:57] offset:2048
	global_load_dwordx4 v[66:69], v0, s[58:59]
	global_load_dwordx4 v[70:73], v155, s[56:57]
	global_load_dwordx4 v[74:77], v155, s[56:57] offset:2048
	global_load_dwordx4 v[78:81], v155, s[58:59]
	global_load_dwordx4 v[82:85], v197, s[60:61]
	global_load_dwordx4 v[86:89], v226, s[62:63]
	global_load_dwordx4 v[90:93], v226, s[62:63] offset:16
	s_add_u32 s56, s56, 0x12000
	s_addc_u32 s57, s57, 0
	s_add_u32 s58, s58, 0x12000
	s_addc_u32 s59, s59, 0
	s_add_u32 s60, s60, 0x4000
	s_addc_u32 s61, s61, 0
	s_add_u32 s62, s62, 0x8000
	s_addc_u32 s63, s63, 0
	global_load_dwordx4 v[94:97], v0, s[56:57]
	global_load_dwordx4 v[98:101], v0, s[56:57] offset:2048
	global_load_dwordx4 v[102:105], v0, s[58:59]
	global_load_dwordx4 v[106:109], v155, s[56:57]
	global_load_dwordx4 v[110:113], v155, s[56:57] offset:2048
	global_load_dwordx4 v[114:117], v155, s[58:59]
	global_load_dwordx4 v[118:121], v197, s[60:61]
	global_load_dwordx4 v[122:125], v226, s[62:63]
	global_load_dwordx4 v[126:129], v226, s[62:63] offset:16
	s_add_u32 s56, s56, 0x36000
	s_addc_u32 s57, s57, 0
	s_add_u32 s58, s58, 0x36000
	s_addc_u32 s59, s59, 0
	s_add_u32 s60, s60, 0xc000
	s_addc_u32 s61, s61, 0
	s_add_u32 s62, s62, 0x18000
	s_addc_u32 s63, s63, 0
	global_load_dwordx4 v[130:133], v0, s[56:57]
	global_load_dwordx4 v[140:143], v0, s[56:57] offset:2048
	global_load_dwordx4 v[144:147], v0, s[58:59]
	global_load_dwordx4 v[156:159], v155, s[56:57]
	global_load_dwordx4 v[160:163], v155, s[56:57] offset:2048
	global_load_dwordx4 v[164:167], v155, s[58:59]
	global_load_dwordx4 v[168:171], v197, s[60:61]
	global_load_dwordx4 v[172:175], v226, s[62:63]
	global_load_dwordx4 v[176:179], v226, s[62:63] offset:16
	s_add_u32 s56, s56, 0x12000
	s_addc_u32 s57, s57, 0
	s_add_u32 s58, s58, 0x12000
	s_addc_u32 s59, s59, 0
	s_add_u32 s60, s60, 0x4000
	s_addc_u32 s61, s61, 0
	s_add_u32 s62, s62, 0x8000
	s_addc_u32 s63, s63, 0
	s_waitcnt vmcnt(27)
	v_sub_f32_e32 v42, 1.0, v34
	v_sub_f32_e32 v43, 1.0, v35
	v_sub_f32_e32 v44, 1.0, v36
	v_sub_f32_e32 v45, 1.0, v37
	v_sub_f32_e32 v46, 1.0, v38
	v_sub_f32_e32 v47, 1.0, v39
	v_sub_f32_e32 v48, 1.0, v40
	v_sub_f32_e32 v49, 1.0, v41
	s_waitcnt vmcnt(18)
	s_cmp_eq_u32 s15, 0
	s_cbranch_scc0 .Lp4p_nofix
	s_mov_b64 exec, 0xff
	v_mov_b32_e32 v70, 0
	v_mov_b32_e32 v71, 0
	v_mov_b32_e32 v72, 0
	v_mov_b32_e32 v73, 0
	v_mov_b32_e32 v74, 0
	v_mov_b32_e32 v75, 0
	v_mov_b32_e32 v76, 0
	v_mov_b32_e32 v77, 0
	v_mov_b32_e32 v78, 0
	v_mov_b32_e32 v79, 0
	v_mov_b32_e32 v80, 0
	v_mov_b32_e32 v81, 0
	s_mov_b64 exec, -1
.Lp4p_nofix:
	v_mov_b32_e32 v134, 0
	v_mov_b32_e32 v135, 0
	v_mov_b32_e32 v148, 0
	v_mov_b32_e32 v149, 0
	v_mov_b32_e32 v220, 0
	v_mov_b32_e32 v221, 0
	v_mov_b32_e32 v222, 0
	v_mov_b32_e32 v223, 0
	v_lshlrev_b32_e32 v198, 16, v58
	v_and_b32_e32 v199, 0xffff0000, v58
	v_lshlrev_b32_e32 v200, 16, v59
	v_and_b32_e32 v201, 0xffff0000, v59
	v_lshlrev_b32_e32 v202, 16, v70
	v_and_b32_e32 v203, 0xffff0000, v70
	v_lshlrev_b32_e32 v204, 16, v71
	v_and_b32_e32 v205, 0xffff0000, v71
	v_pk_add_f32 v[202:203], v[202:203], v[198:199] neg_lo:[0,1] neg_hi:[0,1]
	v_pk_add_f32 v[204:205], v[204:205], v[200:201] neg_lo:[0,1] neg_hi:[0,1]
	v_pk_fma_f32 v[202:203], v[202:203], v[2:3], v[198:199]
	v_pk_fma_f32 v[204:205], v[204:205], v[4:5], v[200:201]
	v_lshlrev_b32_e32 v198, 16, v62
	v_and_b32_e32 v199, 0xffff0000, v62
	v_lshlrev_b32_e32 v200, 16, v63
	v_and_b32_e32 v201, 0xffff0000, v63
	v_lshlrev_b32_e32 v206, 16, v74
	v_and_b32_e32 v207, 0xffff0000, v74
	v_lshlrev_b32_e32 v208, 16, v75
	v_and_b32_e32 v209, 0xffff0000, v75
	v_pk_add_f32 v[206:207], v[206:207], v[198:199] neg_lo:[0,1] neg_hi:[0,1]
	v_pk_add_f32 v[208:209], v[208:209], v[200:201] neg_lo:[0,1] neg_hi:[0,1]
	v_pk_fma_f32 v[206:207], v[206:207], v[10:11], v[198:199]
	v_pk_fma_f32 v[208:209], v[208:209], v[12:13], v[200:201]
	v_lshlrev_b32_e32 v198, 16, v66
	v_and_b32_e32 v199, 0xffff0000, v66
	v_lshlrev_b32_e32 v200, 16, v67
	v_and_b32_e32 v201, 0xffff0000, v67
	v_lshlrev_b32_e32 v210, 16, v78
	v_and_b32_e32 v211, 0xffff0000, v78
	v_lshlrev_b32_e32 v212, 16, v79
	v_and_b32_e32 v213, 0xffff0000, v79
	v_pk_add_f32 v[210:211], v[210:211], v[198:199] neg_lo:[0,1] neg_hi:[0,1]
	v_pk_add_f32 v[212:213], v[212:213], v[200:201] neg_lo:[0,1] neg_hi:[0,1]
	v_pk_fma_f32 v[210:211], v[210:211], v[18:19], v[198:199]
	v_pk_fma_f32 v[212:213], v[212:213], v[20:21], v[200:201]
	ds_write_b128 v228, v[210:213] offset:1280
	v_lshlrev_b32_e32 v214, 16, v82
	v_and_b32_e32 v215, 0xffff0000, v82
	v_lshlrev_b32_e32 v216, 16, v83
	v_and_b32_e32 v217, 0xffff0000, v83
	v_pk_mul_f32 v[180:181], v[206:207], v[26:27]
	v_pk_mul_f32 v[182:183], v[208:209], v[28:29]
	v_pk_fma_f32 v[134:135], v[180:181], v[180:181], v[134:135]
	v_pk_fma_f32 v[134:135], v[182:183], v[182:183], v[134:135]
	v_pk_fma_f32 v[198:199], v[214:215], v[34:35], v[42:43]
	v_pk_fma_f32 v[200:201], v[216:217], v[36:37], v[44:45]
	v_pk_mul_f32 v[198:199], v[206:207], v[198:199]
	v_pk_mul_f32 v[200:201], v[208:209], v[200:201]
	ds_write_b128 v228, v[198:201] offset:768
	v_pk_mul_f32 v[206:207], v[198:199], v[202:203]
	v_pk_mul_f32 v[208:209], v[200:201], v[204:205]
	v_pk_add_f32 v[220:221], v[220:221], v[206:207]
	v_pk_add_f32 v[220:221], v[220:221], v[208:209]
	v_pk_fma_f32 v[222:223], v[206:207], v[50:51], v[222:223]
	v_pk_fma_f32 v[222:223], v[208:209], v[52:53], v[222:223]
	v_pk_mul_f32 v[188:189], v[180:181], v[214:215]
	v_pk_mul_f32 v[190:191], v[182:183], v[216:217]
	v_pk_fma_f32 v[148:149], v[188:189], v[202:203], v[148:149]
	v_pk_fma_f32 v[148:149], v[190:191], v[204:205], v[148:149]
	v_pk_mul_f32 v[210:211], v[86:87], v[202:203]
	v_pk_mul_f32 v[212:213], v[88:89], v[204:205]
	ds_write_b128 v228, v[210:213] offset:256
	ds_write_b128 v228, v[86:89] offset:512
	v_lshlrev_b32_e32 v198, 16, v60
	v_and_b32_e32 v199, 0xffff0000, v60
	v_lshlrev_b32_e32 v200, 16, v61
	v_and_b32_e32 v201, 0xffff0000, v61
	v_lshlrev_b32_e32 v202, 16, v72
	v_and_b32_e32 v203, 0xffff0000, v72
	v_lshlrev_b32_e32 v204, 16, v73
	v_and_b32_e32 v205, 0xffff0000, v73
	v_pk_add_f32 v[202:203], v[202:203], v[198:199] neg_lo:[0,1] neg_hi:[0,1]
	v_pk_add_f32 v[204:205], v[204:205], v[200:201] neg_lo:[0,1] neg_hi:[0,1]
	v_pk_fma_f32 v[202:203], v[202:203], v[6:7], v[198:199]
	v_pk_fma_f32 v[204:205], v[204:205], v[8:9], v[200:201]
	v_lshlrev_b32_e32 v198, 16, v64
	v_and_b32_e32 v199, 0xffff0000, v64
	v_lshlrev_b32_e32 v200, 16, v65
	v_and_b32_e32 v201, 0xffff0000, v65
	v_lshlrev_b32_e32 v206, 16, v76
	v_and_b32_e32 v207, 0xffff0000, v76
	v_lshlrev_b32_e32 v208, 16, v77
	v_and_b32_e32 v209, 0xffff0000, v77
	v_pk_add_f32 v[206:207], v[206:207], v[198:199] neg_lo:[0,1] neg_hi:[0,1]
	v_pk_add_f32 v[208:209], v[208:209], v[200:201] neg_lo:[0,1] neg_hi:[0,1]
	v_pk_fma_f32 v[206:207], v[206:207], v[14:15], v[198:199]
	v_pk_fma_f32 v[208:209], v[208:209], v[16:17], v[200:201]
	v_lshlrev_b32_e32 v198, 16, v68
	v_and_b32_e32 v199, 0xffff0000, v68
	v_lshlrev_b32_e32 v200, 16, v69
	v_and_b32_e32 v201, 0xffff0000, v69
	v_lshlrev_b32_e32 v210, 16, v80
	v_and_b32_e32 v211, 0xffff0000, v80
	v_lshlrev_b32_e32 v212, 16, v81
	v_and_b32_e32 v213, 0xffff0000, v81
	v_pk_add_f32 v[210:211], v[210:211], v[198:199] neg_lo:[0,1] neg_hi:[0,1]
	v_pk_add_f32 v[212:213], v[212:213], v[200:201] neg_lo:[0,1] neg_hi:[0,1]
	v_pk_fma_f32 v[210:211], v[210:211], v[22:23], v[198:199]
	v_pk_fma_f32 v[212:213], v[212:213], v[24:25], v[200:201]
	ds_write_b128 v228, v[210:213] offset:1296
	v_lshlrev_b32_e32 v214, 16, v84
	v_and_b32_e32 v215, 0xffff0000, v84
	v_lshlrev_b32_e32 v216, 16, v85
	v_and_b32_e32 v217, 0xffff0000, v85
	v_pk_mul_f32 v[184:185], v[206:207], v[30:31]
	v_pk_mul_f32 v[186:187], v[208:209], v[32:33]
	v_pk_fma_f32 v[134:135], v[184:185], v[184:185], v[134:135]
	v_pk_fma_f32 v[134:135], v[186:187], v[186:187], v[134:135]
	v_pk_fma_f32 v[198:199], v[214:215], v[38:39], v[46:47]
	v_pk_fma_f32 v[200:201], v[216:217], v[40:41], v[48:49]
	v_pk_mul_f32 v[198:199], v[206:207], v[198:199]
	v_pk_mul_f32 v[200:201], v[208:209], v[200:201]
	ds_write_b128 v228, v[198:201] offset:784
	v_pk_mul_f32 v[206:207], v[198:199], v[202:203]
	v_pk_mul_f32 v[208:209], v[200:201], v[204:205]
	v_pk_add_f32 v[220:221], v[220:221], v[206:207]
	v_pk_add_f32 v[220:221], v[220:221], v[208:209]
	v_pk_fma_f32 v[222:223], v[206:207], v[54:55], v[222:223]
	v_pk_fma_f32 v[222:223], v[208:209], v[56:57], v[222:223]
	v_pk_mul_f32 v[192:193], v[184:185], v[214:215]
	v_pk_mul_f32 v[194:195], v[186:187], v[216:217]
	v_pk_fma_f32 v[148:149], v[192:193], v[202:203], v[148:149]
	v_pk_fma_f32 v[148:149], v[194:195], v[204:205], v[148:149]
	v_pk_mul_f32 v[210:211], v[90:91], v[202:203]
	v_pk_mul_f32 v[212:213], v[92:93], v[204:205]
	ds_write_b128 v228, v[210:213] offset:272
	ds_write_b128 v228, v[90:93] offset:528
	v_add_f32_e32 v134, v134, v135
	v_add_f32_e32 v148, v148, v149
	v_add_f32_e32 v219, v220, v221
	v_add_f32_e32 v222, v222, v223
	v_add_f32_dpp v134, v134, v134 quad_perm:[1,0,3,2] row_mask:0xf bank_mask:0xf bound_ctrl:1
	v_add_f32_dpp v148, v148, v148 quad_perm:[1,0,3,2] row_mask:0xf bank_mask:0xf bound_ctrl:1
	v_add_f32_dpp v219, v219, v219 quad_perm:[1,0,3,2] row_mask:0xf bank_mask:0xf bound_ctrl:1
	v_add_f32_dpp v222, v222, v222 quad_perm:[1,0,3,2] row_mask:0xf bank_mask:0xf bound_ctrl:1
	v_add_f32_dpp v134, v134, v134 quad_perm:[2,3,0,1] row_mask:0xf bank_mask:0xf bound_ctrl:1
	v_add_f32_dpp v148, v148, v148 quad_perm:[2,3,0,1] row_mask:0xf bank_mask:0xf bound_ctrl:1
	v_add_f32_dpp v219, v219, v219 quad_perm:[2,3,0,1] row_mask:0xf bank_mask:0xf bound_ctrl:1
	v_add_f32_dpp v222, v222, v222 quad_perm:[2,3,0,1] row_mask:0xf bank_mask:0xf bound_ctrl:1
	v_add_f32_dpp v134, v134, v134 row_half_mirror row_mask:0xf bank_mask:0xf bound_ctrl:1
	v_add_f32_dpp v148, v148, v148 row_half_mirror row_mask:0xf bank_mask:0xf bound_ctrl:1
	v_add_f32_dpp v219, v219, v219 row_half_mirror row_mask:0xf bank_mask:0xf bound_ctrl:1
	v_add_f32_dpp v222, v222, v222 row_half_mirror row_mask:0xf bank_mask:0xf bound_ctrl:1
	v_max_f32_e32 v134, 0x179abe15, v134
	v_rsq_f32_e32 v224, v134
	s_nop 1
	v_mul_f32_e32 v218, v224, v148
	v_pk_mul_f32 v[198:199], v[180:181], v[224:225] op_sel_hi:[1,0] neg_lo:[0,1] neg_hi:[0,1]
	v_pk_mul_f32 v[200:201], v[182:183], v[224:225] op_sel_hi:[1,0] neg_lo:[0,1] neg_hi:[0,1]
	v_pk_mul_f32 v[206:207], v[184:185], v[224:225] op_sel_hi:[1,0] neg_lo:[0,1] neg_hi:[0,1]
	v_pk_mul_f32 v[208:209], v[186:187], v[224:225] op_sel_hi:[1,0] neg_lo:[0,1] neg_hi:[0,1]
	ds_write_b128 v228, v[198:201] offset:0
	ds_write_b128 v228, v[206:209] offset:16
	v_pk_mul_f32 v[214:215], v[188:189], v[224:225] op_sel_hi:[1,0]
	v_pk_mul_f32 v[216:217], v[190:191], v[224:225] op_sel_hi:[1,0]
	v_pk_mul_f32 v[202:203], v[192:193], v[224:225] op_sel_hi:[1,0]
	v_pk_mul_f32 v[204:205], v[194:195], v[224:225] op_sel_hi:[1,0]
	ds_write_b128 v228, v[214:217] offset:1024
	ds_write_b128 v228, v[202:205] offset:1040
	s_mov_b64 exec, s[52:53]
	ds_write_b64 v228, v[218:219] offset:1536
	global_store_dword v227, v222, s[64:65]
	s_mov_b64 exec, -1
	s_add_u32 s64, s64, 0x200
	s_addc_u32 s65, s65, 0
	global_load_dwordx4 v[58:61], v0, s[56:57]
	global_load_dwordx4 v[62:65], v0, s[56:57] offset:2048
	global_load_dwordx4 v[66:69], v0, s[58:59]
	global_load_dwordx4 v[70:73], v155, s[56:57]
	global_load_dwordx4 v[74:77], v155, s[56:57] offset:2048
	global_load_dwordx4 v[78:81], v155, s[58:59]
	global_load_dwordx4 v[82:85], v197, s[60:61]
	global_load_dwordx4 v[86:89], v226, s[62:63]
	global_load_dwordx4 v[90:93], v226, s[62:63] offset:16
	s_add_u32 s56, s56, 0x36000
	s_addc_u32 s57, s57, 0
	s_add_u32 s58, s58, 0x36000
	s_addc_u32 s59, s59, 0
	s_add_u32 s60, s60, 0xc000
	s_addc_u32 s61, s61, 0
	s_add_u32 s62, s62, 0x18000
	s_addc_u32 s63, s63, 0
	s_waitcnt vmcnt(19)
	v_mov_b32_e32 v134, 0
	v_mov_b32_e32 v135, 0
	v_mov_b32_e32 v148, 0
	v_mov_b32_e32 v149, 0
	v_mov_b32_e32 v220, 0
	v_mov_b32_e32 v221, 0
	v_mov_b32_e32 v222, 0
	v_mov_b32_e32 v223, 0
	v_lshlrev_b32_e32 v198, 16, v94
	v_and_b32_e32 v199, 0xffff0000, v94
	v_lshlrev_b32_e32 v200, 16, v95
	v_and_b32_e32 v201, 0xffff0000, v95
	v_lshlrev_b32_e32 v202, 16, v106
	v_and_b32_e32 v203, 0xffff0000, v106
	v_lshlrev_b32_e32 v204, 16, v107
	v_and_b32_e32 v205, 0xffff0000, v107
	v_pk_add_f32 v[202:203], v[202:203], v[198:199] neg_lo:[0,1] neg_hi:[0,1]
	v_pk_add_f32 v[204:205], v[204:205], v[200:201] neg_lo:[0,1] neg_hi:[0,1]
	v_pk_fma_f32 v[202:203], v[202:203], v[2:3], v[198:199]
	v_pk_fma_f32 v[204:205], v[204:205], v[4:5], v[200:201]
	v_lshlrev_b32_e32 v198, 16, v98
	v_and_b32_e32 v199, 0xffff0000, v98
	v_lshlrev_b32_e32 v200, 16, v99
	v_and_b32_e32 v201, 0xffff0000, v99
	v_lshlrev_b32_e32 v206, 16, v110
	v_and_b32_e32 v207, 0xffff0000, v110
	v_lshlrev_b32_e32 v208, 16, v111
	v_and_b32_e32 v209, 0xffff0000, v111
	v_pk_add_f32 v[206:207], v[206:207], v[198:199] neg_lo:[0,1] neg_hi:[0,1]
	v_pk_add_f32 v[208:209], v[208:209], v[200:201] neg_lo:[0,1] neg_hi:[0,1]
	v_pk_fma_f32 v[206:207], v[206:207], v[10:11], v[198:199]
	v_pk_fma_f32 v[208:209], v[208:209], v[12:13], v[200:201]
	v_lshlrev_b32_e32 v198, 16, v102
	v_and_b32_e32 v199, 0xffff0000, v102
	v_lshlrev_b32_e32 v200, 16, v103
	v_and_b32_e32 v201, 0xffff0000, v103
	v_lshlrev_b32_e32 v210, 16, v114
	v_and_b32_e32 v211, 0xffff0000, v114
	v_lshlrev_b32_e32 v212, 16, v115
	v_and_b32_e32 v213, 0xffff0000, v115
	v_pk_add_f32 v[210:211], v[210:211], v[198:199] neg_lo:[0,1] neg_hi:[0,1]
	v_pk_add_f32 v[212:213], v[212:213], v[200:201] neg_lo:[0,1] neg_hi:[0,1]
	v_pk_fma_f32 v[210:211], v[210:211], v[18:19], v[198:199]
	v_pk_fma_f32 v[212:213], v[212:213], v[20:21], v[200:201]
	ds_write_b128 v228, v[210:213] offset:13696
	v_lshlrev_b32_e32 v214, 16, v118
	v_and_b32_e32 v215, 0xffff0000, v118
	v_lshlrev_b32_e32 v216, 16, v119
	v_and_b32_e32 v217, 0xffff0000, v119
	v_pk_mul_f32 v[180:181], v[206:207], v[26:27]
	v_pk_mul_f32 v[182:183], v[208:209], v[28:29]
	v_pk_fma_f32 v[134:135], v[180:181], v[180:181], v[134:135]
	v_pk_fma_f32 v[134:135], v[182:183], v[182:183], v[134:135]
	v_pk_fma_f32 v[198:199], v[214:215], v[34:35], v[42:43]
	v_pk_fma_f32 v[200:201], v[216:217], v[36:37], v[44:45]
	v_pk_mul_f32 v[198:199], v[206:207], v[198:199]
	v_pk_mul_f32 v[200:201], v[208:209], v[200:201]
	ds_write_b128 v228, v[198:201] offset:13184
	v_pk_mul_f32 v[206:207], v[198:199], v[202:203]
	v_pk_mul_f32 v[208:209], v[200:201], v[204:205]
	v_pk_add_f32 v[220:221], v[220:221], v[206:207]
	v_pk_add_f32 v[220:221], v[220:221], v[208:209]
	v_pk_fma_f32 v[222:223], v[206:207], v[50:51], v[222:223]
	v_pk_fma_f32 v[222:223], v[208:209], v[52:53], v[222:223]
	v_pk_mul_f32 v[188:189], v[180:181], v[214:215]
	v_pk_mul_f32 v[190:191], v[182:183], v[216:217]
	v_pk_fma_f32 v[148:149], v[188:189], v[202:203], v[148:149]
	v_pk_fma_f32 v[148:149], v[190:191], v[204:205], v[148:149]
	v_pk_mul_f32 v[210:211], v[122:123], v[202:203]
	v_pk_mul_f32 v[212:213], v[124:125], v[204:205]
	ds_write_b128 v228, v[210:213] offset:12672
	ds_write_b128 v228, v[122:125] offset:12928
	v_lshlrev_b32_e32 v198, 16, v96
	v_and_b32_e32 v199, 0xffff0000, v96
	v_lshlrev_b32_e32 v200, 16, v97
	v_and_b32_e32 v201, 0xffff0000, v97
	v_lshlrev_b32_e32 v202, 16, v108
	v_and_b32_e32 v203, 0xffff0000, v108
	v_lshlrev_b32_e32 v204, 16, v109
	v_and_b32_e32 v205, 0xffff0000, v109
	v_pk_add_f32 v[202:203], v[202:203], v[198:199] neg_lo:[0,1] neg_hi:[0,1]
	v_pk_add_f32 v[204:205], v[204:205], v[200:201] neg_lo:[0,1] neg_hi:[0,1]
	v_pk_fma_f32 v[202:203], v[202:203], v[6:7], v[198:199]
	v_pk_fma_f32 v[204:205], v[204:205], v[8:9], v[200:201]
	v_lshlrev_b32_e32 v198, 16, v100
	v_and_b32_e32 v199, 0xffff0000, v100
	v_lshlrev_b32_e32 v200, 16, v101
	v_and_b32_e32 v201, 0xffff0000, v101
	v_lshlrev_b32_e32 v206, 16, v112
	v_and_b32_e32 v207, 0xffff0000, v112
	v_lshlrev_b32_e32 v208, 16, v113
	v_and_b32_e32 v209, 0xffff0000, v113
	v_pk_add_f32 v[206:207], v[206:207], v[198:199] neg_lo:[0,1] neg_hi:[0,1]
	v_pk_add_f32 v[208:209], v[208:209], v[200:201] neg_lo:[0,1] neg_hi:[0,1]
	v_pk_fma_f32 v[206:207], v[206:207], v[14:15], v[198:199]
	v_pk_fma_f32 v[208:209], v[208:209], v[16:17], v[200:201]
	v_lshlrev_b32_e32 v198, 16, v104
	v_and_b32_e32 v199, 0xffff0000, v104
	v_lshlrev_b32_e32 v200, 16, v105
	v_and_b32_e32 v201, 0xffff0000, v105
	v_lshlrev_b32_e32 v210, 16, v116
	v_and_b32_e32 v211, 0xffff0000, v116
	v_lshlrev_b32_e32 v212, 16, v117
	v_and_b32_e32 v213, 0xffff0000, v117
	v_pk_add_f32 v[210:211], v[210:211], v[198:199] neg_lo:[0,1] neg_hi:[0,1]
	v_pk_add_f32 v[212:213], v[212:213], v[200:201] neg_lo:[0,1] neg_hi:[0,1]
	v_pk_fma_f32 v[210:211], v[210:211], v[22:23], v[198:199]
	v_pk_fma_f32 v[212:213], v[212:213], v[24:25], v[200:201]
	ds_write_b128 v228, v[210:213] offset:13712
	v_lshlrev_b32_e32 v214, 16, v120
	v_and_b32_e32 v215, 0xffff0000, v120
	v_lshlrev_b32_e32 v216, 16, v121
	v_and_b32_e32 v217, 0xffff0000, v121
	v_pk_mul_f32 v[184:185], v[206:207], v[30:31]
	v_pk_mul_f32 v[186:187], v[208:209], v[32:33]
	v_pk_fma_f32 v[134:135], v[184:185], v[184:185], v[134:135]
	v_pk_fma_f32 v[134:135], v[186:187], v[186:187], v[134:135]
	v_pk_fma_f32 v[198:199], v[214:215], v[38:39], v[46:47]
	v_pk_fma_f32 v[200:201], v[216:217], v[40:41], v[48:49]
	v_pk_mul_f32 v[198:199], v[206:207], v[198:199]
	v_pk_mul_f32 v[200:201], v[208:209], v[200:201]
	ds_write_b128 v228, v[198:201] offset:13200
	v_pk_mul_f32 v[206:207], v[198:199], v[202:203]
	v_pk_mul_f32 v[208:209], v[200:201], v[204:205]
	v_pk_add_f32 v[220:221], v[220:221], v[206:207]
	v_pk_add_f32 v[220:221], v[220:221], v[208:209]
	v_pk_fma_f32 v[222:223], v[206:207], v[54:55], v[222:223]
	v_pk_fma_f32 v[222:223], v[208:209], v[56:57], v[222:223]
	v_pk_mul_f32 v[192:193], v[184:185], v[214:215]
	v_pk_mul_f32 v[194:195], v[186:187], v[216:217]
	v_pk_fma_f32 v[148:149], v[192:193], v[202:203], v[148:149]
	v_pk_fma_f32 v[148:149], v[194:195], v[204:205], v[148:149]
	v_pk_mul_f32 v[210:211], v[126:127], v[202:203]
	v_pk_mul_f32 v[212:213], v[128:129], v[204:205]
	ds_write_b128 v228, v[210:213] offset:12688
	ds_write_b128 v228, v[126:129] offset:12944
	v_add_f32_e32 v134, v134, v135
	v_add_f32_e32 v148, v148, v149
	v_add_f32_e32 v219, v220, v221
	v_add_f32_e32 v222, v222, v223
	v_add_f32_dpp v134, v134, v134 quad_perm:[1,0,3,2] row_mask:0xf bank_mask:0xf bound_ctrl:1
	v_add_f32_dpp v148, v148, v148 quad_perm:[1,0,3,2] row_mask:0xf bank_mask:0xf bound_ctrl:1
	v_add_f32_dpp v219, v219, v219 quad_perm:[1,0,3,2] row_mask:0xf bank_mask:0xf bound_ctrl:1
	v_add_f32_dpp v222, v222, v222 quad_perm:[1,0,3,2] row_mask:0xf bank_mask:0xf bound_ctrl:1
	v_add_f32_dpp v134, v134, v134 quad_perm:[2,3,0,1] row_mask:0xf bank_mask:0xf bound_ctrl:1
	v_add_f32_dpp v148, v148, v148 quad_perm:[2,3,0,1] row_mask:0xf bank_mask:0xf bound_ctrl:1
	v_add_f32_dpp v219, v219, v219 quad_perm:[2,3,0,1] row_mask:0xf bank_mask:0xf bound_ctrl:1
	v_add_f32_dpp v222, v222, v222 quad_perm:[2,3,0,1] row_mask:0xf bank_mask:0xf bound_ctrl:1
	v_add_f32_dpp v134, v134, v134 row_half_mirror row_mask:0xf bank_mask:0xf bound_ctrl:1
	v_add_f32_dpp v148, v148, v148 row_half_mirror row_mask:0xf bank_mask:0xf bound_ctrl:1
	v_add_f32_dpp v219, v219, v219 row_half_mirror row_mask:0xf bank_mask:0xf bound_ctrl:1
	v_add_f32_dpp v222, v222, v222 row_half_mirror row_mask:0xf bank_mask:0xf bound_ctrl:1
	v_max_f32_e32 v134, 0x179abe15, v134
	v_rsq_f32_e32 v224, v134
	s_nop 1
	v_mul_f32_e32 v218, v224, v148
	v_pk_mul_f32 v[198:199], v[180:181], v[224:225] op_sel_hi:[1,0] neg_lo:[0,1] neg_hi:[0,1]
	v_pk_mul_f32 v[200:201], v[182:183], v[224:225] op_sel_hi:[1,0] neg_lo:[0,1] neg_hi:[0,1]
; #define WG_BAR() do { asm volatile("s_waitcnt lgkmcnt(0)" ::: "memory"); __builtin_amdgcn_s_barrier(); asm volatile("" ::: "memory"); } while (0)
; #define SCAN_ITER(D_, SET) do { const int blk = blk0 + (D_); if (blk + 1 < TT / TB) { SCAN_PRODUCE(blk + 1, SET); if (blk + 1 + PD < TT / TB) SCAN_LOAD(blk + 1 + PD, SET); } WG_BAR(); } while (0)
; __global__ void __launch_bounds__(NTHR) hymba_fwd(Params P) {
;     ...
;               SCAN_LOAD(0, 0); SCAN_LOAD(1, 1);
;               SCAN_PRODUCE(0, 0); SCAN_LOAD(2, 0);
;               WG_BAR();
;               static_assert((TT / TB) % PD == 0 && PD == 2, "block loop is unrolled by PD = 2");
;               for (int blk0 = 0; blk0 < TT / TB; blk0 += PD) {
;     ...
;                 SCAN_ITER(0, 1); SCAN_ITER(1, 0);
;     ...
;               }
	v_pk_mul_f32 v[206:207], v[184:185], v[224:225] op_sel_hi:[1,0] neg_lo:[0,1] neg_hi:[0,1]
	v_pk_mul_f32 v[208:209], v[186:187], v[224:225] op_sel_hi:[1,0] neg_lo:[0,1] neg_hi:[0,1]
	ds_write_b128 v228, v[198:201] offset:12416
	ds_write_b128 v228, v[206:209] offset:12432
	v_pk_mul_f32 v[214:215], v[188:189], v[224:225] op_sel_hi:[1,0]
	v_pk_mul_f32 v[216:217], v[190:191], v[224:225] op_sel_hi:[1,0]
	v_pk_mul_f32 v[202:203], v[192:193], v[224:225] op_sel_hi:[1,0]
	v_pk_mul_f32 v[204:205], v[194:195], v[224:225] op_sel_hi:[1,0]
	ds_write_b128 v228, v[214:217] offset:13440
	ds_write_b128 v228, v[202:205] offset:13456
	s_mov_b64 exec, s[52:53]
	ds_write_b64 v228, v[218:219] offset:13952
	global_store_dword v227, v222, s[64:65]
	s_mov_b64 exec, -1
	s_add_u32 s64, s64, 0x600
	s_addc_u32 s65, s65, 0
	global_load_dwordx4 v[94:97], v0, s[56:57]
	global_load_dwordx4 v[98:101], v0, s[56:57] offset:2048
	global_load_dwordx4 v[102:105], v0, s[58:59]
	global_load_dwordx4 v[106:109], v155, s[56:57]
	global_load_dwordx4 v[110:113], v155, s[56:57] offset:2048
	global_load_dwordx4 v[114:117], v155, s[58:59]
	global_load_dwordx4 v[118:121], v197, s[60:61]
	global_load_dwordx4 v[122:125], v226, s[62:63]
	global_load_dwordx4 v[126:129], v226, s[62:63] offset:16
	s_add_u32 s56, s56, 0x12000
	s_addc_u32 s57, s57, 0
	s_add_u32 s58, s58, 0x12000
	s_addc_u32 s59, s59, 0
	s_add_u32 s60, s60, 0x4000
	s_addc_u32 s61, s61, 0
	s_add_u32 s62, s62, 0x8000
	s_addc_u32 s63, s63, 0
	s_waitcnt lgkmcnt(0)
	s_barrier
	s_movk_i32 s14, 21
.Lp4p_loop:
	s_waitcnt vmcnt(20)
	v_mov_b32_e32 v134, 0
	v_mov_b32_e32 v135, 0
	v_mov_b32_e32 v148, 0
	v_mov_b32_e32 v149, 0
	v_mov_b32_e32 v220, 0
	v_mov_b32_e32 v221, 0
	v_mov_b32_e32 v222, 0
	v_mov_b32_e32 v223, 0
	v_lshlrev_b32_e32 v198, 16, v130
	v_and_b32_e32 v199, 0xffff0000, v130
	v_lshlrev_b32_e32 v200, 16, v131
	v_and_b32_e32 v201, 0xffff0000, v131
	v_lshlrev_b32_e32 v202, 16, v156
	v_and_b32_e32 v203, 0xffff0000, v156
	v_lshlrev_b32_e32 v204, 16, v157
	v_and_b32_e32 v205, 0xffff0000, v157
	v_pk_add_f32 v[202:203], v[202:203], v[198:199] neg_lo:[0,1] neg_hi:[0,1]
	v_pk_add_f32 v[204:205], v[204:205], v[200:201] neg_lo:[0,1] neg_hi:[0,1]
	v_pk_fma_f32 v[202:203], v[202:203], v[2:3], v[198:199]
	v_pk_fma_f32 v[204:205], v[204:205], v[4:5], v[200:201]
	v_lshlrev_b32_e32 v198, 16, v140
	v_and_b32_e32 v199, 0xffff0000, v140
	v_lshlrev_b32_e32 v200, 16, v141
	v_and_b32_e32 v201, 0xffff0000, v141
	v_lshlrev_b32_e32 v206, 16, v160
	v_and_b32_e32 v207, 0xffff0000, v160
	v_lshlrev_b32_e32 v208, 16, v161
	v_and_b32_e32 v209, 0xffff0000, v161
	v_pk_add_f32 v[206:207], v[206:207], v[198:199] neg_lo:[0,1] neg_hi:[0,1]
	v_pk_add_f32 v[208:209], v[208:209], v[200:201] neg_lo:[0,1] neg_hi:[0,1]
	v_pk_fma_f32 v[206:207], v[206:207], v[10:11], v[198:199]
	v_pk_fma_f32 v[208:209], v[208:209], v[12:13], v[200:201]
	v_lshlrev_b32_e32 v198, 16, v144
	v_and_b32_e32 v199, 0xffff0000, v144
	v_lshlrev_b32_e32 v200, 16, v145
	v_and_b32_e32 v201, 0xffff0000, v145
	v_lshlrev_b32_e32 v210, 16, v164
	v_and_b32_e32 v211, 0xffff0000, v164
	v_lshlrev_b32_e32 v212, 16, v165
	v_and_b32_e32 v213, 0xffff0000, v165
	v_pk_add_f32 v[210:211], v[210:211], v[198:199] neg_lo:[0,1] neg_hi:[0,1]
	v_pk_add_f32 v[212:213], v[212:213], v[200:201] neg_lo:[0,1] neg_hi:[0,1]
	v_pk_fma_f32 v[210:211], v[210:211], v[18:19], v[198:199]
	v_pk_fma_f32 v[212:213], v[212:213], v[20:21], v[200:201]
	ds_write_b128 v229, v[210:213] offset:1280
	v_lshlrev_b32_e32 v214, 16, v168
	v_and_b32_e32 v215, 0xffff0000, v168
	v_lshlrev_b32_e32 v216, 16, v169
	v_and_b32_e32 v217, 0xffff0000, v169
	v_pk_mul_f32 v[180:181], v[206:207], v[26:27]
	v_pk_mul_f32 v[182:183], v[208:209], v[28:29]
	v_pk_fma_f32 v[134:135], v[180:181], v[180:181], v[134:135]
	v_pk_fma_f32 v[134:135], v[182:183], v[182:183], v[134:135]
	v_pk_fma_f32 v[198:199], v[214:215], v[34:35], v[42:43]
	v_pk_fma_f32 v[200:201], v[216:217], v[36:37], v[44:45]
	v_pk_mul_f32 v[198:199], v[206:207], v[198:199]
	v_pk_mul_f32 v[200:201], v[208:209], v[200:201]
	ds_write_b128 v229, v[198:201] offset:768
	v_pk_mul_f32 v[206:207], v[198:199], v[202:203]
	v_pk_mul_f32 v[208:209], v[200:201], v[204:205]
	v_pk_add_f32 v[220:221], v[220:221], v[206:207]
	v_pk_add_f32 v[220:221], v[220:221], v[208:209]
	v_pk_fma_f32 v[222:223], v[206:207], v[50:51], v[222:223]
	v_pk_fma_f32 v[222:223], v[208:209], v[52:53], v[222:223]
	v_pk_mul_f32 v[188:189], v[180:181], v[214:215]
	v_pk_mul_f32 v[190:191], v[182:183], v[216:217]
	v_pk_fma_f32 v[148:149], v[188:189], v[202:203], v[148:149]
	v_pk_fma_f32 v[148:149], v[190:191], v[204:205], v[148:149]
	v_pk_mul_f32 v[210:211], v[172:173], v[202:203]
	v_pk_mul_f32 v[212:213], v[174:175], v[204:205]
	ds_write_b128 v229, v[210:213] offset:256
	ds_write_b128 v229, v[172:175] offset:512
	v_lshlrev_b32_e32 v198, 16, v132
	v_and_b32_e32 v199, 0xffff0000, v132
	v_lshlrev_b32_e32 v200, 16, v133
	v_and_b32_e32 v201, 0xffff0000, v133
	v_lshlrev_b32_e32 v202, 16, v158
	v_and_b32_e32 v203, 0xffff0000, v158
	v_lshlrev_b32_e32 v204, 16, v159
	v_and_b32_e32 v205, 0xffff0000, v159
	v_pk_add_f32 v[202:203], v[202:203], v[198:199] neg_lo:[0,1] neg_hi:[0,1]
	v_pk_add_f32 v[204:205], v[204:205], v[200:201] neg_lo:[0,1] neg_hi:[0,1]
	v_pk_fma_f32 v[202:203], v[202:203], v[6:7], v[198:199]
	v_pk_fma_f32 v[204:205], v[204:205], v[8:9], v[200:201]
	v_lshlrev_b32_e32 v198, 16, v142
	v_and_b32_e32 v199, 0xffff0000, v142
	v_lshlrev_b32_e32 v200, 16, v143
	v_and_b32_e32 v201, 0xffff0000, v143
	v_lshlrev_b32_e32 v206, 16, v162
	v_and_b32_e32 v207, 0xffff0000, v162
	v_lshlrev_b32_e32 v208, 16, v163
	v_and_b32_e32 v209, 0xffff0000, v163
	v_pk_add_f32 v[206:207], v[206:207], v[198:199] neg_lo:[0,1] neg_hi:[0,1]
	v_pk_add_f32 v[208:209], v[208:209], v[200:201] neg_lo:[0,1] neg_hi:[0,1]
	v_pk_fma_f32 v[206:207], v[206:207], v[14:15], v[198:199]
	v_pk_fma_f32 v[208:209], v[208:209], v[16:17], v[200:201]
	v_lshlrev_b32_e32 v198, 16, v146
	v_and_b32_e32 v199, 0xffff0000, v146
	v_lshlrev_b32_e32 v200, 16, v147
	v_and_b32_e32 v201, 0xffff0000, v147
	v_lshlrev_b32_e32 v210, 16, v166
	v_and_b32_e32 v211, 0xffff0000, v166
	v_lshlrev_b32_e32 v212, 16, v167
	v_and_b32_e32 v213, 0xffff0000, v167
	v_pk_add_f32 v[210:211], v[210:211], v[198:199] neg_lo:[0,1] neg_hi:[0,1]
	v_pk_add_f32 v[212:213], v[212:213], v[200:201] neg_lo:[0,1] neg_hi:[0,1]
	v_pk_fma_f32 v[210:211], v[210:211], v[22:23], v[198:199]
	v_pk_fma_f32 v[212:213], v[212:213], v[24:25], v[200:201]
	ds_write_b128 v229, v[210:213] offset:1296
	v_lshlrev_b32_e32 v214, 16, v170
	v_and_b32_e32 v215, 0xffff0000, v170
	v_lshlrev_b32_e32 v216, 16, v171
	v_and_b32_e32 v217, 0xffff0000, v171
	v_pk_mul_f32 v[184:185], v[206:207], v[30:31]
	v_pk_mul_f32 v[186:187], v[208:209], v[32:33]
	v_pk_fma_f32 v[134:135], v[184:185], v[184:185], v[134:135]
	v_pk_fma_f32 v[134:135], v[186:187], v[186:187], v[134:135]
	v_pk_fma_f32 v[198:199], v[214:215], v[38:39], v[46:47]
	v_pk_fma_f32 v[200:201], v[216:217], v[40:41], v[48:49]
	v_pk_mul_f32 v[198:199], v[206:207], v[198:199]
	v_pk_mul_f32 v[200:201], v[208:209], v[200:201]
	ds_write_b128 v229, v[198:201] offset:784
	v_pk_mul_f32 v[206:207], v[198:199], v[202:203]
	v_pk_mul_f32 v[208:209], v[200:201], v[204:205]
	v_pk_add_f32 v[220:221], v[220:221], v[206:207]
	v_pk_add_f32 v[220:221], v[220:221], v[208:209]
	v_pk_fma_f32 v[222:223], v[206:207], v[54:55], v[222:223]
	v_pk_fma_f32 v[222:223], v[208:209], v[56:57], v[222:223]
	v_pk_mul_f32 v[192:193], v[184:185], v[214:215]
	v_pk_mul_f32 v[194:195], v[186:187], v[216:217]
	v_pk_fma_f32 v[148:149], v[192:193], v[202:203], v[148:149]
	v_pk_fma_f32 v[148:149], v[194:195], v[204:205], v[148:149]
	v_pk_mul_f32 v[210:211], v[176:177], v[202:203]
	v_pk_mul_f32 v[212:213], v[178:179], v[204:205]
	ds_write_b128 v229, v[210:213] offset:272
	ds_write_b128 v229, v[176:179] offset:528
	v_add_f32_e32 v134, v134, v135
	v_add_f32_e32 v148, v148, v149
	v_add_f32_e32 v219, v220, v221
	v_add_f32_e32 v222, v222, v223
	v_add_f32_dpp v134, v134, v134 quad_perm:[1,0,3,2] row_mask:0xf bank_mask:0xf bound_ctrl:1
	v_add_f32_dpp v148, v148, v148 quad_perm:[1,0,3,2] row_mask:0xf bank_mask:0xf bound_ctrl:1
	v_add_f32_dpp v219, v219, v219 quad_perm:[1,0,3,2] row_mask:0xf bank_mask:0xf bound_ctrl:1
	v_add_f32_dpp v222, v222, v222 quad_perm:[1,0,3,2] row_mask:0xf bank_mask:0xf bound_ctrl:1
	v_add_f32_dpp v134, v134, v134 quad_perm:[2,3,0,1] row_mask:0xf bank_mask:0xf bound_ctrl:1
	v_add_f32_dpp v148, v148, v148 quad_perm:[2,3,0,1] row_mask:0xf bank_mask:0xf bound_ctrl:1
	v_add_f32_dpp v219, v219, v219 quad_perm:[2,3,0,1] row_mask:0xf bank_mask:0xf bound_ctrl:1
	v_add_f32_dpp v222, v222, v222 quad_perm:[2,3,0,1] row_mask:0xf bank_mask:0xf bound_ctrl:1
	v_add_f32_dpp v134, v134, v134 row_half_mirror row_mask:0xf bank_mask:0xf bound_ctrl:1
	v_add_f32_dpp v148, v148, v148 row_half_mirror row_mask:0xf bank_mask:0xf bound_ctrl:1
	v_add_f32_dpp v219, v219, v219 row_half_mirror row_mask:0xf bank_mask:0xf bound_ctrl:1
	v_add_f32_dpp v222, v222, v222 row_half_mirror row_mask:0xf bank_mask:0xf bound_ctrl:1
	v_max_f32_e32 v134, 0x179abe15, v134
	v_rsq_f32_e32 v224, v134
	s_nop 1
	v_mul_f32_e32 v218, v224, v148
	v_pk_mul_f32 v[198:199], v[180:181], v[224:225] op_sel_hi:[1,0] neg_lo:[0,1] neg_hi:[0,1]
	v_pk_mul_f32 v[200:201], v[182:183], v[224:225] op_sel_hi:[1,0] neg_lo:[0,1] neg_hi:[0,1]
	v_pk_mul_f32 v[206:207], v[184:185], v[224:225] op_sel_hi:[1,0] neg_lo:[0,1] neg_hi:[0,1]
	v_pk_mul_f32 v[208:209], v[186:187], v[224:225] op_sel_hi:[1,0] neg_lo:[0,1] neg_hi:[0,1]
	ds_write_b128 v229, v[198:201] offset:0
	ds_write_b128 v229, v[206:209] offset:16
	v_pk_mul_f32 v[214:215], v[188:189], v[224:225] op_sel_hi:[1,0]
	v_pk_mul_f32 v[216:217], v[190:191], v[224:225] op_sel_hi:[1,0]
	v_pk_mul_f32 v[202:203], v[192:193], v[224:225] op_sel_hi:[1,0]
	v_pk_mul_f32 v[204:205], v[194:195], v[224:225] op_sel_hi:[1,0]
	ds_write_b128 v229, v[214:217] offset:1024
	ds_write_b128 v229, v[202:205] offset:1040
	s_mov_b64 exec, s[52:53]
	ds_write_b64 v229, v[218:219] offset:1536
	global_store_dword v227, v222, s[64:65]
	s_mov_b64 exec, -1
	s_add_u32 s64, s64, 0x200
	s_addc_u32 s65, s65, 0
	global_load_dwordx4 v[130:133], v0, s[56:57]
	global_load_dwordx4 v[140:143], v0, s[56:57] offset:2048
	global_load_dwordx4 v[144:147], v0, s[58:59]
	global_load_dwordx4 v[156:159], v155, s[56:57]
	global_load_dwordx4 v[160:163], v155, s[56:57] offset:2048
	global_load_dwordx4 v[164:167], v155, s[58:59]
	global_load_dwordx4 v[168:171], v197, s[60:61]
	global_load_dwordx4 v[172:175], v226, s[62:63]
	global_load_dwordx4 v[176:179], v226, s[62:63] offset:16
	s_add_u32 s56, s56, 0x36000
	s_addc_u32 s57, s57, 0
	s_add_u32 s58, s58, 0x36000
	s_addc_u32 s59, s59, 0
	s_add_u32 s60, s60, 0xc000
	s_addc_u32 s61, s61, 0
	s_add_u32 s62, s62, 0x18000
	s_addc_u32 s63, s63, 0
	s_waitcnt vmcnt(20)
	v_mov_b32_e32 v134, 0
	v_mov_b32_e32 v135, 0
	v_mov_b32_e32 v148, 0
	v_mov_b32_e32 v149, 0
	v_mov_b32_e32 v220, 0
	v_mov_b32_e32 v221, 0
	v_mov_b32_e32 v222, 0
	v_mov_b32_e32 v223, 0
	v_lshlrev_b32_e32 v198, 16, v58
	v_and_b32_e32 v199, 0xffff0000, v58
	v_lshlrev_b32_e32 v200, 16, v59
	v_and_b32_e32 v201, 0xffff0000, v59
	v_lshlrev_b32_e32 v202, 16, v70
	v_and_b32_e32 v203, 0xffff0000, v70
	v_lshlrev_b32_e32 v204, 16, v71
	v_and_b32_e32 v205, 0xffff0000, v71
	v_pk_add_f32 v[202:203], v[202:203], v[198:199] neg_lo:[0,1] neg_hi:[0,1]
	v_pk_add_f32 v[204:205], v[204:205], v[200:201] neg_lo:[0,1] neg_hi:[0,1]
	v_pk_fma_f32 v[202:203], v[202:203], v[2:3], v[198:199]
	v_pk_fma_f32 v[204:205], v[204:205], v[4:5], v[200:201]
	v_lshlrev_b32_e32 v198, 16, v62
	v_and_b32_e32 v199, 0xffff0000, v62
	v_lshlrev_b32_e32 v200, 16, v63
	v_and_b32_e32 v201, 0xffff0000, v63
	v_lshlrev_b32_e32 v206, 16, v74
	v_and_b32_e32 v207, 0xffff0000, v74
	v_lshlrev_b32_e32 v208, 16, v75
	v_and_b32_e32 v209, 0xffff0000, v75
	v_pk_add_f32 v[206:207], v[206:207], v[198:199] neg_lo:[0,1] neg_hi:[0,1]
	v_pk_add_f32 v[208:209], v[208:209], v[200:201] neg_lo:[0,1] neg_hi:[0,1]
	v_pk_fma_f32 v[206:207], v[206:207], v[10:11], v[198:199]
	v_pk_fma_f32 v[208:209], v[208:209], v[12:13], v[200:201]
	v_lshlrev_b32_e32 v198, 16, v66
	v_and_b32_e32 v199, 0xffff0000, v66
	v_lshlrev_b32_e32 v200, 16, v67
	v_and_b32_e32 v201, 0xffff0000, v67
	v_lshlrev_b32_e32 v210, 16, v78
	v_and_b32_e32 v211, 0xffff0000, v78
	v_lshlrev_b32_e32 v212, 16, v79
	v_and_b32_e32 v213, 0xffff0000, v79
	v_pk_add_f32 v[210:211], v[210:211], v[198:199] neg_lo:[0,1] neg_hi:[0,1]
	v_pk_add_f32 v[212:213], v[212:213], v[200:201] neg_lo:[0,1] neg_hi:[0,1]
	v_pk_fma_f32 v[210:211], v[210:211], v[18:19], v[198:199]
	v_pk_fma_f32 v[212:213], v[212:213], v[20:21], v[200:201]
	ds_write_b128 v229, v[210:213] offset:13696
	v_lshlrev_b32_e32 v214, 16, v82
	v_and_b32_e32 v215, 0xffff0000, v82
	v_lshlrev_b32_e32 v216, 16, v83
	v_and_b32_e32 v217, 0xffff0000, v83
	v_pk_mul_f32 v[180:181], v[206:207], v[26:27]
	v_pk_mul_f32 v[182:183], v[208:209], v[28:29]
	v_pk_fma_f32 v[134:135], v[180:181], v[180:181], v[134:135]
	v_pk_fma_f32 v[134:135], v[182:183], v[182:183], v[134:135]
	v_pk_fma_f32 v[198:199], v[214:215], v[34:35], v[42:43]
	v_pk_fma_f32 v[200:201], v[216:217], v[36:37], v[44:45]
	v_pk_mul_f32 v[198:199], v[206:207], v[198:199]
	v_pk_mul_f32 v[200:201], v[208:209], v[200:201]
	ds_write_b128 v229, v[198:201] offset:13184
	v_pk_mul_f32 v[206:207], v[198:199], v[202:203]
	v_pk_mul_f32 v[208:209], v[200:201], v[204:205]
	v_pk_add_f32 v[220:221], v[220:221], v[206:207]
	v_pk_add_f32 v[220:221], v[220:221], v[208:209]
	v_pk_fma_f32 v[222:223], v[206:207], v[50:51], v[222:223]
	v_pk_fma_f32 v[222:223], v[208:209], v[52:53], v[222:223]
	v_pk_mul_f32 v[188:189], v[180:181], v[214:215]
	v_pk_mul_f32 v[190:191], v[182:183], v[216:217]
	v_pk_fma_f32 v[148:149], v[188:189], v[202:203], v[148:149]
	v_pk_fma_f32 v[148:149], v[190:191], v[204:205], v[148:149]
	v_pk_mul_f32 v[210:211], v[86:87], v[202:203]
	v_pk_mul_f32 v[212:213], v[88:89], v[204:205]
	ds_write_b128 v229, v[210:213] offset:12672
	ds_write_b128 v229, v[86:89] offset:12928
	v_lshlrev_b32_e32 v198, 16, v60
	v_and_b32_e32 v199, 0xffff0000, v60
	v_lshlrev_b32_e32 v200, 16, v61
	v_and_b32_e32 v201, 0xffff0000, v61
	v_lshlrev_b32_e32 v202, 16, v72
	v_and_b32_e32 v203, 0xffff0000, v72
	v_lshlrev_b32_e32 v204, 16, v73
	v_and_b32_e32 v205, 0xffff0000, v73
	v_pk_add_f32 v[202:203], v[202:203], v[198:199] neg_lo:[0,1] neg_hi:[0,1]
	v_pk_add_f32 v[204:205], v[204:205], v[200:201] neg_lo:[0,1] neg_hi:[0,1]
	v_pk_fma_f32 v[202:203], v[202:203], v[6:7], v[198:199]
	v_pk_fma_f32 v[204:205], v[204:205], v[8:9], v[200:201]
	v_lshlrev_b32_e32 v198, 16, v64
	v_and_b32_e32 v199, 0xffff0000, v64
	v_lshlrev_b32_e32 v200, 16, v65
	v_and_b32_e32 v201, 0xffff0000, v65
	v_lshlrev_b32_e32 v206, 16, v76
	v_and_b32_e32 v207, 0xffff0000, v76
	v_lshlrev_b32_e32 v208, 16, v77
	v_and_b32_e32 v209, 0xffff0000, v77
	v_pk_add_f32 v[206:207], v[206:207], v[198:199] neg_lo:[0,1] neg_hi:[0,1]
	v_pk_add_f32 v[208:209], v[208:209], v[200:201] neg_lo:[0,1] neg_hi:[0,1]
	v_pk_fma_f32 v[206:207], v[206:207], v[14:15], v[198:199]
	v_pk_fma_f32 v[208:209], v[208:209], v[16:17], v[200:201]
	v_lshlrev_b32_e32 v198, 16, v68
	v_and_b32_e32 v199, 0xffff0000, v68
	v_lshlrev_b32_e32 v200, 16, v69
	v_and_b32_e32 v201, 0xffff0000, v69
	v_lshlrev_b32_e32 v210, 16, v80
	v_and_b32_e32 v211, 0xffff0000, v80
	v_lshlrev_b32_e32 v212, 16, v81
	v_and_b32_e32 v213, 0xffff0000, v81
	v_pk_add_f32 v[210:211], v[210:211], v[198:199] neg_lo:[0,1] neg_hi:[0,1]
	v_pk_add_f32 v[212:213], v[212:213], v[200:201] neg_lo:[0,1] neg_hi:[0,1]
	v_pk_fma_f32 v[210:211], v[210:211], v[22:23], v[198:199]
	v_pk_fma_f32 v[212:213], v[212:213], v[24:25], v[200:201]
	ds_write_b128 v229, v[210:213] offset:13712
	v_lshlrev_b32_e32 v214, 16, v84
	v_and_b32_e32 v215, 0xffff0000, v84
	v_lshlrev_b32_e32 v216, 16, v85
	v_and_b32_e32 v217, 0xffff0000, v85
	v_pk_mul_f32 v[184:185], v[206:207], v[30:31]
	v_pk_mul_f32 v[186:187], v[208:209], v[32:33]
	v_pk_fma_f32 v[134:135], v[184:185], v[184:185], v[134:135]
	v_pk_fma_f32 v[134:135], v[186:187], v[186:187], v[134:135]
	v_pk_fma_f32 v[198:199], v[214:215], v[38:39], v[46:47]
	v_pk_fma_f32 v[200:201], v[216:217], v[40:41], v[48:49]
	v_pk_mul_f32 v[198:199], v[206:207], v[198:199]
	v_pk_mul_f32 v[200:201], v[208:209], v[200:201]
	ds_write_b128 v229, v[198:201] offset:13200
	v_pk_mul_f32 v[206:207], v[198:199], v[202:203]
	v_pk_mul_f32 v[208:209], v[200:201], v[204:205]
	v_pk_add_f32 v[220:221], v[220:221], v[206:207]
; #define WG_BAR() do { asm volatile("s_waitcnt lgkmcnt(0)" ::: "memory"); __builtin_amdgcn_s_barrier(); asm volatile("" ::: "memory"); } while (0)
; #define SCAN_ITER(D_, SET) do { const int blk = blk0 + (D_); if (blk + 1 < TT / TB) { SCAN_PRODUCE(blk + 1, SET); if (blk + 1 + PD < TT / TB) SCAN_LOAD(blk + 1 + PD, SET); } WG_BAR(); } while (0)
; __global__ void __launch_bounds__(NTHR) hymba_fwd(Params P) {
;     ...
;               SCAN_LOAD(0, 0); SCAN_LOAD(1, 1);
;               SCAN_PRODUCE(0, 0); SCAN_LOAD(2, 0);
;               WG_BAR();
;               static_assert((TT / TB) % PD == 0 && PD == 2, "block loop is unrolled by PD = 2");
;               for (int blk0 = 0; blk0 < TT / TB; blk0 += PD) {
;     ...
;                 SCAN_ITER(0, 1); SCAN_ITER(1, 0);
;     ...
;               }
	v_pk_add_f32 v[220:221], v[220:221], v[208:209]
	v_pk_fma_f32 v[222:223], v[206:207], v[54:55], v[222:223]
	v_pk_fma_f32 v[222:223], v[208:209], v[56:57], v[222:223]
	v_pk_mul_f32 v[192:193], v[184:185], v[214:215]
	v_pk_mul_f32 v[194:195], v[186:187], v[216:217]
	v_pk_fma_f32 v[148:149], v[192:193], v[202:203], v[148:149]
	v_pk_fma_f32 v[148:149], v[194:195], v[204:205], v[148:149]
	v_pk_mul_f32 v[210:211], v[90:91], v[202:203]
	v_pk_mul_f32 v[212:213], v[92:93], v[204:205]
	ds_write_b128 v229, v[210:213] offset:12688
	ds_write_b128 v229, v[90:93] offset:12944
	v_add_f32_e32 v134, v134, v135
	v_add_f32_e32 v148, v148, v149
	v_add_f32_e32 v219, v220, v221
	v_add_f32_e32 v222, v222, v223
	v_add_f32_dpp v134, v134, v134 quad_perm:[1,0,3,2] row_mask:0xf bank_mask:0xf bound_ctrl:1
	v_add_f32_dpp v148, v148, v148 quad_perm:[1,0,3,2] row_mask:0xf bank_mask:0xf bound_ctrl:1
	v_add_f32_dpp v219, v219, v219 quad_perm:[1,0,3,2] row_mask:0xf bank_mask:0xf bound_ctrl:1
	v_add_f32_dpp v222, v222, v222 quad_perm:[1,0,3,2] row_mask:0xf bank_mask:0xf bound_ctrl:1
	v_add_f32_dpp v134, v134, v134 quad_perm:[2,3,0,1] row_mask:0xf bank_mask:0xf bound_ctrl:1
	v_add_f32_dpp v148, v148, v148 quad_perm:[2,3,0,1] row_mask:0xf bank_mask:0xf bound_ctrl:1
	v_add_f32_dpp v219, v219, v219 quad_perm:[2,3,0,1] row_mask:0xf bank_mask:0xf bound_ctrl:1
	v_add_f32_dpp v222, v222, v222 quad_perm:[2,3,0,1] row_mask:0xf bank_mask:0xf bound_ctrl:1
	v_add_f32_dpp v134, v134, v134 row_half_mirror row_mask:0xf bank_mask:0xf bound_ctrl:1
	v_add_f32_dpp v148, v148, v148 row_half_mirror row_mask:0xf bank_mask:0xf bound_ctrl:1
	v_add_f32_dpp v219, v219, v219 row_half_mirror row_mask:0xf bank_mask:0xf bound_ctrl:1
	v_add_f32_dpp v222, v222, v222 row_half_mirror row_mask:0xf bank_mask:0xf bound_ctrl:1
	v_max_f32_e32 v134, 0x179abe15, v134
	v_rsq_f32_e32 v224, v134
	s_nop 1
	v_mul_f32_e32 v218, v224, v148
	v_pk_mul_f32 v[198:199], v[180:181], v[224:225] op_sel_hi:[1,0] neg_lo:[0,1] neg_hi:[0,1]
	v_pk_mul_f32 v[200:201], v[182:183], v[224:225] op_sel_hi:[1,0] neg_lo:[0,1] neg_hi:[0,1]
	v_pk_mul_f32 v[206:207], v[184:185], v[224:225] op_sel_hi:[1,0] neg_lo:[0,1] neg_hi:[0,1]
	v_pk_mul_f32 v[208:209], v[186:187], v[224:225] op_sel_hi:[1,0] neg_lo:[0,1] neg_hi:[0,1]
	ds_write_b128 v229, v[198:201] offset:12416
	ds_write_b128 v229, v[206:209] offset:12432
	v_pk_mul_f32 v[214:215], v[188:189], v[224:225] op_sel_hi:[1,0]
	v_pk_mul_f32 v[216:217], v[190:191], v[224:225] op_sel_hi:[1,0]
	v_pk_mul_f32 v[202:203], v[192:193], v[224:225] op_sel_hi:[1,0]
	v_pk_mul_f32 v[204:205], v[194:195], v[224:225] op_sel_hi:[1,0]
	ds_write_b128 v229, v[214:217] offset:13440
	ds_write_b128 v229, v[202:205] offset:13456
	s_mov_b64 exec, s[52:53]
	ds_write_b64 v229, v[218:219] offset:13952
	global_store_dword v227, v222, s[64:65]
	s_mov_b64 exec, -1
	s_add_u32 s64, s64, 0x600
	s_addc_u32 s65, s65, 0
	global_load_dwordx4 v[58:61], v0, s[56:57]
	global_load_dwordx4 v[62:65], v0, s[56:57] offset:2048
	global_load_dwordx4 v[66:69], v0, s[58:59]
	global_load_dwordx4 v[70:73], v155, s[56:57]
	global_load_dwordx4 v[74:77], v155, s[56:57] offset:2048
	global_load_dwordx4 v[78:81], v155, s[58:59]
	global_load_dwordx4 v[82:85], v197, s[60:61]
	global_load_dwordx4 v[86:89], v226, s[62:63]
	global_load_dwordx4 v[90:93], v226, s[62:63] offset:16
	s_add_u32 s56, s56, 0x12000
	s_addc_u32 s57, s57, 0
	s_add_u32 s58, s58, 0x12000
	s_addc_u32 s59, s59, 0
	s_add_u32 s60, s60, 0x4000
	s_addc_u32 s61, s61, 0
	s_add_u32 s62, s62, 0x8000
	s_addc_u32 s63, s63, 0
	s_waitcnt lgkmcnt(0)
	s_barrier
	s_waitcnt vmcnt(20)
	v_mov_b32_e32 v134, 0
	v_mov_b32_e32 v135, 0
	v_mov_b32_e32 v148, 0
	v_mov_b32_e32 v149, 0
	v_mov_b32_e32 v220, 0
	v_mov_b32_e32 v221, 0
	v_mov_b32_e32 v222, 0
	v_mov_b32_e32 v223, 0
	v_lshlrev_b32_e32 v198, 16, v94
	v_and_b32_e32 v199, 0xffff0000, v94
	v_lshlrev_b32_e32 v200, 16, v95
	v_and_b32_e32 v201, 0xffff0000, v95
	v_lshlrev_b32_e32 v202, 16, v106
	v_and_b32_e32 v203, 0xffff0000, v106
	v_lshlrev_b32_e32 v204, 16, v107
	v_and_b32_e32 v205, 0xffff0000, v107
	v_pk_add_f32 v[202:203], v[202:203], v[198:199] neg_lo:[0,1] neg_hi:[0,1]
	v_pk_add_f32 v[204:205], v[204:205], v[200:201] neg_lo:[0,1] neg_hi:[0,1]
	v_pk_fma_f32 v[202:203], v[202:203], v[2:3], v[198:199]
	v_pk_fma_f32 v[204:205], v[204:205], v[4:5], v[200:201]
	v_lshlrev_b32_e32 v198, 16, v98
	v_and_b32_e32 v199, 0xffff0000, v98
	v_lshlrev_b32_e32 v200, 16, v99
	v_and_b32_e32 v201, 0xffff0000, v99
	v_lshlrev_b32_e32 v206, 16, v110
	v_and_b32_e32 v207, 0xffff0000, v110
	v_lshlrev_b32_e32 v208, 16, v111
	v_and_b32_e32 v209, 0xffff0000, v111
	v_pk_add_f32 v[206:207], v[206:207], v[198:199] neg_lo:[0,1] neg_hi:[0,1]
	v_pk_add_f32 v[208:209], v[208:209], v[200:201] neg_lo:[0,1] neg_hi:[0,1]
	v_pk_fma_f32 v[206:207], v[206:207], v[10:11], v[198:199]
	v_pk_fma_f32 v[208:209], v[208:209], v[12:13], v[200:201]
	v_lshlrev_b32_e32 v198, 16, v102
	v_and_b32_e32 v199, 0xffff0000, v102
	v_lshlrev_b32_e32 v200, 16, v103
	v_and_b32_e32 v201, 0xffff0000, v103
	v_lshlrev_b32_e32 v210, 16, v114
	v_and_b32_e32 v211, 0xffff0000, v114
	v_lshlrev_b32_e32 v212, 16, v115
	v_and_b32_e32 v213, 0xffff0000, v115
	v_pk_add_f32 v[210:211], v[210:211], v[198:199] neg_lo:[0,1] neg_hi:[0,1]
	v_pk_add_f32 v[212:213], v[212:213], v[200:201] neg_lo:[0,1] neg_hi:[0,1]
	v_pk_fma_f32 v[210:211], v[210:211], v[18:19], v[198:199]
	v_pk_fma_f32 v[212:213], v[212:213], v[20:21], v[200:201]
	ds_write_b128 v228, v[210:213] offset:1280
	v_lshlrev_b32_e32 v214, 16, v118
	v_and_b32_e32 v215, 0xffff0000, v118
	v_lshlrev_b32_e32 v216, 16, v119
	v_and_b32_e32 v217, 0xffff0000, v119
	v_pk_mul_f32 v[180:181], v[206:207], v[26:27]
	v_pk_mul_f32 v[182:183], v[208:209], v[28:29]
	v_pk_fma_f32 v[134:135], v[180:181], v[180:181], v[134:135]
	v_pk_fma_f32 v[134:135], v[182:183], v[182:183], v[134:135]
	v_pk_fma_f32 v[198:199], v[214:215], v[34:35], v[42:43]
	v_pk_fma_f32 v[200:201], v[216:217], v[36:37], v[44:45]
	v_pk_mul_f32 v[198:199], v[206:207], v[198:199]
	v_pk_mul_f32 v[200:201], v[208:209], v[200:201]
	ds_write_b128 v228, v[198:201] offset:768
	v_pk_mul_f32 v[206:207], v[198:199], v[202:203]
	v_pk_mul_f32 v[208:209], v[200:201], v[204:205]
	v_pk_add_f32 v[220:221], v[220:221], v[206:207]
	v_pk_add_f32 v[220:221], v[220:221], v[208:209]
	v_pk_fma_f32 v[222:223], v[206:207], v[50:51], v[222:223]
	v_pk_fma_f32 v[222:223], v[208:209], v[52:53], v[222:223]
	v_pk_mul_f32 v[188:189], v[180:181], v[214:215]
	v_pk_mul_f32 v[190:191], v[182:183], v[216:217]
	v_pk_fma_f32 v[148:149], v[188:189], v[202:203], v[148:149]
	v_pk_fma_f32 v[148:149], v[190:191], v[204:205], v[148:149]
	v_pk_mul_f32 v[210:211], v[122:123], v[202:203]
	v_pk_mul_f32 v[212:213], v[124:125], v[204:205]
	ds_write_b128 v228, v[210:213] offset:256
	ds_write_b128 v228, v[122:125] offset:512
	v_lshlrev_b32_e32 v198, 16, v96
	v_and_b32_e32 v199, 0xffff0000, v96
	v_lshlrev_b32_e32 v200, 16, v97
	v_and_b32_e32 v201, 0xffff0000, v97
	v_lshlrev_b32_e32 v202, 16, v108
	v_and_b32_e32 v203, 0xffff0000, v108
	v_lshlrev_b32_e32 v204, 16, v109
	v_and_b32_e32 v205, 0xffff0000, v109
	v_pk_add_f32 v[202:203], v[202:203], v[198:199] neg_lo:[0,1] neg_hi:[0,1]
	v_pk_add_f32 v[204:205], v[204:205], v[200:201] neg_lo:[0,1] neg_hi:[0,1]
	v_pk_fma_f32 v[202:203], v[202:203], v[6:7], v[198:199]
	v_pk_fma_f32 v[204:205], v[204:205], v[8:9], v[200:201]
	v_lshlrev_b32_e32 v198, 16, v100
	v_and_b32_e32 v199, 0xffff0000, v100
	v_lshlrev_b32_e32 v200, 16, v101
	v_and_b32_e32 v201, 0xffff0000, v101
	v_lshlrev_b32_e32 v206, 16, v112
	v_and_b32_e32 v207, 0xffff0000, v112
	v_lshlrev_b32_e32 v208, 16, v113
	v_and_b32_e32 v209, 0xffff0000, v113
	v_pk_add_f32 v[206:207], v[206:207], v[198:199] neg_lo:[0,1] neg_hi:[0,1]
	v_pk_add_f32 v[208:209], v[208:209], v[200:201] neg_lo:[0,1] neg_hi:[0,1]
	v_pk_fma_f32 v[206:207], v[206:207], v[14:15], v[198:199]
	v_pk_fma_f32 v[208:209], v[208:209], v[16:17], v[200:201]
	v_lshlrev_b32_e32 v198, 16, v104
	v_and_b32_e32 v199, 0xffff0000, v104
	v_lshlrev_b32_e32 v200, 16, v105
	v_and_b32_e32 v201, 0xffff0000, v105
	v_lshlrev_b32_e32 v210, 16, v116
	v_and_b32_e32 v211, 0xffff0000, v116
	v_lshlrev_b32_e32 v212, 16, v117
	v_and_b32_e32 v213, 0xffff0000, v117
	v_pk_add_f32 v[210:211], v[210:211], v[198:199] neg_lo:[0,1] neg_hi:[0,1]
	v_pk_add_f32 v[212:213], v[212:213], v[200:201] neg_lo:[0,1] neg_hi:[0,1]
	v_pk_fma_f32 v[210:211], v[210:211], v[22:23], v[198:199]
	v_pk_fma_f32 v[212:213], v[212:213], v[24:25], v[200:201]
	ds_write_b128 v228, v[210:213] offset:1296
	v_lshlrev_b32_e32 v214, 16, v120
	v_and_b32_e32 v215, 0xffff0000, v120
	v_lshlrev_b32_e32 v216, 16, v121
	v_and_b32_e32 v217, 0xffff0000, v121
	v_pk_mul_f32 v[184:185], v[206:207], v[30:31]
	v_pk_mul_f32 v[186:187], v[208:209], v[32:33]
	v_pk_fma_f32 v[134:135], v[184:185], v[184:185], v[134:135]
	v_pk_fma_f32 v[134:135], v[186:187], v[186:187], v[134:135]
	v_pk_fma_f32 v[198:199], v[214:215], v[38:39], v[46:47]
	v_pk_fma_f32 v[200:201], v[216:217], v[40:41], v[48:49]
	v_pk_mul_f32 v[198:199], v[206:207], v[198:199]
	v_pk_mul_f32 v[200:201], v[208:209], v[200:201]
	ds_write_b128 v228, v[198:201] offset:784
	v_pk_mul_f32 v[206:207], v[198:199], v[202:203]
	v_pk_mul_f32 v[208:209], v[200:201], v[204:205]
	v_pk_add_f32 v[220:221], v[220:221], v[206:207]
	v_pk_add_f32 v[220:221], v[220:221], v[208:209]
	v_pk_fma_f32 v[222:223], v[206:207], v[54:55], v[222:223]
	v_pk_fma_f32 v[222:223], v[208:209], v[56:57], v[222:223]
	v_pk_mul_f32 v[192:193], v[184:185], v[214:215]
	v_pk_mul_f32 v[194:195], v[186:187], v[216:217]
	v_pk_fma_f32 v[148:149], v[192:193], v[202:203], v[148:149]
	v_pk_fma_f32 v[148:149], v[194:195], v[204:205], v[148:149]
	v_pk_mul_f32 v[210:211], v[126:127], v[202:203]
	v_pk_mul_f32 v[212:213], v[128:129], v[204:205]
	ds_write_b128 v228, v[210:213] offset:272
	ds_write_b128 v228, v[126:129] offset:528
	v_add_f32_e32 v134, v134, v135
	v_add_f32_e32 v148, v148, v149
	v_add_f32_e32 v219, v220, v221
	v_add_f32_e32 v222, v222, v223
	v_add_f32_dpp v134, v134, v134 quad_perm:[1,0,3,2] row_mask:0xf bank_mask:0xf bound_ctrl:1
	v_add_f32_dpp v148, v148, v148 quad_perm:[1,0,3,2] row_mask:0xf bank_mask:0xf bound_ctrl:1
	v_add_f32_dpp v219, v219, v219 quad_perm:[1,0,3,2] row_mask:0xf bank_mask:0xf bound_ctrl:1
	v_add_f32_dpp v222, v222, v222 quad_perm:[1,0,3,2] row_mask:0xf bank_mask:0xf bound_ctrl:1
	v_add_f32_dpp v134, v134, v134 quad_perm:[2,3,0,1] row_mask:0xf bank_mask:0xf bound_ctrl:1
	v_add_f32_dpp v148, v148, v148 quad_perm:[2,3,0,1] row_mask:0xf bank_mask:0xf bound_ctrl:1
	v_add_f32_dpp v219, v219, v219 quad_perm:[2,3,0,1] row_mask:0xf bank_mask:0xf bound_ctrl:1
	v_add_f32_dpp v222, v222, v222 quad_perm:[2,3,0,1] row_mask:0xf bank_mask:0xf bound_ctrl:1
	v_add_f32_dpp v134, v134, v134 row_half_mirror row_mask:0xf bank_mask:0xf bound_ctrl:1
	v_add_f32_dpp v148, v148, v148 row_half_mirror row_mask:0xf bank_mask:0xf bound_ctrl:1
	v_add_f32_dpp v219, v219, v219 row_half_mirror row_mask:0xf bank_mask:0xf bound_ctrl:1
	v_add_f32_dpp v222, v222, v222 row_half_mirror row_mask:0xf bank_mask:0xf bound_ctrl:1
	v_max_f32_e32 v134, 0x179abe15, v134
	v_rsq_f32_e32 v224, v134
	s_nop 1
	v_mul_f32_e32 v218, v224, v148
	v_pk_mul_f32 v[198:199], v[180:181], v[224:225] op_sel_hi:[1,0] neg_lo:[0,1] neg_hi:[0,1]
	v_pk_mul_f32 v[200:201], v[182:183], v[224:225] op_sel_hi:[1,0] neg_lo:[0,1] neg_hi:[0,1]
	v_pk_mul_f32 v[206:207], v[184:185], v[224:225] op_sel_hi:[1,0] neg_lo:[0,1] neg_hi:[0,1]
	v_pk_mul_f32 v[208:209], v[186:187], v[224:225] op_sel_hi:[1,0] neg_lo:[0,1] neg_hi:[0,1]
	ds_write_b128 v228, v[198:201] offset:0
	ds_write_b128 v228, v[206:209] offset:16
	v_pk_mul_f32 v[214:215], v[188:189], v[224:225] op_sel_hi:[1,0]
	v_pk_mul_f32 v[216:217], v[190:191], v[224:225] op_sel_hi:[1,0]
	v_pk_mul_f32 v[202:203], v[192:193], v[224:225] op_sel_hi:[1,0]
	v_pk_mul_f32 v[204:205], v[194:195], v[224:225] op_sel_hi:[1,0]
	ds_write_b128 v228, v[214:217] offset:1024
	ds_write_b128 v228, v[202:205] offset:1040
	s_mov_b64 exec, s[52:53]
	ds_write_b64 v228, v[218:219] offset:1536
	global_store_dword v227, v222, s[64:65]
	s_mov_b64 exec, -1
	s_add_u32 s64, s64, 0x200
	s_addc_u32 s65, s65, 0
	global_load_dwordx4 v[94:97], v0, s[56:57]
	global_load_dwordx4 v[98:101], v0, s[56:57] offset:2048
	global_load_dwordx4 v[102:105], v0, s[58:59]
	global_load_dwordx4 v[106:109], v155, s[56:57]
	global_load_dwordx4 v[110:113], v155, s[56:57] offset:2048
	global_load_dwordx4 v[114:117], v155, s[58:59]
	global_load_dwordx4 v[118:121], v197, s[60:61]
	global_load_dwordx4 v[122:125], v226, s[62:63]
	global_load_dwordx4 v[126:129], v226, s[62:63] offset:16
	s_add_u32 s56, s56, 0x36000
	s_addc_u32 s57, s57, 0
	s_add_u32 s58, s58, 0x36000
	s_addc_u32 s59, s59, 0
	s_add_u32 s60, s60, 0xc000
	s_addc_u32 s61, s61, 0
	s_add_u32 s62, s62, 0x18000
	s_addc_u32 s63, s63, 0
	s_waitcnt vmcnt(20)
	v_mov_b32_e32 v134, 0
	v_mov_b32_e32 v135, 0
	v_mov_b32_e32 v148, 0
	v_mov_b32_e32 v149, 0
	v_mov_b32_e32 v220, 0
	v_mov_b32_e32 v221, 0
	v_mov_b32_e32 v222, 0
	v_mov_b32_e32 v223, 0
	v_lshlrev_b32_e32 v198, 16, v130
	v_and_b32_e32 v199, 0xffff0000, v130
	v_lshlrev_b32_e32 v200, 16, v131
	v_and_b32_e32 v201, 0xffff0000, v131
	v_lshlrev_b32_e32 v202, 16, v156
	v_and_b32_e32 v203, 0xffff0000, v156
	v_lshlrev_b32_e32 v204, 16, v157
	v_and_b32_e32 v205, 0xffff0000, v157
	v_pk_add_f32 v[202:203], v[202:203], v[198:199] neg_lo:[0,1] neg_hi:[0,1]
	v_pk_add_f32 v[204:205], v[204:205], v[200:201] neg_lo:[0,1] neg_hi:[0,1]
	v_pk_fma_f32 v[202:203], v[202:203], v[2:3], v[198:199]
	v_pk_fma_f32 v[204:205], v[204:205], v[4:5], v[200:201]
	v_lshlrev_b32_e32 v198, 16, v140
	v_and_b32_e32 v199, 0xffff0000, v140
	v_lshlrev_b32_e32 v200, 16, v141
	v_and_b32_e32 v201, 0xffff0000, v141
	v_lshlrev_b32_e32 v206, 16, v160
	v_and_b32_e32 v207, 0xffff0000, v160
	v_lshlrev_b32_e32 v208, 16, v161
	v_and_b32_e32 v209, 0xffff0000, v161
	v_pk_add_f32 v[206:207], v[206:207], v[198:199] neg_lo:[0,1] neg_hi:[0,1]
	v_pk_add_f32 v[208:209], v[208:209], v[200:201] neg_lo:[0,1] neg_hi:[0,1]
	v_pk_fma_f32 v[206:207], v[206:207], v[10:11], v[198:199]
	v_pk_fma_f32 v[208:209], v[208:209], v[12:13], v[200:201]
	v_lshlrev_b32_e32 v198, 16, v144
	v_and_b32_e32 v199, 0xffff0000, v144
	v_lshlrev_b32_e32 v200, 16, v145
	v_and_b32_e32 v201, 0xffff0000, v145
	v_lshlrev_b32_e32 v210, 16, v164
	v_and_b32_e32 v211, 0xffff0000, v164
	v_lshlrev_b32_e32 v212, 16, v165
	v_and_b32_e32 v213, 0xffff0000, v165
	v_pk_add_f32 v[210:211], v[210:211], v[198:199] neg_lo:[0,1] neg_hi:[0,1]
	v_pk_add_f32 v[212:213], v[212:213], v[200:201] neg_lo:[0,1] neg_hi:[0,1]
	v_pk_fma_f32 v[210:211], v[210:211], v[18:19], v[198:199]
	v_pk_fma_f32 v[212:213], v[212:213], v[20:21], v[200:201]
	ds_write_b128 v228, v[210:213] offset:13696
	v_lshlrev_b32_e32 v214, 16, v168
	v_and_b32_e32 v215, 0xffff0000, v168
	v_lshlrev_b32_e32 v216, 16, v169
	v_and_b32_e32 v217, 0xffff0000, v169
	v_pk_mul_f32 v[180:181], v[206:207], v[26:27]
	v_pk_mul_f32 v[182:183], v[208:209], v[28:29]
	v_pk_fma_f32 v[134:135], v[180:181], v[180:181], v[134:135]
	v_pk_fma_f32 v[134:135], v[182:183], v[182:183], v[134:135]
	v_pk_fma_f32 v[198:199], v[214:215], v[34:35], v[42:43]
	v_pk_fma_f32 v[200:201], v[216:217], v[36:37], v[44:45]
	v_pk_mul_f32 v[198:199], v[206:207], v[198:199]
	v_pk_mul_f32 v[200:201], v[208:209], v[200:201]
	ds_write_b128 v228, v[198:201] offset:13184
	v_pk_mul_f32 v[206:207], v[198:199], v[202:203]
	v_pk_mul_f32 v[208:209], v[200:201], v[204:205]
	v_pk_add_f32 v[220:221], v[220:221], v[206:207]
	v_pk_add_f32 v[220:221], v[220:221], v[208:209]
	v_pk_fma_f32 v[222:223], v[206:207], v[50:51], v[222:223]
	v_pk_fma_f32 v[222:223], v[208:209], v[52:53], v[222:223]
	v_pk_mul_f32 v[188:189], v[180:181], v[214:215]
	v_pk_mul_f32 v[190:191], v[182:183], v[216:217]
	v_pk_fma_f32 v[148:149], v[188:189], v[202:203], v[148:149]
	v_pk_fma_f32 v[148:149], v[190:191], v[204:205], v[148:149]
	v_pk_mul_f32 v[210:211], v[172:173], v[202:203]
	v_pk_mul_f32 v[212:213], v[174:175], v[204:205]
	ds_write_b128 v228, v[210:213] offset:12672
	ds_write_b128 v228, v[172:175] offset:12928
	v_lshlrev_b32_e32 v198, 16, v132
	v_and_b32_e32 v199, 0xffff0000, v132
	v_lshlrev_b32_e32 v200, 16, v133
	v_and_b32_e32 v201, 0xffff0000, v133
	v_lshlrev_b32_e32 v202, 16, v158
	v_and_b32_e32 v203, 0xffff0000, v158
	v_lshlrev_b32_e32 v204, 16, v159
	v_and_b32_e32 v205, 0xffff0000, v159
	v_pk_add_f32 v[202:203], v[202:203], v[198:199] neg_lo:[0,1] neg_hi:[0,1]
	v_pk_add_f32 v[204:205], v[204:205], v[200:201] neg_lo:[0,1] neg_hi:[0,1]
	v_pk_fma_f32 v[202:203], v[202:203], v[6:7], v[198:199]
	v_pk_fma_f32 v[204:205], v[204:205], v[8:9], v[200:201]
	v_lshlrev_b32_e32 v198, 16, v142
	v_and_b32_e32 v199, 0xffff0000, v142
	v_lshlrev_b32_e32 v200, 16, v143
	v_and_b32_e32 v201, 0xffff0000, v143
	v_lshlrev_b32_e32 v206, 16, v162
	v_and_b32_e32 v207, 0xffff0000, v162
	v_lshlrev_b32_e32 v208, 16, v163
	v_and_b32_e32 v209, 0xffff0000, v163
	v_pk_add_f32 v[206:207], v[206:207], v[198:199] neg_lo:[0,1] neg_hi:[0,1]
; #define WG_BAR() do { asm volatile("s_waitcnt lgkmcnt(0)" ::: "memory"); __builtin_amdgcn_s_barrier(); asm volatile("" ::: "memory"); } while (0)
; #define SCAN_ITER(D_, SET) do { const int blk = blk0 + (D_); if (blk + 1 < TT / TB) { SCAN_PRODUCE(blk + 1, SET); if (blk + 1 + PD < TT / TB) SCAN_LOAD(blk + 1 + PD, SET); } WG_BAR(); } while (0)
; __global__ void __launch_bounds__(NTHR) hymba_fwd(Params P) {
;     ...
;               SCAN_LOAD(0, 0); SCAN_LOAD(1, 1);
;               SCAN_PRODUCE(0, 0); SCAN_LOAD(2, 0);
;               WG_BAR();
;               static_assert((TT / TB) % PD == 0 && PD == 2, "block loop is unrolled by PD = 2");
;               for (int blk0 = 0; blk0 < TT / TB; blk0 += PD) {
;     ...
;                 SCAN_ITER(0, 1); SCAN_ITER(1, 0);
;     ...
;               }
	v_pk_add_f32 v[208:209], v[208:209], v[200:201] neg_lo:[0,1] neg_hi:[0,1]
	v_pk_fma_f32 v[206:207], v[206:207], v[14:15], v[198:199]
	v_pk_fma_f32 v[208:209], v[208:209], v[16:17], v[200:201]
	v_lshlrev_b32_e32 v198, 16, v146
	v_and_b32_e32 v199, 0xffff0000, v146
	v_lshlrev_b32_e32 v200, 16, v147
	v_and_b32_e32 v201, 0xffff0000, v147
	v_lshlrev_b32_e32 v210, 16, v166
	v_and_b32_e32 v211, 0xffff0000, v166
	v_lshlrev_b32_e32 v212, 16, v167
	v_and_b32_e32 v213, 0xffff0000, v167
	v_pk_add_f32 v[210:211], v[210:211], v[198:199] neg_lo:[0,1] neg_hi:[0,1]
	v_pk_add_f32 v[212:213], v[212:213], v[200:201] neg_lo:[0,1] neg_hi:[0,1]
	v_pk_fma_f32 v[210:211], v[210:211], v[22:23], v[198:199]
	v_pk_fma_f32 v[212:213], v[212:213], v[24:25], v[200:201]
	ds_write_b128 v228, v[210:213] offset:13712
	v_lshlrev_b32_e32 v214, 16, v170
	v_and_b32_e32 v215, 0xffff0000, v170
	v_lshlrev_b32_e32 v216, 16, v171
	v_and_b32_e32 v217, 0xffff0000, v171
	v_pk_mul_f32 v[184:185], v[206:207], v[30:31]
	v_pk_mul_f32 v[186:187], v[208:209], v[32:33]
	v_pk_fma_f32 v[134:135], v[184:185], v[184:185], v[134:135]
	v_pk_fma_f32 v[134:135], v[186:187], v[186:187], v[134:135]
	v_pk_fma_f32 v[198:199], v[214:215], v[38:39], v[46:47]
	v_pk_fma_f32 v[200:201], v[216:217], v[40:41], v[48:49]
	v_pk_mul_f32 v[198:199], v[206:207], v[198:199]
	v_pk_mul_f32 v[200:201], v[208:209], v[200:201]
	ds_write_b128 v228, v[198:201] offset:13200
	v_pk_mul_f32 v[206:207], v[198:199], v[202:203]
	v_pk_mul_f32 v[208:209], v[200:201], v[204:205]
	v_pk_add_f32 v[220:221], v[220:221], v[206:207]
	v_pk_add_f32 v[220:221], v[220:221], v[208:209]
	v_pk_fma_f32 v[222:223], v[206:207], v[54:55], v[222:223]
	v_pk_fma_f32 v[222:223], v[208:209], v[56:57], v[222:223]
	v_pk_mul_f32 v[192:193], v[184:185], v[214:215]
	v_pk_mul_f32 v[194:195], v[186:187], v[216:217]
	v_pk_fma_f32 v[148:149], v[192:193], v[202:203], v[148:149]
	v_pk_fma_f32 v[148:149], v[194:195], v[204:205], v[148:149]
	v_pk_mul_f32 v[210:211], v[176:177], v[202:203]
	v_pk_mul_f32 v[212:213], v[178:179], v[204:205]
	ds_write_b128 v228, v[210:213] offset:12688
	ds_write_b128 v228, v[176:179] offset:12944
	v_add_f32_e32 v134, v134, v135
	v_add_f32_e32 v148, v148, v149
	v_add_f32_e32 v219, v220, v221
	v_add_f32_e32 v222, v222, v223
	v_add_f32_dpp v134, v134, v134 quad_perm:[1,0,3,2] row_mask:0xf bank_mask:0xf bound_ctrl:1
	v_add_f32_dpp v148, v148, v148 quad_perm:[1,0,3,2] row_mask:0xf bank_mask:0xf bound_ctrl:1
	v_add_f32_dpp v219, v219, v219 quad_perm:[1,0,3,2] row_mask:0xf bank_mask:0xf bound_ctrl:1
	v_add_f32_dpp v222, v222, v222 quad_perm:[1,0,3,2] row_mask:0xf bank_mask:0xf bound_ctrl:1
	v_add_f32_dpp v134, v134, v134 quad_perm:[2,3,0,1] row_mask:0xf bank_mask:0xf bound_ctrl:1
	v_add_f32_dpp v148, v148, v148 quad_perm:[2,3,0,1] row_mask:0xf bank_mask:0xf bound_ctrl:1
	v_add_f32_dpp v219, v219, v219 quad_perm:[2,3,0,1] row_mask:0xf bank_mask:0xf bound_ctrl:1
	v_add_f32_dpp v222, v222, v222 quad_perm:[2,3,0,1] row_mask:0xf bank_mask:0xf bound_ctrl:1
	v_add_f32_dpp v134, v134, v134 row_half_mirror row_mask:0xf bank_mask:0xf bound_ctrl:1
	v_add_f32_dpp v148, v148, v148 row_half_mirror row_mask:0xf bank_mask:0xf bound_ctrl:1
	v_add_f32_dpp v219, v219, v219 row_half_mirror row_mask:0xf bank_mask:0xf bound_ctrl:1
	v_add_f32_dpp v222, v222, v222 row_half_mirror row_mask:0xf bank_mask:0xf bound_ctrl:1
	v_max_f32_e32 v134, 0x179abe15, v134
	v_rsq_f32_e32 v224, v134
	s_nop 1
	v_mul_f32_e32 v218, v224, v148
	v_pk_mul_f32 v[198:199], v[180:181], v[224:225] op_sel_hi:[1,0] neg_lo:[0,1] neg_hi:[0,1]
	v_pk_mul_f32 v[200:201], v[182:183], v[224:225] op_sel_hi:[1,0] neg_lo:[0,1] neg_hi:[0,1]
	v_pk_mul_f32 v[206:207], v[184:185], v[224:225] op_sel_hi:[1,0] neg_lo:[0,1] neg_hi:[0,1]
	v_pk_mul_f32 v[208:209], v[186:187], v[224:225] op_sel_hi:[1,0] neg_lo:[0,1] neg_hi:[0,1]
	ds_write_b128 v228, v[198:201] offset:12416
	ds_write_b128 v228, v[206:209] offset:12432
	v_pk_mul_f32 v[214:215], v[188:189], v[224:225] op_sel_hi:[1,0]
	v_pk_mul_f32 v[216:217], v[190:191], v[224:225] op_sel_hi:[1,0]
	v_pk_mul_f32 v[202:203], v[192:193], v[224:225] op_sel_hi:[1,0]
	v_pk_mul_f32 v[204:205], v[194:195], v[224:225] op_sel_hi:[1,0]
	ds_write_b128 v228, v[214:217] offset:13440
	ds_write_b128 v228, v[202:205] offset:13456
	s_mov_b64 exec, s[52:53]
	ds_write_b64 v228, v[218:219] offset:13952
	global_store_dword v227, v222, s[64:65]
	s_mov_b64 exec, -1
	s_add_u32 s64, s64, 0x600
	s_addc_u32 s65, s65, 0
	global_load_dwordx4 v[130:133], v0, s[56:57]
	global_load_dwordx4 v[140:143], v0, s[56:57] offset:2048
	global_load_dwordx4 v[144:147], v0, s[58:59]
	global_load_dwordx4 v[156:159], v155, s[56:57]
	global_load_dwordx4 v[160:163], v155, s[56:57] offset:2048
	global_load_dwordx4 v[164:167], v155, s[58:59]
	global_load_dwordx4 v[168:171], v197, s[60:61]
	global_load_dwordx4 v[172:175], v226, s[62:63]
	global_load_dwordx4 v[176:179], v226, s[62:63] offset:16
	s_add_u32 s56, s56, 0x12000
	s_addc_u32 s57, s57, 0
	s_add_u32 s58, s58, 0x12000
	s_addc_u32 s59, s59, 0
	s_add_u32 s60, s60, 0x4000
	s_addc_u32 s61, s61, 0
	s_add_u32 s62, s62, 0x8000
	s_addc_u32 s63, s63, 0
	s_waitcnt lgkmcnt(0)
	s_barrier
	s_waitcnt vmcnt(20)
	v_mov_b32_e32 v134, 0
	v_mov_b32_e32 v135, 0
	v_mov_b32_e32 v148, 0
	v_mov_b32_e32 v149, 0
	v_mov_b32_e32 v220, 0
	v_mov_b32_e32 v221, 0
	v_mov_b32_e32 v222, 0
	v_mov_b32_e32 v223, 0
	v_lshlrev_b32_e32 v198, 16, v58
	v_and_b32_e32 v199, 0xffff0000, v58
	v_lshlrev_b32_e32 v200, 16, v59
	v_and_b32_e32 v201, 0xffff0000, v59
	v_lshlrev_b32_e32 v202, 16, v70
	v_and_b32_e32 v203, 0xffff0000, v70
	v_lshlrev_b32_e32 v204, 16, v71
	v_and_b32_e32 v205, 0xffff0000, v71
	v_pk_add_f32 v[202:203], v[202:203], v[198:199] neg_lo:[0,1] neg_hi:[0,1]
	v_pk_add_f32 v[204:205], v[204:205], v[200:201] neg_lo:[0,1] neg_hi:[0,1]
	v_pk_fma_f32 v[202:203], v[202:203], v[2:3], v[198:199]
	v_pk_fma_f32 v[204:205], v[204:205], v[4:5], v[200:201]
	v_lshlrev_b32_e32 v198, 16, v62
	v_and_b32_e32 v199, 0xffff0000, v62
	v_lshlrev_b32_e32 v200, 16, v63
	v_and_b32_e32 v201, 0xffff0000, v63
	v_lshlrev_b32_e32 v206, 16, v74
	v_and_b32_e32 v207, 0xffff0000, v74
	v_lshlrev_b32_e32 v208, 16, v75
	v_and_b32_e32 v209, 0xffff0000, v75
	v_pk_add_f32 v[206:207], v[206:207], v[198:199] neg_lo:[0,1] neg_hi:[0,1]
	v_pk_add_f32 v[208:209], v[208:209], v[200:201] neg_lo:[0,1] neg_hi:[0,1]
	v_pk_fma_f32 v[206:207], v[206:207], v[10:11], v[198:199]
	v_pk_fma_f32 v[208:209], v[208:209], v[12:13], v[200:201]
	v_lshlrev_b32_e32 v198, 16, v66
	v_and_b32_e32 v199, 0xffff0000, v66
	v_lshlrev_b32_e32 v200, 16, v67
	v_and_b32_e32 v201, 0xffff0000, v67
	v_lshlrev_b32_e32 v210, 16, v78
	v_and_b32_e32 v211, 0xffff0000, v78
	v_lshlrev_b32_e32 v212, 16, v79
	v_and_b32_e32 v213, 0xffff0000, v79
	v_pk_add_f32 v[210:211], v[210:211], v[198:199] neg_lo:[0,1] neg_hi:[0,1]
	v_pk_add_f32 v[212:213], v[212:213], v[200:201] neg_lo:[0,1] neg_hi:[0,1]
	v_pk_fma_f32 v[210:211], v[210:211], v[18:19], v[198:199]
	v_pk_fma_f32 v[212:213], v[212:213], v[20:21], v[200:201]
	ds_write_b128 v229, v[210:213] offset:1280
	v_lshlrev_b32_e32 v214, 16, v82
	v_and_b32_e32 v215, 0xffff0000, v82
	v_lshlrev_b32_e32 v216, 16, v83
	v_and_b32_e32 v217, 0xffff0000, v83
	v_pk_mul_f32 v[180:181], v[206:207], v[26:27]
	v_pk_mul_f32 v[182:183], v[208:209], v[28:29]
	v_pk_fma_f32 v[134:135], v[180:181], v[180:181], v[134:135]
	v_pk_fma_f32 v[134:135], v[182:183], v[182:183], v[134:135]
	v_pk_fma_f32 v[198:199], v[214:215], v[34:35], v[42:43]
	v_pk_fma_f32 v[200:201], v[216:217], v[36:37], v[44:45]
	v_pk_mul_f32 v[198:199], v[206:207], v[198:199]
	v_pk_mul_f32 v[200:201], v[208:209], v[200:201]
	ds_write_b128 v229, v[198:201] offset:768
	v_pk_mul_f32 v[206:207], v[198:199], v[202:203]
	v_pk_mul_f32 v[208:209], v[200:201], v[204:205]
	v_pk_add_f32 v[220:221], v[220:221], v[206:207]
	v_pk_add_f32 v[220:221], v[220:221], v[208:209]
	v_pk_fma_f32 v[222:223], v[206:207], v[50:51], v[222:223]
	v_pk_fma_f32 v[222:223], v[208:209], v[52:53], v[222:223]
	v_pk_mul_f32 v[188:189], v[180:181], v[214:215]
	v_pk_mul_f32 v[190:191], v[182:183], v[216:217]
	v_pk_fma_f32 v[148:149], v[188:189], v[202:203], v[148:149]
	v_pk_fma_f32 v[148:149], v[190:191], v[204:205], v[148:149]
	v_pk_mul_f32 v[210:211], v[86:87], v[202:203]
	v_pk_mul_f32 v[212:213], v[88:89], v[204:205]
	ds_write_b128 v229, v[210:213] offset:256
	ds_write_b128 v229, v[86:89] offset:512
	v_lshlrev_b32_e32 v198, 16, v60
	v_and_b32_e32 v199, 0xffff0000, v60
	v_lshlrev_b32_e32 v200, 16, v61
	v_and_b32_e32 v201, 0xffff0000, v61
	v_lshlrev_b32_e32 v202, 16, v72
	v_and_b32_e32 v203, 0xffff0000, v72
	v_lshlrev_b32_e32 v204, 16, v73
	v_and_b32_e32 v205, 0xffff0000, v73
	v_pk_add_f32 v[202:203], v[202:203], v[198:199] neg_lo:[0,1] neg_hi:[0,1]
	v_pk_add_f32 v[204:205], v[204:205], v[200:201] neg_lo:[0,1] neg_hi:[0,1]
	v_pk_fma_f32 v[202:203], v[202:203], v[6:7], v[198:199]
	v_pk_fma_f32 v[204:205], v[204:205], v[8:9], v[200:201]
	v_lshlrev_b32_e32 v198, 16, v64
	v_and_b32_e32 v199, 0xffff0000, v64
	v_lshlrev_b32_e32 v200, 16, v65
	v_and_b32_e32 v201, 0xffff0000, v65
	v_lshlrev_b32_e32 v206, 16, v76
	v_and_b32_e32 v207, 0xffff0000, v76
	v_lshlrev_b32_e32 v208, 16, v77
	v_and_b32_e32 v209, 0xffff0000, v77
	v_pk_add_f32 v[206:207], v[206:207], v[198:199] neg_lo:[0,1] neg_hi:[0,1]
	v_pk_add_f32 v[208:209], v[208:209], v[200:201] neg_lo:[0,1] neg_hi:[0,1]
	v_pk_fma_f32 v[206:207], v[206:207], v[14:15], v[198:199]
	v_pk_fma_f32 v[208:209], v[208:209], v[16:17], v[200:201]
	v_lshlrev_b32_e32 v198, 16, v68
	v_and_b32_e32 v199, 0xffff0000, v68
	v_lshlrev_b32_e32 v200, 16, v69
	v_and_b32_e32 v201, 0xffff0000, v69
	v_lshlrev_b32_e32 v210, 16, v80
	v_and_b32_e32 v211, 0xffff0000, v80
	v_lshlrev_b32_e32 v212, 16, v81
	v_and_b32_e32 v213, 0xffff0000, v81
	v_pk_add_f32 v[210:211], v[210:211], v[198:199] neg_lo:[0,1] neg_hi:[0,1]
	v_pk_add_f32 v[212:213], v[212:213], v[200:201] neg_lo:[0,1] neg_hi:[0,1]
	v_pk_fma_f32 v[210:211], v[210:211], v[22:23], v[198:199]
	v_pk_fma_f32 v[212:213], v[212:213], v[24:25], v[200:201]
	ds_write_b128 v229, v[210:213] offset:1296
	v_lshlrev_b32_e32 v214, 16, v84
	v_and_b32_e32 v215, 0xffff0000, v84
	v_lshlrev_b32_e32 v216, 16, v85
	v_and_b32_e32 v217, 0xffff0000, v85
	v_pk_mul_f32 v[184:185], v[206:207], v[30:31]
	v_pk_mul_f32 v[186:187], v[208:209], v[32:33]
	v_pk_fma_f32 v[134:135], v[184:185], v[184:185], v[134:135]
	v_pk_fma_f32 v[134:135], v[186:187], v[186:187], v[134:135]
	v_pk_fma_f32 v[198:199], v[214:215], v[38:39], v[46:47]
	v_pk_fma_f32 v[200:201], v[216:217], v[40:41], v[48:49]
	v_pk_mul_f32 v[198:199], v[206:207], v[198:199]
	v_pk_mul_f32 v[200:201], v[208:209], v[200:201]
	ds_write_b128 v229, v[198:201] offset:784
	v_pk_mul_f32 v[206:207], v[198:199], v[202:203]
	v_pk_mul_f32 v[208:209], v[200:201], v[204:205]
	v_pk_add_f32 v[220:221], v[220:221], v[206:207]
	v_pk_add_f32 v[220:221], v[220:221], v[208:209]
	v_pk_fma_f32 v[222:223], v[206:207], v[54:55], v[222:223]
	v_pk_fma_f32 v[222:223], v[208:209], v[56:57], v[222:223]
	v_pk_mul_f32 v[192:193], v[184:185], v[214:215]
	v_pk_mul_f32 v[194:195], v[186:187], v[216:217]
	v_pk_fma_f32 v[148:149], v[192:193], v[202:203], v[148:149]
	v_pk_fma_f32 v[148:149], v[194:195], v[204:205], v[148:149]
	v_pk_mul_f32 v[210:211], v[90:91], v[202:203]
	v_pk_mul_f32 v[212:213], v[92:93], v[204:205]
	ds_write_b128 v229, v[210:213] offset:272
	ds_write_b128 v229, v[90:93] offset:528
	v_add_f32_e32 v134, v134, v135
	v_add_f32_e32 v148, v148, v149
	v_add_f32_e32 v219, v220, v221
	v_add_f32_e32 v222, v222, v223
	v_add_f32_dpp v134, v134, v134 quad_perm:[1,0,3,2] row_mask:0xf bank_mask:0xf bound_ctrl:1
	v_add_f32_dpp v148, v148, v148 quad_perm:[1,0,3,2] row_mask:0xf bank_mask:0xf bound_ctrl:1
	v_add_f32_dpp v219, v219, v219 quad_perm:[1,0,3,2] row_mask:0xf bank_mask:0xf bound_ctrl:1
	v_add_f32_dpp v222, v222, v222 quad_perm:[1,0,3,2] row_mask:0xf bank_mask:0xf bound_ctrl:1
	v_add_f32_dpp v134, v134, v134 quad_perm:[2,3,0,1] row_mask:0xf bank_mask:0xf bound_ctrl:1
	v_add_f32_dpp v148, v148, v148 quad_perm:[2,3,0,1] row_mask:0xf bank_mask:0xf bound_ctrl:1
	v_add_f32_dpp v219, v219, v219 quad_perm:[2,3,0,1] row_mask:0xf bank_mask:0xf bound_ctrl:1
	v_add_f32_dpp v222, v222, v222 quad_perm:[2,3,0,1] row_mask:0xf bank_mask:0xf bound_ctrl:1
	v_add_f32_dpp v134, v134, v134 row_half_mirror row_mask:0xf bank_mask:0xf bound_ctrl:1
	v_add_f32_dpp v148, v148, v148 row_half_mirror row_mask:0xf bank_mask:0xf bound_ctrl:1
	v_add_f32_dpp v219, v219, v219 row_half_mirror row_mask:0xf bank_mask:0xf bound_ctrl:1
	v_add_f32_dpp v222, v222, v222 row_half_mirror row_mask:0xf bank_mask:0xf bound_ctrl:1
	v_max_f32_e32 v134, 0x179abe15, v134
	v_rsq_f32_e32 v224, v134
	s_nop 1
	v_mul_f32_e32 v218, v224, v148
	v_pk_mul_f32 v[198:199], v[180:181], v[224:225] op_sel_hi:[1,0] neg_lo:[0,1] neg_hi:[0,1]
	v_pk_mul_f32 v[200:201], v[182:183], v[224:225] op_sel_hi:[1,0] neg_lo:[0,1] neg_hi:[0,1]
	v_pk_mul_f32 v[206:207], v[184:185], v[224:225] op_sel_hi:[1,0] neg_lo:[0,1] neg_hi:[0,1]
	v_pk_mul_f32 v[208:209], v[186:187], v[224:225] op_sel_hi:[1,0] neg_lo:[0,1] neg_hi:[0,1]
	ds_write_b128 v229, v[198:201] offset:0
	ds_write_b128 v229, v[206:209] offset:16
	v_pk_mul_f32 v[214:215], v[188:189], v[224:225] op_sel_hi:[1,0]
	v_pk_mul_f32 v[216:217], v[190:191], v[224:225] op_sel_hi:[1,0]
	v_pk_mul_f32 v[202:203], v[192:193], v[224:225] op_sel_hi:[1,0]
	v_pk_mul_f32 v[204:205], v[194:195], v[224:225] op_sel_hi:[1,0]
	ds_write_b128 v229, v[214:217] offset:1024
	ds_write_b128 v229, v[202:205] offset:1040
	s_mov_b64 exec, s[52:53]
	ds_write_b64 v229, v[218:219] offset:1536
	global_store_dword v227, v222, s[64:65]
	s_mov_b64 exec, -1
	s_add_u32 s64, s64, 0x200
	s_addc_u32 s65, s65, 0
	global_load_dwordx4 v[58:61], v0, s[56:57]
	global_load_dwordx4 v[62:65], v0, s[56:57] offset:2048
	global_load_dwordx4 v[66:69], v0, s[58:59]
	global_load_dwordx4 v[70:73], v155, s[56:57]
	global_load_dwordx4 v[74:77], v155, s[56:57] offset:2048
	global_load_dwordx4 v[78:81], v155, s[58:59]
	global_load_dwordx4 v[82:85], v197, s[60:61]
	global_load_dwordx4 v[86:89], v226, s[62:63]
	global_load_dwordx4 v[90:93], v226, s[62:63] offset:16
	s_add_u32 s56, s56, 0x36000
	s_addc_u32 s57, s57, 0
	s_add_u32 s58, s58, 0x36000
	s_addc_u32 s59, s59, 0
	s_add_u32 s60, s60, 0xc000
	s_addc_u32 s61, s61, 0
	s_add_u32 s62, s62, 0x18000
	s_addc_u32 s63, s63, 0
	s_waitcnt vmcnt(20)
	v_mov_b32_e32 v134, 0
	v_mov_b32_e32 v135, 0
	v_mov_b32_e32 v148, 0
	v_mov_b32_e32 v149, 0
	v_mov_b32_e32 v220, 0
	v_mov_b32_e32 v221, 0
	v_mov_b32_e32 v222, 0
	v_mov_b32_e32 v223, 0
	v_lshlrev_b32_e32 v198, 16, v94
	v_and_b32_e32 v199, 0xffff0000, v94
	v_lshlrev_b32_e32 v200, 16, v95
	v_and_b32_e32 v201, 0xffff0000, v95
	v_lshlrev_b32_e32 v202, 16, v106
	v_and_b32_e32 v203, 0xffff0000, v106
	v_lshlrev_b32_e32 v204, 16, v107
	v_and_b32_e32 v205, 0xffff0000, v107
	v_pk_add_f32 v[202:203], v[202:203], v[198:199] neg_lo:[0,1] neg_hi:[0,1]
	v_pk_add_f32 v[204:205], v[204:205], v[200:201] neg_lo:[0,1] neg_hi:[0,1]
	v_pk_fma_f32 v[202:203], v[202:203], v[2:3], v[198:199]
	v_pk_fma_f32 v[204:205], v[204:205], v[4:5], v[200:201]
	v_lshlrev_b32_e32 v198, 16, v98
	v_and_b32_e32 v199, 0xffff0000, v98
	v_lshlrev_b32_e32 v200, 16, v99
	v_and_b32_e32 v201, 0xffff0000, v99
	v_lshlrev_b32_e32 v206, 16, v110
	v_and_b32_e32 v207, 0xffff0000, v110
	v_lshlrev_b32_e32 v208, 16, v111
	v_and_b32_e32 v209, 0xffff0000, v111
	v_pk_add_f32 v[206:207], v[206:207], v[198:199] neg_lo:[0,1] neg_hi:[0,1]
	v_pk_add_f32 v[208:209], v[208:209], v[200:201] neg_lo:[0,1] neg_hi:[0,1]
	v_pk_fma_f32 v[206:207], v[206:207], v[10:11], v[198:199]
	v_pk_fma_f32 v[208:209], v[208:209], v[12:13], v[200:201]
	v_lshlrev_b32_e32 v198, 16, v102
	v_and_b32_e32 v199, 0xffff0000, v102
	v_lshlrev_b32_e32 v200, 16, v103
	v_and_b32_e32 v201, 0xffff0000, v103
	v_lshlrev_b32_e32 v210, 16, v114
	v_and_b32_e32 v211, 0xffff0000, v114
	v_lshlrev_b32_e32 v212, 16, v115
	v_and_b32_e32 v213, 0xffff0000, v115
	v_pk_add_f32 v[210:211], v[210:211], v[198:199] neg_lo:[0,1] neg_hi:[0,1]
	v_pk_add_f32 v[212:213], v[212:213], v[200:201] neg_lo:[0,1] neg_hi:[0,1]
	v_pk_fma_f32 v[210:211], v[210:211], v[18:19], v[198:199]
	v_pk_fma_f32 v[212:213], v[212:213], v[20:21], v[200:201]
	ds_write_b128 v229, v[210:213] offset:13696
	v_lshlrev_b32_e32 v214, 16, v118
	v_and_b32_e32 v215, 0xffff0000, v118
	v_lshlrev_b32_e32 v216, 16, v119
	v_and_b32_e32 v217, 0xffff0000, v119
	v_pk_mul_f32 v[180:181], v[206:207], v[26:27]
	v_pk_mul_f32 v[182:183], v[208:209], v[28:29]
	v_pk_fma_f32 v[134:135], v[180:181], v[180:181], v[134:135]
	v_pk_fma_f32 v[134:135], v[182:183], v[182:183], v[134:135]
	v_pk_fma_f32 v[198:199], v[214:215], v[34:35], v[42:43]
	v_pk_fma_f32 v[200:201], v[216:217], v[36:37], v[44:45]
	v_pk_mul_f32 v[198:199], v[206:207], v[198:199]
	v_pk_mul_f32 v[200:201], v[208:209], v[200:201]
	ds_write_b128 v229, v[198:201] offset:13184
	v_pk_mul_f32 v[206:207], v[198:199], v[202:203]
	v_pk_mul_f32 v[208:209], v[200:201], v[204:205]
	v_pk_add_f32 v[220:221], v[220:221], v[206:207]
	v_pk_add_f32 v[220:221], v[220:221], v[208:209]
	v_pk_fma_f32 v[222:223], v[206:207], v[50:51], v[222:223]
	v_pk_fma_f32 v[222:223], v[208:209], v[52:53], v[222:223]
	v_pk_mul_f32 v[188:189], v[180:181], v[214:215]
	v_pk_mul_f32 v[190:191], v[182:183], v[216:217]
	v_pk_fma_f32 v[148:149], v[188:189], v[202:203], v[148:149]
	v_pk_fma_f32 v[148:149], v[190:191], v[204:205], v[148:149]
	v_pk_mul_f32 v[210:211], v[122:123], v[202:203]
	v_pk_mul_f32 v[212:213], v[124:125], v[204:205]
	ds_write_b128 v229, v[210:213] offset:12672
	ds_write_b128 v229, v[122:125] offset:12928
	v_lshlrev_b32_e32 v198, 16, v96
	v_and_b32_e32 v199, 0xffff0000, v96
	v_lshlrev_b32_e32 v200, 16, v97
	v_and_b32_e32 v201, 0xffff0000, v97
	v_lshlrev_b32_e32 v202, 16, v108
	v_and_b32_e32 v203, 0xffff0000, v108
	v_lshlrev_b32_e32 v204, 16, v109
	v_and_b32_e32 v205, 0xffff0000, v109
	v_pk_add_f32 v[202:203], v[202:203], v[198:199] neg_lo:[0,1] neg_hi:[0,1]
	v_pk_add_f32 v[204:205], v[204:205], v[200:201] neg_lo:[0,1] neg_hi:[0,1]
	v_pk_fma_f32 v[202:203], v[202:203], v[6:7], v[198:199]
	v_pk_fma_f32 v[204:205], v[204:205], v[8:9], v[200:201]
	v_lshlrev_b32_e32 v198, 16, v100
	v_and_b32_e32 v199, 0xffff0000, v100
	v_lshlrev_b32_e32 v200, 16, v101
	v_and_b32_e32 v201, 0xffff0000, v101
	v_lshlrev_b32_e32 v206, 16, v112
	v_and_b32_e32 v207, 0xffff0000, v112
	v_lshlrev_b32_e32 v208, 16, v113
	v_and_b32_e32 v209, 0xffff0000, v113
	v_pk_add_f32 v[206:207], v[206:207], v[198:199] neg_lo:[0,1] neg_hi:[0,1]
	v_pk_add_f32 v[208:209], v[208:209], v[200:201] neg_lo:[0,1] neg_hi:[0,1]
	v_pk_fma_f32 v[206:207], v[206:207], v[14:15], v[198:199]
	v_pk_fma_f32 v[208:209], v[208:209], v[16:17], v[200:201]
	v_lshlrev_b32_e32 v198, 16, v104
	v_and_b32_e32 v199, 0xffff0000, v104
	v_lshlrev_b32_e32 v200, 16, v105
	v_and_b32_e32 v201, 0xffff0000, v105
	v_lshlrev_b32_e32 v210, 16, v116
	v_and_b32_e32 v211, 0xffff0000, v116
	v_lshlrev_b32_e32 v212, 16, v117
	v_and_b32_e32 v213, 0xffff0000, v117
	v_pk_add_f32 v[210:211], v[210:211], v[198:199] neg_lo:[0,1] neg_hi:[0,1]
	v_pk_add_f32 v[212:213], v[212:213], v[200:201] neg_lo:[0,1] neg_hi:[0,1]
	v_pk_fma_f32 v[210:211], v[210:211], v[22:23], v[198:199]
	v_pk_fma_f32 v[212:213], v[212:213], v[24:25], v[200:201]
	ds_write_b128 v229, v[210:213] offset:13712
	v_lshlrev_b32_e32 v214, 16, v120
	v_and_b32_e32 v215, 0xffff0000, v120
	v_lshlrev_b32_e32 v216, 16, v121
	v_and_b32_e32 v217, 0xffff0000, v121
	v_pk_mul_f32 v[184:185], v[206:207], v[30:31]
	v_pk_mul_f32 v[186:187], v[208:209], v[32:33]
	v_pk_fma_f32 v[134:135], v[184:185], v[184:185], v[134:135]
	v_pk_fma_f32 v[134:135], v[186:187], v[186:187], v[134:135]
	v_pk_fma_f32 v[198:199], v[214:215], v[38:39], v[46:47]
	v_pk_fma_f32 v[200:201], v[216:217], v[40:41], v[48:49]
	v_pk_mul_f32 v[198:199], v[206:207], v[198:199]
	v_pk_mul_f32 v[200:201], v[208:209], v[200:201]
	ds_write_b128 v229, v[198:201] offset:13200
	v_pk_mul_f32 v[206:207], v[198:199], v[202:203]
	v_pk_mul_f32 v[208:209], v[200:201], v[204:205]
	v_pk_add_f32 v[220:221], v[220:221], v[206:207]
	v_pk_add_f32 v[220:221], v[220:221], v[208:209]
; #define WG_BAR() do { asm volatile("s_waitcnt lgkmcnt(0)" ::: "memory"); __builtin_amdgcn_s_barrier(); asm volatile("" ::: "memory"); } while (0)
; #define SCAN_ITER(D_, SET) do { const int blk = blk0 + (D_); if (blk + 1 < TT / TB) { SCAN_PRODUCE(blk + 1, SET); if (blk + 1 + PD < TT / TB) SCAN_LOAD(blk + 1 + PD, SET); } WG_BAR(); } while (0)
; __global__ void __launch_bounds__(NTHR) hymba_fwd(Params P) {
;     ...
;               WG_BAR();
;               static_assert((TT / TB) % PD == 0 && PD == 2, "block loop is unrolled by PD = 2");
;               for (int blk0 = 0; blk0 < TT / TB; blk0 += PD) {
;     ...
;                 SCAN_ITER(0, 1); SCAN_ITER(1, 0);
;     ...
;               }
	v_pk_fma_f32 v[222:223], v[206:207], v[54:55], v[222:223]
	v_pk_fma_f32 v[222:223], v[208:209], v[56:57], v[222:223]
	v_pk_mul_f32 v[192:193], v[184:185], v[214:215]
	v_pk_mul_f32 v[194:195], v[186:187], v[216:217]
	v_pk_fma_f32 v[148:149], v[192:193], v[202:203], v[148:149]
	v_pk_fma_f32 v[148:149], v[194:195], v[204:205], v[148:149]
	v_pk_mul_f32 v[210:211], v[126:127], v[202:203]
	v_pk_mul_f32 v[212:213], v[128:129], v[204:205]
	ds_write_b128 v229, v[210:213] offset:12688
	ds_write_b128 v229, v[126:129] offset:12944
	v_add_f32_e32 v134, v134, v135
	v_add_f32_e32 v148, v148, v149
	v_add_f32_e32 v219, v220, v221
	v_add_f32_e32 v222, v222, v223
	v_add_f32_dpp v134, v134, v134 quad_perm:[1,0,3,2] row_mask:0xf bank_mask:0xf bound_ctrl:1
	v_add_f32_dpp v148, v148, v148 quad_perm:[1,0,3,2] row_mask:0xf bank_mask:0xf bound_ctrl:1
	v_add_f32_dpp v219, v219, v219 quad_perm:[1,0,3,2] row_mask:0xf bank_mask:0xf bound_ctrl:1
	v_add_f32_dpp v222, v222, v222 quad_perm:[1,0,3,2] row_mask:0xf bank_mask:0xf bound_ctrl:1
	v_add_f32_dpp v134, v134, v134 quad_perm:[2,3,0,1] row_mask:0xf bank_mask:0xf bound_ctrl:1
	v_add_f32_dpp v148, v148, v148 quad_perm:[2,3,0,1] row_mask:0xf bank_mask:0xf bound_ctrl:1
	v_add_f32_dpp v219, v219, v219 quad_perm:[2,3,0,1] row_mask:0xf bank_mask:0xf bound_ctrl:1
	v_add_f32_dpp v222, v222, v222 quad_perm:[2,3,0,1] row_mask:0xf bank_mask:0xf bound_ctrl:1
	v_add_f32_dpp v134, v134, v134 row_half_mirror row_mask:0xf bank_mask:0xf bound_ctrl:1
	v_add_f32_dpp v148, v148, v148 row_half_mirror row_mask:0xf bank_mask:0xf bound_ctrl:1
	v_add_f32_dpp v219, v219, v219 row_half_mirror row_mask:0xf bank_mask:0xf bound_ctrl:1
	v_add_f32_dpp v222, v222, v222 row_half_mirror row_mask:0xf bank_mask:0xf bound_ctrl:1
	v_max_f32_e32 v134, 0x179abe15, v134
	v_rsq_f32_e32 v224, v134
	s_nop 1
	v_mul_f32_e32 v218, v224, v148
	v_pk_mul_f32 v[198:199], v[180:181], v[224:225] op_sel_hi:[1,0] neg_lo:[0,1] neg_hi:[0,1]
	v_pk_mul_f32 v[200:201], v[182:183], v[224:225] op_sel_hi:[1,0] neg_lo:[0,1] neg_hi:[0,1]
	v_pk_mul_f32 v[206:207], v[184:185], v[224:225] op_sel_hi:[1,0] neg_lo:[0,1] neg_hi:[0,1]
	v_pk_mul_f32 v[208:209], v[186:187], v[224:225] op_sel_hi:[1,0] neg_lo:[0,1] neg_hi:[0,1]
	ds_write_b128 v229, v[198:201] offset:12416
	ds_write_b128 v229, v[206:209] offset:12432
	v_pk_mul_f32 v[214:215], v[188:189], v[224:225] op_sel_hi:[1,0]
	v_pk_mul_f32 v[216:217], v[190:191], v[224:225] op_sel_hi:[1,0]
	v_pk_mul_f32 v[202:203], v[192:193], v[224:225] op_sel_hi:[1,0]
	v_pk_mul_f32 v[204:205], v[194:195], v[224:225] op_sel_hi:[1,0]
	ds_write_b128 v229, v[214:217] offset:13440
	ds_write_b128 v229, v[202:205] offset:13456
	s_mov_b64 exec, s[52:53]
	ds_write_b64 v229, v[218:219] offset:13952
	global_store_dword v227, v222, s[64:65]
	s_mov_b64 exec, -1
	s_add_u32 s64, s64, 0x600
	s_addc_u32 s65, s65, 0
	global_load_dwordx4 v[94:97], v0, s[56:57]
	global_load_dwordx4 v[98:101], v0, s[56:57] offset:2048
	global_load_dwordx4 v[102:105], v0, s[58:59]
	global_load_dwordx4 v[106:109], v155, s[56:57]
	global_load_dwordx4 v[110:113], v155, s[56:57] offset:2048
	global_load_dwordx4 v[114:117], v155, s[58:59]
	global_load_dwordx4 v[118:121], v197, s[60:61]
	global_load_dwordx4 v[122:125], v226, s[62:63]
	global_load_dwordx4 v[126:129], v226, s[62:63] offset:16
	s_add_u32 s56, s56, 0x12000
	s_addc_u32 s57, s57, 0
	s_add_u32 s58, s58, 0x12000
	s_addc_u32 s59, s59, 0
	s_add_u32 s60, s60, 0x4000
	s_addc_u32 s61, s61, 0
	s_add_u32 s62, s62, 0x8000
	s_addc_u32 s63, s63, 0
	s_waitcnt lgkmcnt(0)
	s_barrier
	v_swap_b32 v228, v229
	s_add_i32 s14, s14, -1
	s_cmp_lg_u32 s14, 0
	s_cbranch_scc1 .Lp4p_loop
	s_waitcnt lgkmcnt(0)
	s_barrier

; __global__ void __launch_bounds__(NTHR) hymba_fwd(Params P) {
;     ...
;               const int crow = wv * 8 + (lane >> 3), kq = lane & 7; const bool first8 = kq == 0;
;               f32x2 S2[4];
; #pragma unroll
;               for (int e = 0; e < 4; ++e) S2[e] = (f32x2){0.f, 0.f};
;               const LAS float* recq0 = ldf + kq * 8; const LAS float* recv0 = ldf + 320 + q * 16 + crow;
;               float* yp = Yb + (size_t)(b * TT + 7 - kq) * CW + h * 64 + q * 16 + crow;
;               __builtin_amdgcn_s_setprio(3);
;               WG_BAR();
;               for (int blk = 0; blk < TT / TB; ++blk) {
;                     const int bo = (blk & 1) * (TB * REC);
;                     const LAS float* recq = recq0 + bo; const LAS float* recv = recv0 + bo; const LAS float* recs = ldf + bo + 384;
;     ...
;                     f32x4 av0, av1, bv0, bv1, dw0, dw1, kt0, kt1, wr0, wr1; float vv; f32x2 sc;
;                     f32x4 nav0, nav1, nbv0, nbv1, ndw0, ndw1, nkt0, nkt1, nwr0, nwr1; float nvv; f32x2 nsc;
;                     f32x4 a0, a1, b0, b1, d0, d1, k0, k1, w0_, w1_; float vv_; f32x2 sc_;
;                     LDSTEP(0, a0, a1, b0, b1, d0, d1, k0, k1, w0_, w1_, vv_, sc_);
;                     LDSTEP(REC, av0, av1, bv0, bv1, dw0, dw1, kt0, kt1, wr0, wr1, vv, sc);
;                     float yacc = 0.f;
; #pragma unroll
;                     for (int st = 0; st < TB; ++st) {
;                         if (st + 2 < TB) LDSTEP((st + 2) * REC, nav0, nav1, nbv0, nbv1, ndw0, ndw1, nkt0, nkt1, nwr0, nwr1, nvv, nsc);
;                         __builtin_amdgcn_sched_barrier(0);
;                         const f32x2 pa = pkfma_(S2[3], hi2(a1), pkfma_(S2[2], lo2(a1), pkfma_(S2[1], hi2(a0), pkmul_(S2[0], lo2(a0)))));
;                         const f32x2 py = pkfma_(S2[3], hi2(w1_), pkfma_(S2[2], lo2(w1_), pkfma_(S2[1], hi2(w0_), pkmul_(S2[0], lo2(w0_)))));
;                         float da = pa[0] + pa[1], dy = py[0] + py[1];
;                         da = red8(da); dy = red8(dy);
;                         const float y = dy + da * sc_[0] + vv_ * sc_[1];
;                         { f32x2 dab, vvb; dab[0] = da; dab[1] = da; vvb[0] = vv_; vvb[1] = vv_;
;                           S2[0] = pkfma_b(lo2(k0), vvb, pkfma_b(lo2(b0), dab, pkmul_(S2[0], lo2(d0)))); S2[1] = pkfma_b(hi2(k0), vvb, pkfma_b(hi2(b0), dab, pkmul_(S2[1], hi2(d0))));
.LBB0_851:
	s_andn2_b64 vcc, exec, s[4:5]
	s_cbranch_vccnz .LBB0_672
	v_and_b32_e32 v124, 15, v136
	v_lshrrev_b32_e32 v125, 4, v136
	s_lshl_b32 s4, s95, 2
	s_lshl_b32 s5, s93, 4
	s_add_i32 s4, s4, s5
	v_add_u32_e32 v126, s4, v125
	v_lshlrev_b32_e32 v47, 4, v124
	v_lshlrev_b32_e32 v48, 2, v126
	v_add_u32_e32 v48, 0x500, v48
	v_mov_b32_e32 v49, 0
	s_lshl_b32 s5, s92, 8
	v_lshlrev_b32_e32 v50, 12, v124
	v_lshl_add_u32 v50, v126, 2, v50
	v_add_u32_e32 v50, s5, v50
	s_lshl_b32 s4, s35, 23
	s_add_u32 s8, s88, s4
	s_addc_u32 s9, s89, 0
	v_lshlrev_b32_e32 v51, 8, v126
	v_lshl_add_u32 v51, v124, 4, v51
	s_lshl_b32 s4, s35, 4
	s_add_i32 s4, s4, s92
	s_lshl_b32 s4, s4, 14
	s_add_u32 s22, s88, s4
	s_addc_u32 s23, s89, 0
	s_add_u32 s22, s22, 0x4149200
	s_addc_u32 s23, s23, 0
	v_mov_b32_e32 v36, 0
	v_mov_b32_e32 v37, 0
	v_mov_b32_e32 v38, 0
	v_mov_b32_e32 v39, 0
	v_mov_b32_e32 v46, 0
	s_mov_b32 s10, 0x10001
	s_mov_b32 s11, 0x10001
	s_movk_i32 s14, 64
	s_setprio 3
	s_waitcnt lgkmcnt(0)
	s_barrier
.Lp4c_blk:
	ds_read_b128 v[52:55], v47 offset:0
	ds_read_b128 v[56:59], v47 offset:256
	ds_read_b128 v[60:63], v47 offset:512
	ds_read_b128 v[64:67], v47 offset:768
	ds_read_b32 v72, v48 offset:0
	ds_read_b128 v[68:71], v47 offset:1024
	ds_read_b64 v[74:75], v49 offset:1536
	ds_read_b128 v[76:79], v47 offset:1552
	ds_read_b128 v[80:83], v47 offset:1808
	ds_read_b128 v[84:87], v47 offset:2064
	ds_read_b128 v[88:91], v47 offset:2320
	ds_read_b32 v96, v48 offset:1552
	ds_read_b128 v[92:95], v47 offset:2576
	ds_read_b64 v[98:99], v49 offset:3088
	s_waitcnt lgkmcnt(7)
	ds_read_b128 v[100:103], v47 offset:3104
	ds_read_b128 v[104:107], v47 offset:3360
	ds_read_b128 v[108:111], v47 offset:3616
	ds_read_b128 v[112:115], v47 offset:3872
	ds_read_b32 v120, v48 offset:3104
	ds_read_b128 v[116:119], v47 offset:4128
	ds_read_b64 v[122:123], v49 offset:4640
	v_pk_mul_f32 v[40:41], v[36:37], v[52:53]
	v_pk_mul_f32 v[42:43], v[36:37], v[56:57]
	v_pk_fma_f32 v[40:41], v[38:39], v[54:55], v[40:41]
	v_pk_fma_f32 v[42:43], v[38:39], v[58:59], v[42:43]
	v_add_f32_e32 v44, v40, v41
	v_add_f32_e32 v45, v42, v43
	v_pk_mul_f32 v[36:37], v[36:37], v[60:61]
	v_add_f32_dpp v44, v44, v44 quad_perm:[1,0,3,2] row_mask:0xf bank_mask:0xf bound_ctrl:1
	v_add_f32_dpp v45, v45, v45 quad_perm:[1,0,3,2] row_mask:0xf bank_mask:0xf bound_ctrl:1
	v_pk_mul_f32 v[38:39], v[38:39], v[62:63]
	v_add_f32_dpp v44, v44, v44 quad_perm:[2,3,0,1] row_mask:0xf bank_mask:0xf bound_ctrl:1
	v_add_f32_dpp v45, v45, v45 quad_perm:[2,3,0,1] row_mask:0xf bank_mask:0xf bound_ctrl:1
	v_pk_fma_f32 v[36:37], v[64:65], v[72:73], v[36:37] op_sel_hi:[1,0,1]
	v_add_f32_dpp v44, v44, v44 row_half_mirror row_mask:0xf bank_mask:0xf bound_ctrl:1
	v_add_f32_dpp v45, v45, v45 row_half_mirror row_mask:0xf bank_mask:0xf bound_ctrl:1
	v_pk_fma_f32 v[38:39], v[66:67], v[72:73], v[38:39] op_sel_hi:[1,0,1]
	v_add_f32_dpp v44, v44, v44 row_mirror row_mask:0xf bank_mask:0xf bound_ctrl:1
	v_add_f32_dpp v45, v45, v45 row_mirror row_mask:0xf bank_mask:0xf bound_ctrl:1
	v_pk_fma_f32 v[36:37], v[68:69], v[44:45], v[36:37] op_sel_hi:[1,0,1]
	v_pk_fma_f32 v[38:39], v[70:71], v[44:45], v[38:39] op_sel_hi:[1,0,1]
	v_fmac_f32_e32 v45, v44, v74
	v_fmac_f32_e32 v45, v72, v75
	v_cndmask_b32_e64 v46, v46, v45, s[10:11]
	s_lshl_b64 s[10:11], s[10:11], 1
	s_waitcnt lgkmcnt(7)
	ds_read_b128 v[52:55], v47 offset:4656
	ds_read_b128 v[56:59], v47 offset:4912
	ds_read_b128 v[60:63], v47 offset:5168
	ds_read_b128 v[64:67], v47 offset:5424
	ds_read_b32 v72, v48 offset:4656
	ds_read_b128 v[68:71], v47 offset:5680
	ds_read_b64 v[74:75], v49 offset:6192
	v_pk_mul_f32 v[40:41], v[36:37], v[76:77]
	v_pk_mul_f32 v[42:43], v[36:37], v[80:81]
	v_pk_fma_f32 v[40:41], v[38:39], v[78:79], v[40:41]
	v_pk_fma_f32 v[42:43], v[38:39], v[82:83], v[42:43]
	v_add_f32_e32 v44, v40, v41
	v_add_f32_e32 v45, v42, v43
	v_pk_mul_f32 v[36:37], v[36:37], v[84:85]
	v_add_f32_dpp v44, v44, v44 quad_perm:[1,0,3,2] row_mask:0xf bank_mask:0xf bound_ctrl:1
	v_add_f32_dpp v45, v45, v45 quad_perm:[1,0,3,2] row_mask:0xf bank_mask:0xf bound_ctrl:1
	v_pk_mul_f32 v[38:39], v[38:39], v[86:87]
	v_add_f32_dpp v44, v44, v44 quad_perm:[2,3,0,1] row_mask:0xf bank_mask:0xf bound_ctrl:1
	v_add_f32_dpp v45, v45, v45 quad_perm:[2,3,0,1] row_mask:0xf bank_mask:0xf bound_ctrl:1
	v_pk_fma_f32 v[36:37], v[88:89], v[96:97], v[36:37] op_sel_hi:[1,0,1]
	v_add_f32_dpp v44, v44, v44 row_half_mirror row_mask:0xf bank_mask:0xf bound_ctrl:1
	v_add_f32_dpp v45, v45, v45 row_half_mirror row_mask:0xf bank_mask:0xf bound_ctrl:1
	v_pk_fma_f32 v[38:39], v[90:91], v[96:97], v[38:39] op_sel_hi:[1,0,1]
	v_add_f32_dpp v44, v44, v44 row_mirror row_mask:0xf bank_mask:0xf bound_ctrl:1
	v_add_f32_dpp v45, v45, v45 row_mirror row_mask:0xf bank_mask:0xf bound_ctrl:1
	v_pk_fma_f32 v[36:37], v[92:93], v[44:45], v[36:37] op_sel_hi:[1,0,1]
	v_pk_fma_f32 v[38:39], v[94:95], v[44:45], v[38:39] op_sel_hi:[1,0,1]
	v_fmac_f32_e32 v45, v44, v98
	v_fmac_f32_e32 v45, v96, v99
	v_cndmask_b32_e64 v46, v46, v45, s[10:11]
	s_lshl_b64 s[10:11], s[10:11], 1
	s_waitcnt lgkmcnt(7)
; __device__ __forceinline__ f32x2 pkmul_(f32x2 a, f32x2 b) { f32x2 d; asm("v_pk_mul_f32 %0, %1, %2" : "=v"(d) : "v"(a), "v"(b)); return d; }
; __device__ __forceinline__ f32x2 pkfma_(f32x2 a, f32x2 b, f32x2 c) { f32x2 d; asm("v_pk_fma_f32 %0, %1, %2, %3" : "=v"(d) : "v"(a), "v"(b), "v"(c)); return d; }
; __device__ __forceinline__ f32x2 pkfma_b(f32x2 a, f32x2 s, f32x2 c) { f32x2 d; asm("v_pk_fma_f32 %0, %1, %2, %3 op_sel_hi:[1,0,1]" : "=v"(d) : "v"(a), "v"(s), "v"(c)); return d; }
; __device__ __forceinline__ f32x2 lo2(f32x4 v) { return __builtin_shufflevector(v, v, 0, 1); }
; __device__ __forceinline__ f32x2 hi2(f32x4 v) { return __builtin_shufflevector(v, v, 2, 3); }
; __global__ void __launch_bounds__(NTHR) hymba_fwd(Params P) {
;     ...
;                     for (int st = 0; st < TB; ++st) {
;                         if (st + 2 < TB) LDSTEP((st + 2) * REC, nav0, nav1, nbv0, nbv1, ndw0, ndw1, nkt0, nkt1, nwr0, nwr1, nvv, nsc);
;                         __builtin_amdgcn_sched_barrier(0);
;                         const f32x2 pa = pkfma_(S2[3], hi2(a1), pkfma_(S2[2], lo2(a1), pkfma_(S2[1], hi2(a0), pkmul_(S2[0], lo2(a0)))));
;                         const f32x2 py = pkfma_(S2[3], hi2(w1_), pkfma_(S2[2], lo2(w1_), pkfma_(S2[1], hi2(w0_), pkmul_(S2[0], lo2(w0_)))));
;                         float da = pa[0] + pa[1], dy = py[0] + py[1];
;                         da = red8(da); dy = red8(dy);
;                         const float y = dy + da * sc_[0] + vv_ * sc_[1];
;                         { f32x2 dab, vvb; dab[0] = da; dab[1] = da; vvb[0] = vv_; vvb[1] = vv_;
;                           S2[0] = pkfma_b(lo2(k0), vvb, pkfma_b(lo2(b0), dab, pkmul_(S2[0], lo2(d0)))); S2[1] = pkfma_b(hi2(k0), vvb, pkfma_b(hi2(b0), dab, pkmul_(S2[1], hi2(d0))));
;                           S2[2] = pkfma_b(lo2(k1), vvb, pkfma_b(lo2(b1), dab, pkmul_(S2[2], lo2(d1)))); S2[3] = pkfma_b(hi2(k1), vvb, pkfma_b(hi2(b1), dab, pkmul_(S2[3], hi2(d1)))); }
;                         const float sh = __int_as_float(__builtin_amdgcn_update_dpp(__float_as_int(y), __float_as_int(yacc), 0x111, 0xF, 0xF, false));
;                         yacc = first8 ? y : sh;
;                         if ((st & 7) == 7) yp[(size_t)(blk * TB + (st - 7)) * CW] = yacc;
;                         a0 = av0; a1 = av1; b0 = bv0; b1 = bv1; d0 = dw0; d1 = dw1; k0 = kt0; k1 = kt1; w0_ = wr0; w1_ = wr1; vv_ = vv; sc_ = sc;
	ds_read_b128 v[76:79], v47 offset:6208
	ds_read_b128 v[80:83], v47 offset:6464
	ds_read_b128 v[84:87], v47 offset:6720
	ds_read_b128 v[88:91], v47 offset:6976
	ds_read_b32 v96, v48 offset:6208
	ds_read_b128 v[92:95], v47 offset:7232
	ds_read_b64 v[98:99], v49 offset:7744
	v_pk_mul_f32 v[40:41], v[36:37], v[100:101]
	v_pk_mul_f32 v[42:43], v[36:37], v[104:105]
	v_pk_fma_f32 v[40:41], v[38:39], v[102:103], v[40:41]
	v_pk_fma_f32 v[42:43], v[38:39], v[106:107], v[42:43]
	v_add_f32_e32 v44, v40, v41
	v_add_f32_e32 v45, v42, v43
	v_pk_mul_f32 v[36:37], v[36:37], v[108:109]
	v_add_f32_dpp v44, v44, v44 quad_perm:[1,0,3,2] row_mask:0xf bank_mask:0xf bound_ctrl:1
	v_add_f32_dpp v45, v45, v45 quad_perm:[1,0,3,2] row_mask:0xf bank_mask:0xf bound_ctrl:1
	v_pk_mul_f32 v[38:39], v[38:39], v[110:111]
	v_add_f32_dpp v44, v44, v44 quad_perm:[2,3,0,1] row_mask:0xf bank_mask:0xf bound_ctrl:1
	v_add_f32_dpp v45, v45, v45 quad_perm:[2,3,0,1] row_mask:0xf bank_mask:0xf bound_ctrl:1
	v_pk_fma_f32 v[36:37], v[112:113], v[120:121], v[36:37] op_sel_hi:[1,0,1]
	v_add_f32_dpp v44, v44, v44 row_half_mirror row_mask:0xf bank_mask:0xf bound_ctrl:1
	v_add_f32_dpp v45, v45, v45 row_half_mirror row_mask:0xf bank_mask:0xf bound_ctrl:1
	v_pk_fma_f32 v[38:39], v[114:115], v[120:121], v[38:39] op_sel_hi:[1,0,1]
	v_add_f32_dpp v44, v44, v44 row_mirror row_mask:0xf bank_mask:0xf bound_ctrl:1
	v_add_f32_dpp v45, v45, v45 row_mirror row_mask:0xf bank_mask:0xf bound_ctrl:1
	v_pk_fma_f32 v[36:37], v[116:117], v[44:45], v[36:37] op_sel_hi:[1,0,1]
	v_pk_fma_f32 v[38:39], v[118:119], v[44:45], v[38:39] op_sel_hi:[1,0,1]
	v_fmac_f32_e32 v45, v44, v122
	v_fmac_f32_e32 v45, v120, v123
	v_cndmask_b32_e64 v46, v46, v45, s[10:11]
	s_lshl_b64 s[10:11], s[10:11], 1
	s_waitcnt lgkmcnt(7)
	ds_read_b128 v[100:103], v47 offset:7760
	ds_read_b128 v[104:107], v47 offset:8016
	ds_read_b128 v[108:111], v47 offset:8272
	ds_read_b128 v[112:115], v47 offset:8528
	ds_read_b32 v120, v48 offset:7760
	ds_read_b128 v[116:119], v47 offset:8784
	ds_read_b64 v[122:123], v49 offset:9296
	v_pk_mul_f32 v[40:41], v[36:37], v[52:53]
	v_pk_mul_f32 v[42:43], v[36:37], v[56:57]
	v_pk_fma_f32 v[40:41], v[38:39], v[54:55], v[40:41]
	v_pk_fma_f32 v[42:43], v[38:39], v[58:59], v[42:43]
	v_add_f32_e32 v44, v40, v41
	v_add_f32_e32 v45, v42, v43
	v_pk_mul_f32 v[36:37], v[36:37], v[60:61]
	v_add_f32_dpp v44, v44, v44 quad_perm:[1,0,3,2] row_mask:0xf bank_mask:0xf bound_ctrl:1
	v_add_f32_dpp v45, v45, v45 quad_perm:[1,0,3,2] row_mask:0xf bank_mask:0xf bound_ctrl:1
	v_pk_mul_f32 v[38:39], v[38:39], v[62:63]
	v_add_f32_dpp v44, v44, v44 quad_perm:[2,3,0,1] row_mask:0xf bank_mask:0xf bound_ctrl:1
	v_add_f32_dpp v45, v45, v45 quad_perm:[2,3,0,1] row_mask:0xf bank_mask:0xf bound_ctrl:1
	v_pk_fma_f32 v[36:37], v[64:65], v[72:73], v[36:37] op_sel_hi:[1,0,1]
	v_add_f32_dpp v44, v44, v44 row_half_mirror row_mask:0xf bank_mask:0xf bound_ctrl:1
	v_add_f32_dpp v45, v45, v45 row_half_mirror row_mask:0xf bank_mask:0xf bound_ctrl:1
	v_pk_fma_f32 v[38:39], v[66:67], v[72:73], v[38:39] op_sel_hi:[1,0,1]
	v_add_f32_dpp v44, v44, v44 row_mirror row_mask:0xf bank_mask:0xf bound_ctrl:1
	v_add_f32_dpp v45, v45, v45 row_mirror row_mask:0xf bank_mask:0xf bound_ctrl:1
	v_pk_fma_f32 v[36:37], v[68:69], v[44:45], v[36:37] op_sel_hi:[1,0,1]
	v_pk_fma_f32 v[38:39], v[70:71], v[44:45], v[38:39] op_sel_hi:[1,0,1]
	v_fmac_f32_e32 v45, v44, v74
	v_fmac_f32_e32 v45, v72, v75
	v_cndmask_b32_e64 v46, v46, v45, s[10:11]
	s_lshl_b64 s[10:11], s[10:11], 1
	s_waitcnt lgkmcnt(7)
	ds_read_b128 v[52:55], v47 offset:9312
	ds_read_b128 v[56:59], v47 offset:9568
	ds_read_b128 v[60:63], v47 offset:9824
	ds_read_b128 v[64:67], v47 offset:10080
	ds_read_b32 v72, v48 offset:9312
	ds_read_b128 v[68:71], v47 offset:10336
	ds_read_b64 v[74:75], v49 offset:10848
	v_pk_mul_f32 v[40:41], v[36:37], v[76:77]
	v_pk_mul_f32 v[42:43], v[36:37], v[80:81]
	v_pk_fma_f32 v[40:41], v[38:39], v[78:79], v[40:41]
	v_pk_fma_f32 v[42:43], v[38:39], v[82:83], v[42:43]
	v_add_f32_e32 v44, v40, v41
	v_add_f32_e32 v45, v42, v43
	v_pk_mul_f32 v[36:37], v[36:37], v[84:85]
	v_add_f32_dpp v44, v44, v44 quad_perm:[1,0,3,2] row_mask:0xf bank_mask:0xf bound_ctrl:1
	v_add_f32_dpp v45, v45, v45 quad_perm:[1,0,3,2] row_mask:0xf bank_mask:0xf bound_ctrl:1
	v_pk_mul_f32 v[38:39], v[38:39], v[86:87]
	v_add_f32_dpp v44, v44, v44 quad_perm:[2,3,0,1] row_mask:0xf bank_mask:0xf bound_ctrl:1
	v_add_f32_dpp v45, v45, v45 quad_perm:[2,3,0,1] row_mask:0xf bank_mask:0xf bound_ctrl:1
	v_pk_fma_f32 v[36:37], v[88:89], v[96:97], v[36:37] op_sel_hi:[1,0,1]
	v_add_f32_dpp v44, v44, v44 row_half_mirror row_mask:0xf bank_mask:0xf bound_ctrl:1
	v_add_f32_dpp v45, v45, v45 row_half_mirror row_mask:0xf bank_mask:0xf bound_ctrl:1
	v_pk_fma_f32 v[38:39], v[90:91], v[96:97], v[38:39] op_sel_hi:[1,0,1]
	v_add_f32_dpp v44, v44, v44 row_mirror row_mask:0xf bank_mask:0xf bound_ctrl:1
	v_add_f32_dpp v45, v45, v45 row_mirror row_mask:0xf bank_mask:0xf bound_ctrl:1
	v_pk_fma_f32 v[36:37], v[92:93], v[44:45], v[36:37] op_sel_hi:[1,0,1]
	v_pk_fma_f32 v[38:39], v[94:95], v[44:45], v[38:39] op_sel_hi:[1,0,1]
	v_fmac_f32_e32 v45, v44, v98
	v_fmac_f32_e32 v45, v96, v99
	v_cndmask_b32_e64 v46, v46, v45, s[10:11]
	s_lshl_b64 s[10:11], s[10:11], 1
	s_waitcnt lgkmcnt(7)
; __device__ __forceinline__ f32x2 pkmul_(f32x2 a, f32x2 b) { f32x2 d; asm("v_pk_mul_f32 %0, %1, %2" : "=v"(d) : "v"(a), "v"(b)); return d; }
; __device__ __forceinline__ f32x2 pkfma_(f32x2 a, f32x2 b, f32x2 c) { f32x2 d; asm("v_pk_fma_f32 %0, %1, %2, %3" : "=v"(d) : "v"(a), "v"(b), "v"(c)); return d; }
; __device__ __forceinline__ f32x2 pkfma_b(f32x2 a, f32x2 s, f32x2 c) { f32x2 d; asm("v_pk_fma_f32 %0, %1, %2, %3 op_sel_hi:[1,0,1]" : "=v"(d) : "v"(a), "v"(s), "v"(c)); return d; }
; __device__ __forceinline__ f32x2 lo2(f32x4 v) { return __builtin_shufflevector(v, v, 0, 1); }
; __device__ __forceinline__ f32x2 hi2(f32x4 v) { return __builtin_shufflevector(v, v, 2, 3); }
; __global__ void __launch_bounds__(NTHR) hymba_fwd(Params P) {
;     ...
;                     for (int st = 0; st < TB; ++st) {
;                         if (st + 2 < TB) LDSTEP((st + 2) * REC, nav0, nav1, nbv0, nbv1, ndw0, ndw1, nkt0, nkt1, nwr0, nwr1, nvv, nsc);
;                         __builtin_amdgcn_sched_barrier(0);
;                         const f32x2 pa = pkfma_(S2[3], hi2(a1), pkfma_(S2[2], lo2(a1), pkfma_(S2[1], hi2(a0), pkmul_(S2[0], lo2(a0)))));
;                         const f32x2 py = pkfma_(S2[3], hi2(w1_), pkfma_(S2[2], lo2(w1_), pkfma_(S2[1], hi2(w0_), pkmul_(S2[0], lo2(w0_)))));
;                         float da = pa[0] + pa[1], dy = py[0] + py[1];
;                         da = red8(da); dy = red8(dy);
;                         const float y = dy + da * sc_[0] + vv_ * sc_[1];
;                         { f32x2 dab, vvb; dab[0] = da; dab[1] = da; vvb[0] = vv_; vvb[1] = vv_;
;                           S2[0] = pkfma_b(lo2(k0), vvb, pkfma_b(lo2(b0), dab, pkmul_(S2[0], lo2(d0)))); S2[1] = pkfma_b(hi2(k0), vvb, pkfma_b(hi2(b0), dab, pkmul_(S2[1], hi2(d0))));
;                           S2[2] = pkfma_b(lo2(k1), vvb, pkfma_b(lo2(b1), dab, pkmul_(S2[2], lo2(d1)))); S2[3] = pkfma_b(hi2(k1), vvb, pkfma_b(hi2(b1), dab, pkmul_(S2[3], hi2(d1)))); }
;                         const float sh = __int_as_float(__builtin_amdgcn_update_dpp(__float_as_int(y), __float_as_int(yacc), 0x111, 0xF, 0xF, false));
;                         yacc = first8 ? y : sh;
;                         if ((st & 7) == 7) yp[(size_t)(blk * TB + (st - 7)) * CW] = yacc;
;                         a0 = av0; a1 = av1; b0 = bv0; b1 = bv1; d0 = dw0; d1 = dw1; k0 = kt0; k1 = kt1; w0_ = wr0; w1_ = wr1; vv_ = vv; sc_ = sc;
	ds_read_b128 v[76:79], v47 offset:10864
	ds_read_b128 v[80:83], v47 offset:11120
	ds_read_b128 v[84:87], v47 offset:11376
	ds_read_b128 v[88:91], v47 offset:11632
	ds_read_b32 v96, v48 offset:10864
	ds_read_b128 v[92:95], v47 offset:11888
	ds_read_b64 v[98:99], v49 offset:12400
	v_pk_mul_f32 v[40:41], v[36:37], v[100:101]
	v_pk_mul_f32 v[42:43], v[36:37], v[104:105]
	v_pk_fma_f32 v[40:41], v[38:39], v[102:103], v[40:41]
	v_pk_fma_f32 v[42:43], v[38:39], v[106:107], v[42:43]
	v_add_f32_e32 v44, v40, v41
	v_add_f32_e32 v45, v42, v43
	v_pk_mul_f32 v[36:37], v[36:37], v[108:109]
	v_add_f32_dpp v44, v44, v44 quad_perm:[1,0,3,2] row_mask:0xf bank_mask:0xf bound_ctrl:1
	v_add_f32_dpp v45, v45, v45 quad_perm:[1,0,3,2] row_mask:0xf bank_mask:0xf bound_ctrl:1
	v_pk_mul_f32 v[38:39], v[38:39], v[110:111]
	v_add_f32_dpp v44, v44, v44 quad_perm:[2,3,0,1] row_mask:0xf bank_mask:0xf bound_ctrl:1
	v_add_f32_dpp v45, v45, v45 quad_perm:[2,3,0,1] row_mask:0xf bank_mask:0xf bound_ctrl:1
	v_pk_fma_f32 v[36:37], v[112:113], v[120:121], v[36:37] op_sel_hi:[1,0,1]
	v_add_f32_dpp v44, v44, v44 row_half_mirror row_mask:0xf bank_mask:0xf bound_ctrl:1
	v_add_f32_dpp v45, v45, v45 row_half_mirror row_mask:0xf bank_mask:0xf bound_ctrl:1
	v_pk_fma_f32 v[38:39], v[114:115], v[120:121], v[38:39] op_sel_hi:[1,0,1]
	v_add_f32_dpp v44, v44, v44 row_mirror row_mask:0xf bank_mask:0xf bound_ctrl:1
	v_add_f32_dpp v45, v45, v45 row_mirror row_mask:0xf bank_mask:0xf bound_ctrl:1
	v_pk_fma_f32 v[36:37], v[116:117], v[44:45], v[36:37] op_sel_hi:[1,0,1]
	v_pk_fma_f32 v[38:39], v[118:119], v[44:45], v[38:39] op_sel_hi:[1,0,1]
	v_fmac_f32_e32 v45, v44, v122
	v_fmac_f32_e32 v45, v120, v123
	v_cndmask_b32_e64 v46, v46, v45, s[10:11]
	s_lshl_b64 s[10:11], s[10:11], 1
	s_waitcnt lgkmcnt(7)
	ds_read_b128 v[100:103], v47 offset:12416
	ds_read_b128 v[104:107], v47 offset:12672
	ds_read_b128 v[108:111], v47 offset:12928
	ds_read_b128 v[112:115], v47 offset:13184
	ds_read_b32 v120, v48 offset:12416
	ds_read_b128 v[116:119], v47 offset:13440
	ds_read_b64 v[122:123], v49 offset:13952
	v_pk_mul_f32 v[40:41], v[36:37], v[52:53]
	v_pk_mul_f32 v[42:43], v[36:37], v[56:57]
	v_pk_fma_f32 v[40:41], v[38:39], v[54:55], v[40:41]
	v_pk_fma_f32 v[42:43], v[38:39], v[58:59], v[42:43]
	v_add_f32_e32 v44, v40, v41
	v_add_f32_e32 v45, v42, v43
	v_pk_mul_f32 v[36:37], v[36:37], v[60:61]
	v_add_f32_dpp v44, v44, v44 quad_perm:[1,0,3,2] row_mask:0xf bank_mask:0xf bound_ctrl:1
	v_add_f32_dpp v45, v45, v45 quad_perm:[1,0,3,2] row_mask:0xf bank_mask:0xf bound_ctrl:1
	v_pk_mul_f32 v[38:39], v[38:39], v[62:63]
	v_add_f32_dpp v44, v44, v44 quad_perm:[2,3,0,1] row_mask:0xf bank_mask:0xf bound_ctrl:1
	v_add_f32_dpp v45, v45, v45 quad_perm:[2,3,0,1] row_mask:0xf bank_mask:0xf bound_ctrl:1
	v_pk_fma_f32 v[36:37], v[64:65], v[72:73], v[36:37] op_sel_hi:[1,0,1]
	v_add_f32_dpp v44, v44, v44 row_half_mirror row_mask:0xf bank_mask:0xf bound_ctrl:1
	v_add_f32_dpp v45, v45, v45 row_half_mirror row_mask:0xf bank_mask:0xf bound_ctrl:1
	v_pk_fma_f32 v[38:39], v[66:67], v[72:73], v[38:39] op_sel_hi:[1,0,1]
	v_add_f32_dpp v44, v44, v44 row_mirror row_mask:0xf bank_mask:0xf bound_ctrl:1
	v_add_f32_dpp v45, v45, v45 row_mirror row_mask:0xf bank_mask:0xf bound_ctrl:1
	v_pk_fma_f32 v[36:37], v[68:69], v[44:45], v[36:37] op_sel_hi:[1,0,1]
	v_pk_fma_f32 v[38:39], v[70:71], v[44:45], v[38:39] op_sel_hi:[1,0,1]
	v_fmac_f32_e32 v45, v44, v74
	v_fmac_f32_e32 v45, v72, v75
	v_cndmask_b32_e64 v46, v46, v45, s[10:11]
	s_lshl_b64 s[10:11], s[10:11], 1
	s_waitcnt lgkmcnt(7)
	ds_read_b128 v[52:55], v47 offset:13968
	ds_read_b128 v[56:59], v47 offset:14224
	ds_read_b128 v[60:63], v47 offset:14480
	ds_read_b128 v[64:67], v47 offset:14736
	ds_read_b32 v72, v48 offset:13968
	ds_read_b128 v[68:71], v47 offset:14992
	ds_read_b64 v[74:75], v49 offset:15504
	v_pk_mul_f32 v[40:41], v[36:37], v[76:77]
	v_pk_mul_f32 v[42:43], v[36:37], v[80:81]
	v_pk_fma_f32 v[40:41], v[38:39], v[78:79], v[40:41]
	v_pk_fma_f32 v[42:43], v[38:39], v[82:83], v[42:43]
	v_add_f32_e32 v44, v40, v41
	v_add_f32_e32 v45, v42, v43
	v_pk_mul_f32 v[36:37], v[36:37], v[84:85]
	v_add_f32_dpp v44, v44, v44 quad_perm:[1,0,3,2] row_mask:0xf bank_mask:0xf bound_ctrl:1
	v_add_f32_dpp v45, v45, v45 quad_perm:[1,0,3,2] row_mask:0xf bank_mask:0xf bound_ctrl:1
	v_pk_mul_f32 v[38:39], v[38:39], v[86:87]
	v_add_f32_dpp v44, v44, v44 quad_perm:[2,3,0,1] row_mask:0xf bank_mask:0xf bound_ctrl:1
	v_add_f32_dpp v45, v45, v45 quad_perm:[2,3,0,1] row_mask:0xf bank_mask:0xf bound_ctrl:1
	v_pk_fma_f32 v[36:37], v[88:89], v[96:97], v[36:37] op_sel_hi:[1,0,1]
	v_add_f32_dpp v44, v44, v44 row_half_mirror row_mask:0xf bank_mask:0xf bound_ctrl:1
	v_add_f32_dpp v45, v45, v45 row_half_mirror row_mask:0xf bank_mask:0xf bound_ctrl:1
	v_pk_fma_f32 v[38:39], v[90:91], v[96:97], v[38:39] op_sel_hi:[1,0,1]
	v_add_f32_dpp v44, v44, v44 row_mirror row_mask:0xf bank_mask:0xf bound_ctrl:1
	v_add_f32_dpp v45, v45, v45 row_mirror row_mask:0xf bank_mask:0xf bound_ctrl:1
	v_pk_fma_f32 v[36:37], v[92:93], v[44:45], v[36:37] op_sel_hi:[1,0,1]
	v_pk_fma_f32 v[38:39], v[94:95], v[44:45], v[38:39] op_sel_hi:[1,0,1]
	v_fmac_f32_e32 v45, v44, v98
	v_fmac_f32_e32 v45, v96, v99
	v_cndmask_b32_e64 v46, v46, v45, s[10:11]
	s_lshl_b64 s[10:11], s[10:11], 1
	s_waitcnt lgkmcnt(7)
; __device__ __forceinline__ f32x2 pkmul_(f32x2 a, f32x2 b) { f32x2 d; asm("v_pk_mul_f32 %0, %1, %2" : "=v"(d) : "v"(a), "v"(b)); return d; }
; __device__ __forceinline__ f32x2 pkfma_(f32x2 a, f32x2 b, f32x2 c) { f32x2 d; asm("v_pk_fma_f32 %0, %1, %2, %3" : "=v"(d) : "v"(a), "v"(b), "v"(c)); return d; }
; __device__ __forceinline__ f32x2 pkfma_b(f32x2 a, f32x2 s, f32x2 c) { f32x2 d; asm("v_pk_fma_f32 %0, %1, %2, %3 op_sel_hi:[1,0,1]" : "=v"(d) : "v"(a), "v"(s), "v"(c)); return d; }
; __device__ __forceinline__ f32x2 lo2(f32x4 v) { return __builtin_shufflevector(v, v, 0, 1); }
; __device__ __forceinline__ f32x2 hi2(f32x4 v) { return __builtin_shufflevector(v, v, 2, 3); }
; __global__ void __launch_bounds__(NTHR) hymba_fwd(Params P) {
;     ...
;                     for (int st = 0; st < TB; ++st) {
;                         if (st + 2 < TB) LDSTEP((st + 2) * REC, nav0, nav1, nbv0, nbv1, ndw0, ndw1, nkt0, nkt1, nwr0, nwr1, nvv, nsc);
;                         __builtin_amdgcn_sched_barrier(0);
;                         const f32x2 pa = pkfma_(S2[3], hi2(a1), pkfma_(S2[2], lo2(a1), pkfma_(S2[1], hi2(a0), pkmul_(S2[0], lo2(a0)))));
;                         const f32x2 py = pkfma_(S2[3], hi2(w1_), pkfma_(S2[2], lo2(w1_), pkfma_(S2[1], hi2(w0_), pkmul_(S2[0], lo2(w0_)))));
;                         float da = pa[0] + pa[1], dy = py[0] + py[1];
;                         da = red8(da); dy = red8(dy);
;                         const float y = dy + da * sc_[0] + vv_ * sc_[1];
;                         { f32x2 dab, vvb; dab[0] = da; dab[1] = da; vvb[0] = vv_; vvb[1] = vv_;
;                           S2[0] = pkfma_b(lo2(k0), vvb, pkfma_b(lo2(b0), dab, pkmul_(S2[0], lo2(d0)))); S2[1] = pkfma_b(hi2(k0), vvb, pkfma_b(hi2(b0), dab, pkmul_(S2[1], hi2(d0))));
;                           S2[2] = pkfma_b(lo2(k1), vvb, pkfma_b(lo2(b1), dab, pkmul_(S2[2], lo2(d1)))); S2[3] = pkfma_b(hi2(k1), vvb, pkfma_b(hi2(b1), dab, pkmul_(S2[3], hi2(d1)))); }
;                         const float sh = __int_as_float(__builtin_amdgcn_update_dpp(__float_as_int(y), __float_as_int(yacc), 0x111, 0xF, 0xF, false));
;                         yacc = first8 ? y : sh;
;                         if ((st & 7) == 7) yp[(size_t)(blk * TB + (st - 7)) * CW] = yacc;
;                         a0 = av0; a1 = av1; b0 = bv0; b1 = bv1; d0 = dw0; d1 = dw1; k0 = kt0; k1 = kt1; w0_ = wr0; w1_ = wr1; vv_ = vv; sc_ = sc;
	ds_read_b128 v[76:79], v47 offset:15520
	ds_read_b128 v[80:83], v47 offset:15776
	ds_read_b128 v[84:87], v47 offset:16032
	ds_read_b128 v[88:91], v47 offset:16288
	ds_read_b32 v96, v48 offset:15520
	ds_read_b128 v[92:95], v47 offset:16544
	ds_read_b64 v[98:99], v49 offset:17056
	v_pk_mul_f32 v[40:41], v[36:37], v[100:101]
	v_pk_mul_f32 v[42:43], v[36:37], v[104:105]
	v_pk_fma_f32 v[40:41], v[38:39], v[102:103], v[40:41]
	v_pk_fma_f32 v[42:43], v[38:39], v[106:107], v[42:43]
	v_add_f32_e32 v44, v40, v41
	v_add_f32_e32 v45, v42, v43
	v_pk_mul_f32 v[36:37], v[36:37], v[108:109]
	v_add_f32_dpp v44, v44, v44 quad_perm:[1,0,3,2] row_mask:0xf bank_mask:0xf bound_ctrl:1
	v_add_f32_dpp v45, v45, v45 quad_perm:[1,0,3,2] row_mask:0xf bank_mask:0xf bound_ctrl:1
	v_pk_mul_f32 v[38:39], v[38:39], v[110:111]
	v_add_f32_dpp v44, v44, v44 quad_perm:[2,3,0,1] row_mask:0xf bank_mask:0xf bound_ctrl:1
	v_add_f32_dpp v45, v45, v45 quad_perm:[2,3,0,1] row_mask:0xf bank_mask:0xf bound_ctrl:1
	v_pk_fma_f32 v[36:37], v[112:113], v[120:121], v[36:37] op_sel_hi:[1,0,1]
	v_add_f32_dpp v44, v44, v44 row_half_mirror row_mask:0xf bank_mask:0xf bound_ctrl:1
	v_add_f32_dpp v45, v45, v45 row_half_mirror row_mask:0xf bank_mask:0xf bound_ctrl:1
	v_pk_fma_f32 v[38:39], v[114:115], v[120:121], v[38:39] op_sel_hi:[1,0,1]
	v_add_f32_dpp v44, v44, v44 row_mirror row_mask:0xf bank_mask:0xf bound_ctrl:1
	v_add_f32_dpp v45, v45, v45 row_mirror row_mask:0xf bank_mask:0xf bound_ctrl:1
	v_pk_fma_f32 v[36:37], v[116:117], v[44:45], v[36:37] op_sel_hi:[1,0,1]
	v_pk_fma_f32 v[38:39], v[118:119], v[44:45], v[38:39] op_sel_hi:[1,0,1]
	v_fmac_f32_e32 v45, v44, v122
	v_fmac_f32_e32 v45, v120, v123
	v_cndmask_b32_e64 v46, v46, v45, s[10:11]
	s_lshl_b64 s[10:11], s[10:11], 1
	s_waitcnt lgkmcnt(7)
	ds_read_b128 v[100:103], v47 offset:17072
	ds_read_b128 v[104:107], v47 offset:17328
	ds_read_b128 v[108:111], v47 offset:17584
	ds_read_b128 v[112:115], v47 offset:17840
	ds_read_b32 v120, v48 offset:17072
	ds_read_b128 v[116:119], v47 offset:18096
	ds_read_b64 v[122:123], v49 offset:18608
	v_pk_mul_f32 v[40:41], v[36:37], v[52:53]
	v_pk_mul_f32 v[42:43], v[36:37], v[56:57]
	v_pk_fma_f32 v[40:41], v[38:39], v[54:55], v[40:41]
	v_pk_fma_f32 v[42:43], v[38:39], v[58:59], v[42:43]
	v_add_f32_e32 v44, v40, v41
	v_add_f32_e32 v45, v42, v43
	v_pk_mul_f32 v[36:37], v[36:37], v[60:61]
	v_add_f32_dpp v44, v44, v44 quad_perm:[1,0,3,2] row_mask:0xf bank_mask:0xf bound_ctrl:1
	v_add_f32_dpp v45, v45, v45 quad_perm:[1,0,3,2] row_mask:0xf bank_mask:0xf bound_ctrl:1
	v_pk_mul_f32 v[38:39], v[38:39], v[62:63]
	v_add_f32_dpp v44, v44, v44 quad_perm:[2,3,0,1] row_mask:0xf bank_mask:0xf bound_ctrl:1
	v_add_f32_dpp v45, v45, v45 quad_perm:[2,3,0,1] row_mask:0xf bank_mask:0xf bound_ctrl:1
	v_pk_fma_f32 v[36:37], v[64:65], v[72:73], v[36:37] op_sel_hi:[1,0,1]
	v_add_f32_dpp v44, v44, v44 row_half_mirror row_mask:0xf bank_mask:0xf bound_ctrl:1
	v_add_f32_dpp v45, v45, v45 row_half_mirror row_mask:0xf bank_mask:0xf bound_ctrl:1
	v_pk_fma_f32 v[38:39], v[66:67], v[72:73], v[38:39] op_sel_hi:[1,0,1]
	v_add_f32_dpp v44, v44, v44 row_mirror row_mask:0xf bank_mask:0xf bound_ctrl:1
	v_add_f32_dpp v45, v45, v45 row_mirror row_mask:0xf bank_mask:0xf bound_ctrl:1
	v_pk_fma_f32 v[36:37], v[68:69], v[44:45], v[36:37] op_sel_hi:[1,0,1]
	v_pk_fma_f32 v[38:39], v[70:71], v[44:45], v[38:39] op_sel_hi:[1,0,1]
	v_fmac_f32_e32 v45, v44, v74
	v_fmac_f32_e32 v45, v72, v75
	v_cndmask_b32_e64 v46, v46, v45, s[10:11]
	s_lshl_b64 s[10:11], s[10:11], 1
	s_waitcnt lgkmcnt(7)
	ds_read_b128 v[52:55], v47 offset:18624
	ds_read_b128 v[56:59], v47 offset:18880
	ds_read_b128 v[60:63], v47 offset:19136
	ds_read_b128 v[64:67], v47 offset:19392
	ds_read_b32 v72, v48 offset:18624
	ds_read_b128 v[68:71], v47 offset:19648
	ds_read_b64 v[74:75], v49 offset:20160
	v_pk_mul_f32 v[40:41], v[36:37], v[76:77]
	v_pk_mul_f32 v[42:43], v[36:37], v[80:81]
	v_pk_fma_f32 v[40:41], v[38:39], v[78:79], v[40:41]
	v_pk_fma_f32 v[42:43], v[38:39], v[82:83], v[42:43]
	v_add_f32_e32 v44, v40, v41
	v_add_f32_e32 v45, v42, v43
	v_pk_mul_f32 v[36:37], v[36:37], v[84:85]
	v_add_f32_dpp v44, v44, v44 quad_perm:[1,0,3,2] row_mask:0xf bank_mask:0xf bound_ctrl:1
	v_add_f32_dpp v45, v45, v45 quad_perm:[1,0,3,2] row_mask:0xf bank_mask:0xf bound_ctrl:1
	v_pk_mul_f32 v[38:39], v[38:39], v[86:87]
	v_add_f32_dpp v44, v44, v44 quad_perm:[2,3,0,1] row_mask:0xf bank_mask:0xf bound_ctrl:1
	v_add_f32_dpp v45, v45, v45 quad_perm:[2,3,0,1] row_mask:0xf bank_mask:0xf bound_ctrl:1
	v_pk_fma_f32 v[36:37], v[88:89], v[96:97], v[36:37] op_sel_hi:[1,0,1]
	v_add_f32_dpp v44, v44, v44 row_half_mirror row_mask:0xf bank_mask:0xf bound_ctrl:1
	v_add_f32_dpp v45, v45, v45 row_half_mirror row_mask:0xf bank_mask:0xf bound_ctrl:1
	v_pk_fma_f32 v[38:39], v[90:91], v[96:97], v[38:39] op_sel_hi:[1,0,1]
	v_add_f32_dpp v44, v44, v44 row_mirror row_mask:0xf bank_mask:0xf bound_ctrl:1
	v_add_f32_dpp v45, v45, v45 row_mirror row_mask:0xf bank_mask:0xf bound_ctrl:1
	v_pk_fma_f32 v[36:37], v[92:93], v[44:45], v[36:37] op_sel_hi:[1,0,1]
	v_pk_fma_f32 v[38:39], v[94:95], v[44:45], v[38:39] op_sel_hi:[1,0,1]
	v_fmac_f32_e32 v45, v44, v98
	v_fmac_f32_e32 v45, v96, v99
	v_cndmask_b32_e64 v46, v46, v45, s[10:11]
	s_lshl_b64 s[10:11], s[10:11], 1
	s_waitcnt lgkmcnt(7)
; __device__ __forceinline__ f32x2 pkmul_(f32x2 a, f32x2 b) { f32x2 d; asm("v_pk_mul_f32 %0, %1, %2" : "=v"(d) : "v"(a), "v"(b)); return d; }
; __device__ __forceinline__ f32x2 pkfma_(f32x2 a, f32x2 b, f32x2 c) { f32x2 d; asm("v_pk_fma_f32 %0, %1, %2, %3" : "=v"(d) : "v"(a), "v"(b), "v"(c)); return d; }
; __device__ __forceinline__ f32x2 pkfma_b(f32x2 a, f32x2 s, f32x2 c) { f32x2 d; asm("v_pk_fma_f32 %0, %1, %2, %3 op_sel_hi:[1,0,1]" : "=v"(d) : "v"(a), "v"(s), "v"(c)); return d; }
; __device__ __forceinline__ f32x2 lo2(f32x4 v) { return __builtin_shufflevector(v, v, 0, 1); }
; __device__ __forceinline__ f32x2 hi2(f32x4 v) { return __builtin_shufflevector(v, v, 2, 3); }
; __global__ void __launch_bounds__(NTHR) hymba_fwd(Params P) {
;     ...
;                     for (int st = 0; st < TB; ++st) {
;                         if (st + 2 < TB) LDSTEP((st + 2) * REC, nav0, nav1, nbv0, nbv1, ndw0, ndw1, nkt0, nkt1, nwr0, nwr1, nvv, nsc);
;                         __builtin_amdgcn_sched_barrier(0);
;                         const f32x2 pa = pkfma_(S2[3], hi2(a1), pkfma_(S2[2], lo2(a1), pkfma_(S2[1], hi2(a0), pkmul_(S2[0], lo2(a0)))));
;                         const f32x2 py = pkfma_(S2[3], hi2(w1_), pkfma_(S2[2], lo2(w1_), pkfma_(S2[1], hi2(w0_), pkmul_(S2[0], lo2(w0_)))));
;                         float da = pa[0] + pa[1], dy = py[0] + py[1];
;                         da = red8(da); dy = red8(dy);
;                         const float y = dy + da * sc_[0] + vv_ * sc_[1];
;                         { f32x2 dab, vvb; dab[0] = da; dab[1] = da; vvb[0] = vv_; vvb[1] = vv_;
;                           S2[0] = pkfma_b(lo2(k0), vvb, pkfma_b(lo2(b0), dab, pkmul_(S2[0], lo2(d0)))); S2[1] = pkfma_b(hi2(k0), vvb, pkfma_b(hi2(b0), dab, pkmul_(S2[1], hi2(d0))));
;                           S2[2] = pkfma_b(lo2(k1), vvb, pkfma_b(lo2(b1), dab, pkmul_(S2[2], lo2(d1)))); S2[3] = pkfma_b(hi2(k1), vvb, pkfma_b(hi2(b1), dab, pkmul_(S2[3], hi2(d1)))); }
;                         const float sh = __int_as_float(__builtin_amdgcn_update_dpp(__float_as_int(y), __float_as_int(yacc), 0x111, 0xF, 0xF, false));
;                         yacc = first8 ? y : sh;
;                         if ((st & 7) == 7) yp[(size_t)(blk * TB + (st - 7)) * CW] = yacc;
;                         a0 = av0; a1 = av1; b0 = bv0; b1 = bv1; d0 = dw0; d1 = dw1; k0 = kt0; k1 = kt1; w0_ = wr0; w1_ = wr1; vv_ = vv; sc_ = sc;
	ds_read_b128 v[76:79], v47 offset:20176
	ds_read_b128 v[80:83], v47 offset:20432
	ds_read_b128 v[84:87], v47 offset:20688
	ds_read_b128 v[88:91], v47 offset:20944
	ds_read_b32 v96, v48 offset:20176
	ds_read_b128 v[92:95], v47 offset:21200
	ds_read_b64 v[98:99], v49 offset:21712
	v_pk_mul_f32 v[40:41], v[36:37], v[100:101]
	v_pk_mul_f32 v[42:43], v[36:37], v[104:105]
	v_pk_fma_f32 v[40:41], v[38:39], v[102:103], v[40:41]
	v_pk_fma_f32 v[42:43], v[38:39], v[106:107], v[42:43]
	v_add_f32_e32 v44, v40, v41
	v_add_f32_e32 v45, v42, v43
	v_pk_mul_f32 v[36:37], v[36:37], v[108:109]
	v_add_f32_dpp v44, v44, v44 quad_perm:[1,0,3,2] row_mask:0xf bank_mask:0xf bound_ctrl:1
	v_add_f32_dpp v45, v45, v45 quad_perm:[1,0,3,2] row_mask:0xf bank_mask:0xf bound_ctrl:1
	v_pk_mul_f32 v[38:39], v[38:39], v[110:111]
	v_add_f32_dpp v44, v44, v44 quad_perm:[2,3,0,1] row_mask:0xf bank_mask:0xf bound_ctrl:1
	v_add_f32_dpp v45, v45, v45 quad_perm:[2,3,0,1] row_mask:0xf bank_mask:0xf bound_ctrl:1
	v_pk_fma_f32 v[36:37], v[112:113], v[120:121], v[36:37] op_sel_hi:[1,0,1]
	v_add_f32_dpp v44, v44, v44 row_half_mirror row_mask:0xf bank_mask:0xf bound_ctrl:1
	v_add_f32_dpp v45, v45, v45 row_half_mirror row_mask:0xf bank_mask:0xf bound_ctrl:1
	v_pk_fma_f32 v[38:39], v[114:115], v[120:121], v[38:39] op_sel_hi:[1,0,1]
	v_add_f32_dpp v44, v44, v44 row_mirror row_mask:0xf bank_mask:0xf bound_ctrl:1
	v_add_f32_dpp v45, v45, v45 row_mirror row_mask:0xf bank_mask:0xf bound_ctrl:1
	v_pk_fma_f32 v[36:37], v[116:117], v[44:45], v[36:37] op_sel_hi:[1,0,1]
	v_pk_fma_f32 v[38:39], v[118:119], v[44:45], v[38:39] op_sel_hi:[1,0,1]
	v_fmac_f32_e32 v45, v44, v122
	v_fmac_f32_e32 v45, v120, v123
	v_cndmask_b32_e64 v46, v46, v45, s[10:11]
	s_lshl_b64 s[10:11], s[10:11], 1
	s_waitcnt lgkmcnt(7)
	ds_read_b128 v[100:103], v47 offset:21728
	ds_read_b128 v[104:107], v47 offset:21984
	ds_read_b128 v[108:111], v47 offset:22240
	ds_read_b128 v[112:115], v47 offset:22496
	ds_read_b32 v120, v48 offset:21728
	ds_read_b128 v[116:119], v47 offset:22752
	ds_read_b64 v[122:123], v49 offset:23264
	v_pk_mul_f32 v[40:41], v[36:37], v[52:53]
	v_pk_mul_f32 v[42:43], v[36:37], v[56:57]
	v_pk_fma_f32 v[40:41], v[38:39], v[54:55], v[40:41]
	v_pk_fma_f32 v[42:43], v[38:39], v[58:59], v[42:43]
	v_add_f32_e32 v44, v40, v41
	v_add_f32_e32 v45, v42, v43
	v_pk_mul_f32 v[36:37], v[36:37], v[60:61]
	v_add_f32_dpp v44, v44, v44 quad_perm:[1,0,3,2] row_mask:0xf bank_mask:0xf bound_ctrl:1
	v_add_f32_dpp v45, v45, v45 quad_perm:[1,0,3,2] row_mask:0xf bank_mask:0xf bound_ctrl:1
	v_pk_mul_f32 v[38:39], v[38:39], v[62:63]
	v_add_f32_dpp v44, v44, v44 quad_perm:[2,3,0,1] row_mask:0xf bank_mask:0xf bound_ctrl:1
	v_add_f32_dpp v45, v45, v45 quad_perm:[2,3,0,1] row_mask:0xf bank_mask:0xf bound_ctrl:1
	v_pk_fma_f32 v[36:37], v[64:65], v[72:73], v[36:37] op_sel_hi:[1,0,1]
	v_add_f32_dpp v44, v44, v44 row_half_mirror row_mask:0xf bank_mask:0xf bound_ctrl:1
	v_add_f32_dpp v45, v45, v45 row_half_mirror row_mask:0xf bank_mask:0xf bound_ctrl:1
	v_pk_fma_f32 v[38:39], v[66:67], v[72:73], v[38:39] op_sel_hi:[1,0,1]
	v_add_f32_dpp v44, v44, v44 row_mirror row_mask:0xf bank_mask:0xf bound_ctrl:1
	v_add_f32_dpp v45, v45, v45 row_mirror row_mask:0xf bank_mask:0xf bound_ctrl:1
	v_pk_fma_f32 v[36:37], v[68:69], v[44:45], v[36:37] op_sel_hi:[1,0,1]
	v_pk_fma_f32 v[38:39], v[70:71], v[44:45], v[38:39] op_sel_hi:[1,0,1]
	v_fmac_f32_e32 v45, v44, v74
	v_fmac_f32_e32 v45, v72, v75
	v_cndmask_b32_e64 v46, v46, v45, s[10:11]
	s_lshl_b64 s[10:11], s[10:11], 1
	s_waitcnt lgkmcnt(7)
	ds_read_b128 v[52:55], v47 offset:23280
	ds_read_b128 v[56:59], v47 offset:23536
	ds_read_b128 v[60:63], v47 offset:23792
	ds_read_b128 v[64:67], v47 offset:24048
	ds_read_b32 v72, v48 offset:23280
	ds_read_b128 v[68:71], v47 offset:24304
	ds_read_b64 v[74:75], v49 offset:24816
	v_pk_mul_f32 v[40:41], v[36:37], v[76:77]
	v_pk_mul_f32 v[42:43], v[36:37], v[80:81]
	v_pk_fma_f32 v[40:41], v[38:39], v[78:79], v[40:41]
	v_pk_fma_f32 v[42:43], v[38:39], v[82:83], v[42:43]
	v_add_f32_e32 v44, v40, v41
	v_add_f32_e32 v45, v42, v43
	v_pk_mul_f32 v[36:37], v[36:37], v[84:85]
	v_add_f32_dpp v44, v44, v44 quad_perm:[1,0,3,2] row_mask:0xf bank_mask:0xf bound_ctrl:1
	v_add_f32_dpp v45, v45, v45 quad_perm:[1,0,3,2] row_mask:0xf bank_mask:0xf bound_ctrl:1
	v_pk_mul_f32 v[38:39], v[38:39], v[86:87]
	v_add_f32_dpp v44, v44, v44 quad_perm:[2,3,0,1] row_mask:0xf bank_mask:0xf bound_ctrl:1
	v_add_f32_dpp v45, v45, v45 quad_perm:[2,3,0,1] row_mask:0xf bank_mask:0xf bound_ctrl:1
	v_pk_fma_f32 v[36:37], v[88:89], v[96:97], v[36:37] op_sel_hi:[1,0,1]
	v_add_f32_dpp v44, v44, v44 row_half_mirror row_mask:0xf bank_mask:0xf bound_ctrl:1
	v_add_f32_dpp v45, v45, v45 row_half_mirror row_mask:0xf bank_mask:0xf bound_ctrl:1
	v_pk_fma_f32 v[38:39], v[90:91], v[96:97], v[38:39] op_sel_hi:[1,0,1]
	v_add_f32_dpp v44, v44, v44 row_mirror row_mask:0xf bank_mask:0xf bound_ctrl:1
	v_add_f32_dpp v45, v45, v45 row_mirror row_mask:0xf bank_mask:0xf bound_ctrl:1
	v_pk_fma_f32 v[36:37], v[92:93], v[44:45], v[36:37] op_sel_hi:[1,0,1]
	v_pk_fma_f32 v[38:39], v[94:95], v[44:45], v[38:39] op_sel_hi:[1,0,1]
	v_fmac_f32_e32 v45, v44, v98
	v_fmac_f32_e32 v45, v96, v99
	v_cndmask_b32_e64 v46, v46, v45, s[10:11]
	s_lshl_b64 s[10:11], s[10:11], 1
	s_waitcnt lgkmcnt(7)
; __device__ __forceinline__ f32x2 pkmul_(f32x2 a, f32x2 b) { f32x2 d; asm("v_pk_mul_f32 %0, %1, %2" : "=v"(d) : "v"(a), "v"(b)); return d; }
; __device__ __forceinline__ f32x2 pkfma_(f32x2 a, f32x2 b, f32x2 c) { f32x2 d; asm("v_pk_fma_f32 %0, %1, %2, %3" : "=v"(d) : "v"(a), "v"(b), "v"(c)); return d; }
; __device__ __forceinline__ f32x2 pkfma_b(f32x2 a, f32x2 s, f32x2 c) { f32x2 d; asm("v_pk_fma_f32 %0, %1, %2, %3 op_sel_hi:[1,0,1]" : "=v"(d) : "v"(a), "v"(s), "v"(c)); return d; }
; __global__ void __launch_bounds__(NTHR) hymba_fwd(Params P) {
;     ...
;                     for (int st = 0; st < TB; ++st) {
;                         if (st + 2 < TB) LDSTEP((st + 2) * REC, nav0, nav1, nbv0, nbv1, ndw0, ndw1, nkt0, nkt1, nwr0, nwr1, nvv, nsc);
;                         __builtin_amdgcn_sched_barrier(0);
;                         const f32x2 pa = pkfma_(S2[3], hi2(a1), pkfma_(S2[2], lo2(a1), pkfma_(S2[1], hi2(a0), pkmul_(S2[0], lo2(a0)))));
;                         const f32x2 py = pkfma_(S2[3], hi2(w1_), pkfma_(S2[2], lo2(w1_), pkfma_(S2[1], hi2(w0_), pkmul_(S2[0], lo2(w0_)))));
;                         float da = pa[0] + pa[1], dy = py[0] + py[1];
;                         da = red8(da); dy = red8(dy);
;                         const float y = dy + da * sc_[0] + vv_ * sc_[1];
;                         { f32x2 dab, vvb; dab[0] = da; dab[1] = da; vvb[0] = vv_; vvb[1] = vv_;
;                           S2[0] = pkfma_b(lo2(k0), vvb, pkfma_b(lo2(b0), dab, pkmul_(S2[0], lo2(d0)))); S2[1] = pkfma_b(hi2(k0), vvb, pkfma_b(hi2(b0), dab, pkmul_(S2[1], hi2(d0))));
;                           S2[2] = pkfma_b(lo2(k1), vvb, pkfma_b(lo2(b1), dab, pkmul_(S2[2], lo2(d1)))); S2[3] = pkfma_b(hi2(k1), vvb, pkfma_b(hi2(b1), dab, pkmul_(S2[3], hi2(d1)))); }
;                         const float sh = __int_as_float(__builtin_amdgcn_update_dpp(__float_as_int(y), __float_as_int(yacc), 0x111, 0xF, 0xF, false));
;                         yacc = first8 ? y : sh;
;                         if ((st & 7) == 7) yp[(size_t)(blk * TB + (st - 7)) * CW] = yacc;
;                         a0 = av0; a1 = av1; b0 = bv0; b1 = bv1; d0 = dw0; d1 = dw1; k0 = kt0; k1 = kt1; w0_ = wr0; w1_ = wr1; vv_ = vv; sc_ = sc;
;                         av0 = nav0; av1 = nav1; bv0 = nbv0; bv1 = nbv1; dw0 = ndw0; dw1 = ndw1; kt0 = nkt0; kt1 = nkt1; wr0 = nwr0; wr1 = nwr1; vv = nvv; sc = nsc;
	ds_read_b128 v[76:79], v47 offset:24832
	ds_read_b128 v[80:83], v47 offset:25088
	ds_read_b128 v[84:87], v47 offset:25344
	ds_read_b128 v[88:91], v47 offset:25600
	ds_read_b32 v96, v48 offset:24832
	ds_read_b128 v[92:95], v47 offset:25856
	ds_read_b64 v[98:99], v49 offset:26368
	v_pk_mul_f32 v[40:41], v[36:37], v[100:101]
	v_pk_mul_f32 v[42:43], v[36:37], v[104:105]
	v_pk_fma_f32 v[40:41], v[38:39], v[102:103], v[40:41]
	v_pk_fma_f32 v[42:43], v[38:39], v[106:107], v[42:43]
	v_add_f32_e32 v44, v40, v41
	v_add_f32_e32 v45, v42, v43
	v_pk_mul_f32 v[36:37], v[36:37], v[108:109]
	v_add_f32_dpp v44, v44, v44 quad_perm:[1,0,3,2] row_mask:0xf bank_mask:0xf bound_ctrl:1
	v_add_f32_dpp v45, v45, v45 quad_perm:[1,0,3,2] row_mask:0xf bank_mask:0xf bound_ctrl:1
	v_pk_mul_f32 v[38:39], v[38:39], v[110:111]
	v_add_f32_dpp v44, v44, v44 quad_perm:[2,3,0,1] row_mask:0xf bank_mask:0xf bound_ctrl:1
	v_add_f32_dpp v45, v45, v45 quad_perm:[2,3,0,1] row_mask:0xf bank_mask:0xf bound_ctrl:1
	v_pk_fma_f32 v[36:37], v[112:113], v[120:121], v[36:37] op_sel_hi:[1,0,1]
	v_add_f32_dpp v44, v44, v44 row_half_mirror row_mask:0xf bank_mask:0xf bound_ctrl:1
	v_add_f32_dpp v45, v45, v45 row_half_mirror row_mask:0xf bank_mask:0xf bound_ctrl:1
	v_pk_fma_f32 v[38:39], v[114:115], v[120:121], v[38:39] op_sel_hi:[1,0,1]
	v_add_f32_dpp v44, v44, v44 row_mirror row_mask:0xf bank_mask:0xf bound_ctrl:1
	v_add_f32_dpp v45, v45, v45 row_mirror row_mask:0xf bank_mask:0xf bound_ctrl:1
	v_pk_fma_f32 v[36:37], v[116:117], v[44:45], v[36:37] op_sel_hi:[1,0,1]
	v_pk_fma_f32 v[38:39], v[118:119], v[44:45], v[38:39] op_sel_hi:[1,0,1]
	v_fmac_f32_e32 v45, v44, v122
	v_fmac_f32_e32 v45, v120, v123
	v_cndmask_b32_e64 v46, v46, v45, s[10:11]
	s_lshl_b64 s[10:11], s[10:11], 1
	s_waitcnt lgkmcnt(7)
	ds_read_b128 v[100:103], v47 offset:26384
	ds_read_b128 v[104:107], v47 offset:26640
	ds_read_b128 v[108:111], v47 offset:26896
	ds_read_b128 v[112:115], v47 offset:27152
	ds_read_b32 v120, v48 offset:26384
	ds_read_b128 v[116:119], v47 offset:27408
	ds_read_b64 v[122:123], v49 offset:27920
	v_pk_mul_f32 v[40:41], v[36:37], v[52:53]
	v_pk_mul_f32 v[42:43], v[36:37], v[56:57]
	v_pk_fma_f32 v[40:41], v[38:39], v[54:55], v[40:41]
	v_pk_fma_f32 v[42:43], v[38:39], v[58:59], v[42:43]
	v_add_f32_e32 v44, v40, v41
	v_add_f32_e32 v45, v42, v43
	v_pk_mul_f32 v[36:37], v[36:37], v[60:61]
	v_add_f32_dpp v44, v44, v44 quad_perm:[1,0,3,2] row_mask:0xf bank_mask:0xf bound_ctrl:1
	v_add_f32_dpp v45, v45, v45 quad_perm:[1,0,3,2] row_mask:0xf bank_mask:0xf bound_ctrl:1
	v_pk_mul_f32 v[38:39], v[38:39], v[62:63]
	v_add_f32_dpp v44, v44, v44 quad_perm:[2,3,0,1] row_mask:0xf bank_mask:0xf bound_ctrl:1
	v_add_f32_dpp v45, v45, v45 quad_perm:[2,3,0,1] row_mask:0xf bank_mask:0xf bound_ctrl:1
	v_pk_fma_f32 v[36:37], v[64:65], v[72:73], v[36:37] op_sel_hi:[1,0,1]
	v_add_f32_dpp v44, v44, v44 row_half_mirror row_mask:0xf bank_mask:0xf bound_ctrl:1
	v_add_f32_dpp v45, v45, v45 row_half_mirror row_mask:0xf bank_mask:0xf bound_ctrl:1
	v_pk_fma_f32 v[38:39], v[66:67], v[72:73], v[38:39] op_sel_hi:[1,0,1]
	v_add_f32_dpp v44, v44, v44 row_mirror row_mask:0xf bank_mask:0xf bound_ctrl:1
	v_add_f32_dpp v45, v45, v45 row_mirror row_mask:0xf bank_mask:0xf bound_ctrl:1
	v_pk_fma_f32 v[36:37], v[68:69], v[44:45], v[36:37] op_sel_hi:[1,0,1]
	v_pk_fma_f32 v[38:39], v[70:71], v[44:45], v[38:39] op_sel_hi:[1,0,1]
	v_fmac_f32_e32 v45, v44, v74
	v_fmac_f32_e32 v45, v72, v75
	v_cndmask_b32_e64 v46, v46, v45, s[10:11]
	s_lshl_b64 s[10:11], s[10:11], 1
	global_store_dword v50, v46, s[8:9]
	s_add_u32 s8, s8, 0x10000
	s_addc_u32 s9, s9, 0
	s_mov_b32 s10, 0x10001
	s_mov_b32 s11, 0x10001
	s_waitcnt lgkmcnt(7)
	ds_read_b128 v[52:55], v47 offset:27936
	ds_read_b128 v[56:59], v47 offset:28192
	ds_read_b128 v[60:63], v47 offset:28448
	ds_read_b128 v[64:67], v47 offset:28704
	ds_read_b32 v72, v48 offset:27936
	ds_read_b128 v[68:71], v47 offset:28960
	ds_read_b64 v[74:75], v49 offset:29472
	v_pk_mul_f32 v[40:41], v[36:37], v[76:77]
	v_pk_mul_f32 v[42:43], v[36:37], v[80:81]
	v_pk_fma_f32 v[40:41], v[38:39], v[78:79], v[40:41]
	v_pk_fma_f32 v[42:43], v[38:39], v[82:83], v[42:43]
	v_add_f32_e32 v44, v40, v41
	v_add_f32_e32 v45, v42, v43
	v_pk_mul_f32 v[36:37], v[36:37], v[84:85]
	v_add_f32_dpp v44, v44, v44 quad_perm:[1,0,3,2] row_mask:0xf bank_mask:0xf bound_ctrl:1
	v_add_f32_dpp v45, v45, v45 quad_perm:[1,0,3,2] row_mask:0xf bank_mask:0xf bound_ctrl:1
	v_pk_mul_f32 v[38:39], v[38:39], v[86:87]
	v_add_f32_dpp v44, v44, v44 quad_perm:[2,3,0,1] row_mask:0xf bank_mask:0xf bound_ctrl:1
	v_add_f32_dpp v45, v45, v45 quad_perm:[2,3,0,1] row_mask:0xf bank_mask:0xf bound_ctrl:1
	v_pk_fma_f32 v[36:37], v[88:89], v[96:97], v[36:37] op_sel_hi:[1,0,1]
	v_add_f32_dpp v44, v44, v44 row_half_mirror row_mask:0xf bank_mask:0xf bound_ctrl:1
	v_add_f32_dpp v45, v45, v45 row_half_mirror row_mask:0xf bank_mask:0xf bound_ctrl:1
	v_pk_fma_f32 v[38:39], v[90:91], v[96:97], v[38:39] op_sel_hi:[1,0,1]
	v_add_f32_dpp v44, v44, v44 row_mirror row_mask:0xf bank_mask:0xf bound_ctrl:1
	v_add_f32_dpp v45, v45, v45 row_mirror row_mask:0xf bank_mask:0xf bound_ctrl:1
	v_pk_fma_f32 v[36:37], v[92:93], v[44:45], v[36:37] op_sel_hi:[1,0,1]
	v_pk_fma_f32 v[38:39], v[94:95], v[44:45], v[38:39] op_sel_hi:[1,0,1]
	v_fmac_f32_e32 v45, v44, v98
	v_fmac_f32_e32 v45, v96, v99
	v_cndmask_b32_e64 v46, v46, v45, s[10:11]
	s_lshl_b64 s[10:11], s[10:11], 1
	s_waitcnt lgkmcnt(7)
; __device__ __forceinline__ f32x2 pkmul_(f32x2 a, f32x2 b) { f32x2 d; asm("v_pk_mul_f32 %0, %1, %2" : "=v"(d) : "v"(a), "v"(b)); return d; }
; __device__ __forceinline__ f32x2 pkfma_(f32x2 a, f32x2 b, f32x2 c) { f32x2 d; asm("v_pk_fma_f32 %0, %1, %2, %3" : "=v"(d) : "v"(a), "v"(b), "v"(c)); return d; }
; __device__ __forceinline__ f32x2 pkfma_b(f32x2 a, f32x2 s, f32x2 c) { f32x2 d; asm("v_pk_fma_f32 %0, %1, %2, %3 op_sel_hi:[1,0,1]" : "=v"(d) : "v"(a), "v"(s), "v"(c)); return d; }
; __device__ __forceinline__ f32x2 lo2(f32x4 v) { return __builtin_shufflevector(v, v, 0, 1); }
; __device__ __forceinline__ f32x2 hi2(f32x4 v) { return __builtin_shufflevector(v, v, 2, 3); }
; __global__ void __launch_bounds__(NTHR) hymba_fwd(Params P) {
;     ...
;                     for (int st = 0; st < TB; ++st) {
;                         if (st + 2 < TB) LDSTEP((st + 2) * REC, nav0, nav1, nbv0, nbv1, ndw0, ndw1, nkt0, nkt1, nwr0, nwr1, nvv, nsc);
;                         __builtin_amdgcn_sched_barrier(0);
;                         const f32x2 pa = pkfma_(S2[3], hi2(a1), pkfma_(S2[2], lo2(a1), pkfma_(S2[1], hi2(a0), pkmul_(S2[0], lo2(a0)))));
;                         const f32x2 py = pkfma_(S2[3], hi2(w1_), pkfma_(S2[2], lo2(w1_), pkfma_(S2[1], hi2(w0_), pkmul_(S2[0], lo2(w0_)))));
;                         float da = pa[0] + pa[1], dy = py[0] + py[1];
;                         da = red8(da); dy = red8(dy);
;                         const float y = dy + da * sc_[0] + vv_ * sc_[1];
;                         { f32x2 dab, vvb; dab[0] = da; dab[1] = da; vvb[0] = vv_; vvb[1] = vv_;
;                           S2[0] = pkfma_b(lo2(k0), vvb, pkfma_b(lo2(b0), dab, pkmul_(S2[0], lo2(d0)))); S2[1] = pkfma_b(hi2(k0), vvb, pkfma_b(hi2(b0), dab, pkmul_(S2[1], hi2(d0))));
;                           S2[2] = pkfma_b(lo2(k1), vvb, pkfma_b(lo2(b1), dab, pkmul_(S2[2], lo2(d1)))); S2[3] = pkfma_b(hi2(k1), vvb, pkfma_b(hi2(b1), dab, pkmul_(S2[3], hi2(d1)))); }
;                         const float sh = __int_as_float(__builtin_amdgcn_update_dpp(__float_as_int(y), __float_as_int(yacc), 0x111, 0xF, 0xF, false));
;                         yacc = first8 ? y : sh;
;                         if ((st & 7) == 7) yp[(size_t)(blk * TB + (st - 7)) * CW] = yacc;
;                         a0 = av0; a1 = av1; b0 = bv0; b1 = bv1; d0 = dw0; d1 = dw1; k0 = kt0; k1 = kt1; w0_ = wr0; w1_ = wr1; vv_ = vv; sc_ = sc;
	ds_read_b128 v[76:79], v47 offset:29488
	ds_read_b128 v[80:83], v47 offset:29744
	ds_read_b128 v[84:87], v47 offset:30000
	ds_read_b128 v[88:91], v47 offset:30256
	ds_read_b32 v96, v48 offset:29488
	ds_read_b128 v[92:95], v47 offset:30512
	ds_read_b64 v[98:99], v49 offset:31024
	v_pk_mul_f32 v[40:41], v[36:37], v[100:101]
	v_pk_mul_f32 v[42:43], v[36:37], v[104:105]
	v_pk_fma_f32 v[40:41], v[38:39], v[102:103], v[40:41]
	v_pk_fma_f32 v[42:43], v[38:39], v[106:107], v[42:43]
	v_add_f32_e32 v44, v40, v41
	v_add_f32_e32 v45, v42, v43
	v_pk_mul_f32 v[36:37], v[36:37], v[108:109]
	v_add_f32_dpp v44, v44, v44 quad_perm:[1,0,3,2] row_mask:0xf bank_mask:0xf bound_ctrl:1
	v_add_f32_dpp v45, v45, v45 quad_perm:[1,0,3,2] row_mask:0xf bank_mask:0xf bound_ctrl:1
	v_pk_mul_f32 v[38:39], v[38:39], v[110:111]
	v_add_f32_dpp v44, v44, v44 quad_perm:[2,3,0,1] row_mask:0xf bank_mask:0xf bound_ctrl:1
	v_add_f32_dpp v45, v45, v45 quad_perm:[2,3,0,1] row_mask:0xf bank_mask:0xf bound_ctrl:1
	v_pk_fma_f32 v[36:37], v[112:113], v[120:121], v[36:37] op_sel_hi:[1,0,1]
	v_add_f32_dpp v44, v44, v44 row_half_mirror row_mask:0xf bank_mask:0xf bound_ctrl:1
	v_add_f32_dpp v45, v45, v45 row_half_mirror row_mask:0xf bank_mask:0xf bound_ctrl:1
	v_pk_fma_f32 v[38:39], v[114:115], v[120:121], v[38:39] op_sel_hi:[1,0,1]
	v_add_f32_dpp v44, v44, v44 row_mirror row_mask:0xf bank_mask:0xf bound_ctrl:1
	v_add_f32_dpp v45, v45, v45 row_mirror row_mask:0xf bank_mask:0xf bound_ctrl:1
	v_pk_fma_f32 v[36:37], v[116:117], v[44:45], v[36:37] op_sel_hi:[1,0,1]
	v_pk_fma_f32 v[38:39], v[118:119], v[44:45], v[38:39] op_sel_hi:[1,0,1]
	v_fmac_f32_e32 v45, v44, v122
	v_fmac_f32_e32 v45, v120, v123
	v_cndmask_b32_e64 v46, v46, v45, s[10:11]
	s_lshl_b64 s[10:11], s[10:11], 1
	s_waitcnt lgkmcnt(7)
	ds_read_b128 v[100:103], v47 offset:31040
	ds_read_b128 v[104:107], v47 offset:31296
	ds_read_b128 v[108:111], v47 offset:31552
	ds_read_b128 v[112:115], v47 offset:31808
	ds_read_b32 v120, v48 offset:31040
	ds_read_b128 v[116:119], v47 offset:32064
	ds_read_b64 v[122:123], v49 offset:32576
	v_pk_mul_f32 v[40:41], v[36:37], v[52:53]
	v_pk_mul_f32 v[42:43], v[36:37], v[56:57]
	v_pk_fma_f32 v[40:41], v[38:39], v[54:55], v[40:41]
	v_pk_fma_f32 v[42:43], v[38:39], v[58:59], v[42:43]
	v_add_f32_e32 v44, v40, v41
	v_add_f32_e32 v45, v42, v43
	v_pk_mul_f32 v[36:37], v[36:37], v[60:61]
	v_add_f32_dpp v44, v44, v44 quad_perm:[1,0,3,2] row_mask:0xf bank_mask:0xf bound_ctrl:1
	v_add_f32_dpp v45, v45, v45 quad_perm:[1,0,3,2] row_mask:0xf bank_mask:0xf bound_ctrl:1
	v_pk_mul_f32 v[38:39], v[38:39], v[62:63]
	v_add_f32_dpp v44, v44, v44 quad_perm:[2,3,0,1] row_mask:0xf bank_mask:0xf bound_ctrl:1
	v_add_f32_dpp v45, v45, v45 quad_perm:[2,3,0,1] row_mask:0xf bank_mask:0xf bound_ctrl:1
	v_pk_fma_f32 v[36:37], v[64:65], v[72:73], v[36:37] op_sel_hi:[1,0,1]
	v_add_f32_dpp v44, v44, v44 row_half_mirror row_mask:0xf bank_mask:0xf bound_ctrl:1
	v_add_f32_dpp v45, v45, v45 row_half_mirror row_mask:0xf bank_mask:0xf bound_ctrl:1
	v_pk_fma_f32 v[38:39], v[66:67], v[72:73], v[38:39] op_sel_hi:[1,0,1]
	v_add_f32_dpp v44, v44, v44 row_mirror row_mask:0xf bank_mask:0xf bound_ctrl:1
	v_add_f32_dpp v45, v45, v45 row_mirror row_mask:0xf bank_mask:0xf bound_ctrl:1
	v_pk_fma_f32 v[36:37], v[68:69], v[44:45], v[36:37] op_sel_hi:[1,0,1]
	v_pk_fma_f32 v[38:39], v[70:71], v[44:45], v[38:39] op_sel_hi:[1,0,1]
	v_fmac_f32_e32 v45, v44, v74
	v_fmac_f32_e32 v45, v72, v75
	v_cndmask_b32_e64 v46, v46, v45, s[10:11]
	s_lshl_b64 s[10:11], s[10:11], 1
	s_waitcnt lgkmcnt(7)
	ds_read_b128 v[52:55], v47 offset:32592
	ds_read_b128 v[56:59], v47 offset:32848
	ds_read_b128 v[60:63], v47 offset:33104
	ds_read_b128 v[64:67], v47 offset:33360
	ds_read_b32 v72, v48 offset:32592
	ds_read_b128 v[68:71], v47 offset:33616
	ds_read_b64 v[74:75], v49 offset:34128
	v_pk_mul_f32 v[40:41], v[36:37], v[76:77]
	v_pk_mul_f32 v[42:43], v[36:37], v[80:81]
	v_pk_fma_f32 v[40:41], v[38:39], v[78:79], v[40:41]
	v_pk_fma_f32 v[42:43], v[38:39], v[82:83], v[42:43]
	v_add_f32_e32 v44, v40, v41
	v_add_f32_e32 v45, v42, v43
	v_pk_mul_f32 v[36:37], v[36:37], v[84:85]
	v_add_f32_dpp v44, v44, v44 quad_perm:[1,0,3,2] row_mask:0xf bank_mask:0xf bound_ctrl:1
	v_add_f32_dpp v45, v45, v45 quad_perm:[1,0,3,2] row_mask:0xf bank_mask:0xf bound_ctrl:1
	v_pk_mul_f32 v[38:39], v[38:39], v[86:87]
	v_add_f32_dpp v44, v44, v44 quad_perm:[2,3,0,1] row_mask:0xf bank_mask:0xf bound_ctrl:1
	v_add_f32_dpp v45, v45, v45 quad_perm:[2,3,0,1] row_mask:0xf bank_mask:0xf bound_ctrl:1
	v_pk_fma_f32 v[36:37], v[88:89], v[96:97], v[36:37] op_sel_hi:[1,0,1]
	v_add_f32_dpp v44, v44, v44 row_half_mirror row_mask:0xf bank_mask:0xf bound_ctrl:1
	v_add_f32_dpp v45, v45, v45 row_half_mirror row_mask:0xf bank_mask:0xf bound_ctrl:1
	v_pk_fma_f32 v[38:39], v[90:91], v[96:97], v[38:39] op_sel_hi:[1,0,1]
	v_add_f32_dpp v44, v44, v44 row_mirror row_mask:0xf bank_mask:0xf bound_ctrl:1
	v_add_f32_dpp v45, v45, v45 row_mirror row_mask:0xf bank_mask:0xf bound_ctrl:1
	v_pk_fma_f32 v[36:37], v[92:93], v[44:45], v[36:37] op_sel_hi:[1,0,1]
	v_pk_fma_f32 v[38:39], v[94:95], v[44:45], v[38:39] op_sel_hi:[1,0,1]
	v_fmac_f32_e32 v45, v44, v98
	v_fmac_f32_e32 v45, v96, v99
	v_cndmask_b32_e64 v46, v46, v45, s[10:11]
	s_lshl_b64 s[10:11], s[10:11], 1
	s_waitcnt lgkmcnt(7)
; __device__ __forceinline__ f32x2 pkmul_(f32x2 a, f32x2 b) { f32x2 d; asm("v_pk_mul_f32 %0, %1, %2" : "=v"(d) : "v"(a), "v"(b)); return d; }
; __device__ __forceinline__ f32x2 pkfma_(f32x2 a, f32x2 b, f32x2 c) { f32x2 d; asm("v_pk_fma_f32 %0, %1, %2, %3" : "=v"(d) : "v"(a), "v"(b), "v"(c)); return d; }
; __device__ __forceinline__ f32x2 pkfma_b(f32x2 a, f32x2 s, f32x2 c) { f32x2 d; asm("v_pk_fma_f32 %0, %1, %2, %3 op_sel_hi:[1,0,1]" : "=v"(d) : "v"(a), "v"(s), "v"(c)); return d; }
; __device__ __forceinline__ f32x2 lo2(f32x4 v) { return __builtin_shufflevector(v, v, 0, 1); }
; __device__ __forceinline__ f32x2 hi2(f32x4 v) { return __builtin_shufflevector(v, v, 2, 3); }
; __global__ void __launch_bounds__(NTHR) hymba_fwd(Params P) {
;     ...
;                     for (int st = 0; st < TB; ++st) {
;                         if (st + 2 < TB) LDSTEP((st + 2) * REC, nav0, nav1, nbv0, nbv1, ndw0, ndw1, nkt0, nkt1, nwr0, nwr1, nvv, nsc);
;                         __builtin_amdgcn_sched_barrier(0);
;                         const f32x2 pa = pkfma_(S2[3], hi2(a1), pkfma_(S2[2], lo2(a1), pkfma_(S2[1], hi2(a0), pkmul_(S2[0], lo2(a0)))));
;                         const f32x2 py = pkfma_(S2[3], hi2(w1_), pkfma_(S2[2], lo2(w1_), pkfma_(S2[1], hi2(w0_), pkmul_(S2[0], lo2(w0_)))));
;                         float da = pa[0] + pa[1], dy = py[0] + py[1];
;                         da = red8(da); dy = red8(dy);
;                         const float y = dy + da * sc_[0] + vv_ * sc_[1];
;                         { f32x2 dab, vvb; dab[0] = da; dab[1] = da; vvb[0] = vv_; vvb[1] = vv_;
;                           S2[0] = pkfma_b(lo2(k0), vvb, pkfma_b(lo2(b0), dab, pkmul_(S2[0], lo2(d0)))); S2[1] = pkfma_b(hi2(k0), vvb, pkfma_b(hi2(b0), dab, pkmul_(S2[1], hi2(d0))));
;                           S2[2] = pkfma_b(lo2(k1), vvb, pkfma_b(lo2(b1), dab, pkmul_(S2[2], lo2(d1)))); S2[3] = pkfma_b(hi2(k1), vvb, pkfma_b(hi2(b1), dab, pkmul_(S2[3], hi2(d1)))); }
;                         const float sh = __int_as_float(__builtin_amdgcn_update_dpp(__float_as_int(y), __float_as_int(yacc), 0x111, 0xF, 0xF, false));
;                         yacc = first8 ? y : sh;
;                         if ((st & 7) == 7) yp[(size_t)(blk * TB + (st - 7)) * CW] = yacc;
;                         a0 = av0; a1 = av1; b0 = bv0; b1 = bv1; d0 = dw0; d1 = dw1; k0 = kt0; k1 = kt1; w0_ = wr0; w1_ = wr1; vv_ = vv; sc_ = sc;
	ds_read_b128 v[76:79], v47 offset:34144
	ds_read_b128 v[80:83], v47 offset:34400
	ds_read_b128 v[84:87], v47 offset:34656
	ds_read_b128 v[88:91], v47 offset:34912
	ds_read_b32 v96, v48 offset:34144
	ds_read_b128 v[92:95], v47 offset:35168
	ds_read_b64 v[98:99], v49 offset:35680
	v_pk_mul_f32 v[40:41], v[36:37], v[100:101]
	v_pk_mul_f32 v[42:43], v[36:37], v[104:105]
	v_pk_fma_f32 v[40:41], v[38:39], v[102:103], v[40:41]
	v_pk_fma_f32 v[42:43], v[38:39], v[106:107], v[42:43]
	v_add_f32_e32 v44, v40, v41
	v_add_f32_e32 v45, v42, v43
	v_pk_mul_f32 v[36:37], v[36:37], v[108:109]
	v_add_f32_dpp v44, v44, v44 quad_perm:[1,0,3,2] row_mask:0xf bank_mask:0xf bound_ctrl:1
	v_add_f32_dpp v45, v45, v45 quad_perm:[1,0,3,2] row_mask:0xf bank_mask:0xf bound_ctrl:1
	v_pk_mul_f32 v[38:39], v[38:39], v[110:111]
	v_add_f32_dpp v44, v44, v44 quad_perm:[2,3,0,1] row_mask:0xf bank_mask:0xf bound_ctrl:1
	v_add_f32_dpp v45, v45, v45 quad_perm:[2,3,0,1] row_mask:0xf bank_mask:0xf bound_ctrl:1
	v_pk_fma_f32 v[36:37], v[112:113], v[120:121], v[36:37] op_sel_hi:[1,0,1]
	v_add_f32_dpp v44, v44, v44 row_half_mirror row_mask:0xf bank_mask:0xf bound_ctrl:1
	v_add_f32_dpp v45, v45, v45 row_half_mirror row_mask:0xf bank_mask:0xf bound_ctrl:1
	v_pk_fma_f32 v[38:39], v[114:115], v[120:121], v[38:39] op_sel_hi:[1,0,1]
	v_add_f32_dpp v44, v44, v44 row_mirror row_mask:0xf bank_mask:0xf bound_ctrl:1
	v_add_f32_dpp v45, v45, v45 row_mirror row_mask:0xf bank_mask:0xf bound_ctrl:1
	v_pk_fma_f32 v[36:37], v[116:117], v[44:45], v[36:37] op_sel_hi:[1,0,1]
	v_pk_fma_f32 v[38:39], v[118:119], v[44:45], v[38:39] op_sel_hi:[1,0,1]
	v_fmac_f32_e32 v45, v44, v122
	v_fmac_f32_e32 v45, v120, v123
	v_cndmask_b32_e64 v46, v46, v45, s[10:11]
	s_lshl_b64 s[10:11], s[10:11], 1
	s_waitcnt lgkmcnt(7)
	ds_read_b128 v[100:103], v47 offset:35696
	ds_read_b128 v[104:107], v47 offset:35952
	ds_read_b128 v[108:111], v47 offset:36208
	ds_read_b128 v[112:115], v47 offset:36464
	ds_read_b32 v120, v48 offset:35696
	ds_read_b128 v[116:119], v47 offset:36720
	ds_read_b64 v[122:123], v49 offset:37232
	v_pk_mul_f32 v[40:41], v[36:37], v[52:53]
	v_pk_mul_f32 v[42:43], v[36:37], v[56:57]
	v_pk_fma_f32 v[40:41], v[38:39], v[54:55], v[40:41]
	v_pk_fma_f32 v[42:43], v[38:39], v[58:59], v[42:43]
	v_add_f32_e32 v44, v40, v41
	v_add_f32_e32 v45, v42, v43
	v_pk_mul_f32 v[36:37], v[36:37], v[60:61]
	v_add_f32_dpp v44, v44, v44 quad_perm:[1,0,3,2] row_mask:0xf bank_mask:0xf bound_ctrl:1
	v_add_f32_dpp v45, v45, v45 quad_perm:[1,0,3,2] row_mask:0xf bank_mask:0xf bound_ctrl:1
	v_pk_mul_f32 v[38:39], v[38:39], v[62:63]
	v_add_f32_dpp v44, v44, v44 quad_perm:[2,3,0,1] row_mask:0xf bank_mask:0xf bound_ctrl:1
	v_add_f32_dpp v45, v45, v45 quad_perm:[2,3,0,1] row_mask:0xf bank_mask:0xf bound_ctrl:1
	v_pk_fma_f32 v[36:37], v[64:65], v[72:73], v[36:37] op_sel_hi:[1,0,1]
	v_add_f32_dpp v44, v44, v44 row_half_mirror row_mask:0xf bank_mask:0xf bound_ctrl:1
	v_add_f32_dpp v45, v45, v45 row_half_mirror row_mask:0xf bank_mask:0xf bound_ctrl:1
	v_pk_fma_f32 v[38:39], v[66:67], v[72:73], v[38:39] op_sel_hi:[1,0,1]
	v_add_f32_dpp v44, v44, v44 row_mirror row_mask:0xf bank_mask:0xf bound_ctrl:1
	v_add_f32_dpp v45, v45, v45 row_mirror row_mask:0xf bank_mask:0xf bound_ctrl:1
	v_pk_fma_f32 v[36:37], v[68:69], v[44:45], v[36:37] op_sel_hi:[1,0,1]
	v_pk_fma_f32 v[38:39], v[70:71], v[44:45], v[38:39] op_sel_hi:[1,0,1]
	v_fmac_f32_e32 v45, v44, v74
	v_fmac_f32_e32 v45, v72, v75
	v_cndmask_b32_e64 v46, v46, v45, s[10:11]
	s_lshl_b64 s[10:11], s[10:11], 1
	s_waitcnt lgkmcnt(7)
	ds_read_b128 v[52:55], v47 offset:37248
	ds_read_b128 v[56:59], v47 offset:37504
	ds_read_b128 v[60:63], v47 offset:37760
	ds_read_b128 v[64:67], v47 offset:38016
	ds_read_b32 v72, v48 offset:37248
	ds_read_b128 v[68:71], v47 offset:38272
	ds_read_b64 v[74:75], v49 offset:38784
	v_pk_mul_f32 v[40:41], v[36:37], v[76:77]
	v_pk_mul_f32 v[42:43], v[36:37], v[80:81]
	v_pk_fma_f32 v[40:41], v[38:39], v[78:79], v[40:41]
	v_pk_fma_f32 v[42:43], v[38:39], v[82:83], v[42:43]
	v_add_f32_e32 v44, v40, v41
	v_add_f32_e32 v45, v42, v43
	v_pk_mul_f32 v[36:37], v[36:37], v[84:85]
	v_add_f32_dpp v44, v44, v44 quad_perm:[1,0,3,2] row_mask:0xf bank_mask:0xf bound_ctrl:1
	v_add_f32_dpp v45, v45, v45 quad_perm:[1,0,3,2] row_mask:0xf bank_mask:0xf bound_ctrl:1
	v_pk_mul_f32 v[38:39], v[38:39], v[86:87]
	v_add_f32_dpp v44, v44, v44 quad_perm:[2,3,0,1] row_mask:0xf bank_mask:0xf bound_ctrl:1
	v_add_f32_dpp v45, v45, v45 quad_perm:[2,3,0,1] row_mask:0xf bank_mask:0xf bound_ctrl:1
	v_pk_fma_f32 v[36:37], v[88:89], v[96:97], v[36:37] op_sel_hi:[1,0,1]
	v_add_f32_dpp v44, v44, v44 row_half_mirror row_mask:0xf bank_mask:0xf bound_ctrl:1
	v_add_f32_dpp v45, v45, v45 row_half_mirror row_mask:0xf bank_mask:0xf bound_ctrl:1
	v_pk_fma_f32 v[38:39], v[90:91], v[96:97], v[38:39] op_sel_hi:[1,0,1]
	v_add_f32_dpp v44, v44, v44 row_mirror row_mask:0xf bank_mask:0xf bound_ctrl:1
	v_add_f32_dpp v45, v45, v45 row_mirror row_mask:0xf bank_mask:0xf bound_ctrl:1
	v_pk_fma_f32 v[36:37], v[92:93], v[44:45], v[36:37] op_sel_hi:[1,0,1]
	v_pk_fma_f32 v[38:39], v[94:95], v[44:45], v[38:39] op_sel_hi:[1,0,1]
	v_fmac_f32_e32 v45, v44, v98
	v_fmac_f32_e32 v45, v96, v99
	v_cndmask_b32_e64 v46, v46, v45, s[10:11]
	s_lshl_b64 s[10:11], s[10:11], 1
	s_waitcnt lgkmcnt(7)
; __device__ __forceinline__ f32x2 pkmul_(f32x2 a, f32x2 b) { f32x2 d; asm("v_pk_mul_f32 %0, %1, %2" : "=v"(d) : "v"(a), "v"(b)); return d; }
; __device__ __forceinline__ f32x2 pkfma_(f32x2 a, f32x2 b, f32x2 c) { f32x2 d; asm("v_pk_fma_f32 %0, %1, %2, %3" : "=v"(d) : "v"(a), "v"(b), "v"(c)); return d; }
; __device__ __forceinline__ f32x2 pkfma_b(f32x2 a, f32x2 s, f32x2 c) { f32x2 d; asm("v_pk_fma_f32 %0, %1, %2, %3 op_sel_hi:[1,0,1]" : "=v"(d) : "v"(a), "v"(s), "v"(c)); return d; }
; __device__ __forceinline__ f32x2 lo2(f32x4 v) { return __builtin_shufflevector(v, v, 0, 1); }
; __device__ __forceinline__ f32x2 hi2(f32x4 v) { return __builtin_shufflevector(v, v, 2, 3); }
; __global__ void __launch_bounds__(NTHR) hymba_fwd(Params P) {
;     ...
;                     for (int st = 0; st < TB; ++st) {
;                         if (st + 2 < TB) LDSTEP((st + 2) * REC, nav0, nav1, nbv0, nbv1, ndw0, ndw1, nkt0, nkt1, nwr0, nwr1, nvv, nsc);
;                         __builtin_amdgcn_sched_barrier(0);
;                         const f32x2 pa = pkfma_(S2[3], hi2(a1), pkfma_(S2[2], lo2(a1), pkfma_(S2[1], hi2(a0), pkmul_(S2[0], lo2(a0)))));
;                         const f32x2 py = pkfma_(S2[3], hi2(w1_), pkfma_(S2[2], lo2(w1_), pkfma_(S2[1], hi2(w0_), pkmul_(S2[0], lo2(w0_)))));
;                         float da = pa[0] + pa[1], dy = py[0] + py[1];
;                         da = red8(da); dy = red8(dy);
;                         const float y = dy + da * sc_[0] + vv_ * sc_[1];
;                         { f32x2 dab, vvb; dab[0] = da; dab[1] = da; vvb[0] = vv_; vvb[1] = vv_;
;                           S2[0] = pkfma_b(lo2(k0), vvb, pkfma_b(lo2(b0), dab, pkmul_(S2[0], lo2(d0)))); S2[1] = pkfma_b(hi2(k0), vvb, pkfma_b(hi2(b0), dab, pkmul_(S2[1], hi2(d0))));
;                           S2[2] = pkfma_b(lo2(k1), vvb, pkfma_b(lo2(b1), dab, pkmul_(S2[2], lo2(d1)))); S2[3] = pkfma_b(hi2(k1), vvb, pkfma_b(hi2(b1), dab, pkmul_(S2[3], hi2(d1)))); }
;                         const float sh = __int_as_float(__builtin_amdgcn_update_dpp(__float_as_int(y), __float_as_int(yacc), 0x111, 0xF, 0xF, false));
;                         yacc = first8 ? y : sh;
;                         if ((st & 7) == 7) yp[(size_t)(blk * TB + (st - 7)) * CW] = yacc;
;                         a0 = av0; a1 = av1; b0 = bv0; b1 = bv1; d0 = dw0; d1 = dw1; k0 = kt0; k1 = kt1; w0_ = wr0; w1_ = wr1; vv_ = vv; sc_ = sc;
	ds_read_b128 v[76:79], v47 offset:38800
	ds_read_b128 v[80:83], v47 offset:39056
	ds_read_b128 v[84:87], v47 offset:39312
	ds_read_b128 v[88:91], v47 offset:39568
	ds_read_b32 v96, v48 offset:38800
	ds_read_b128 v[92:95], v47 offset:39824
	ds_read_b64 v[98:99], v49 offset:40336
	v_pk_mul_f32 v[40:41], v[36:37], v[100:101]
	v_pk_mul_f32 v[42:43], v[36:37], v[104:105]
	v_pk_fma_f32 v[40:41], v[38:39], v[102:103], v[40:41]
	v_pk_fma_f32 v[42:43], v[38:39], v[106:107], v[42:43]
	v_add_f32_e32 v44, v40, v41
	v_add_f32_e32 v45, v42, v43
	v_pk_mul_f32 v[36:37], v[36:37], v[108:109]
	v_add_f32_dpp v44, v44, v44 quad_perm:[1,0,3,2] row_mask:0xf bank_mask:0xf bound_ctrl:1
	v_add_f32_dpp v45, v45, v45 quad_perm:[1,0,3,2] row_mask:0xf bank_mask:0xf bound_ctrl:1
	v_pk_mul_f32 v[38:39], v[38:39], v[110:111]
	v_add_f32_dpp v44, v44, v44 quad_perm:[2,3,0,1] row_mask:0xf bank_mask:0xf bound_ctrl:1
	v_add_f32_dpp v45, v45, v45 quad_perm:[2,3,0,1] row_mask:0xf bank_mask:0xf bound_ctrl:1
	v_pk_fma_f32 v[36:37], v[112:113], v[120:121], v[36:37] op_sel_hi:[1,0,1]
	v_add_f32_dpp v44, v44, v44 row_half_mirror row_mask:0xf bank_mask:0xf bound_ctrl:1
	v_add_f32_dpp v45, v45, v45 row_half_mirror row_mask:0xf bank_mask:0xf bound_ctrl:1
	v_pk_fma_f32 v[38:39], v[114:115], v[120:121], v[38:39] op_sel_hi:[1,0,1]
	v_add_f32_dpp v44, v44, v44 row_mirror row_mask:0xf bank_mask:0xf bound_ctrl:1
	v_add_f32_dpp v45, v45, v45 row_mirror row_mask:0xf bank_mask:0xf bound_ctrl:1
	v_pk_fma_f32 v[36:37], v[116:117], v[44:45], v[36:37] op_sel_hi:[1,0,1]
	v_pk_fma_f32 v[38:39], v[118:119], v[44:45], v[38:39] op_sel_hi:[1,0,1]
	v_fmac_f32_e32 v45, v44, v122
	v_fmac_f32_e32 v45, v120, v123
	v_cndmask_b32_e64 v46, v46, v45, s[10:11]
	s_lshl_b64 s[10:11], s[10:11], 1
	s_waitcnt lgkmcnt(7)
	ds_read_b128 v[100:103], v47 offset:40352
	ds_read_b128 v[104:107], v47 offset:40608
	ds_read_b128 v[108:111], v47 offset:40864
	ds_read_b128 v[112:115], v47 offset:41120
	ds_read_b32 v120, v48 offset:40352
	ds_read_b128 v[116:119], v47 offset:41376
	ds_read_b64 v[122:123], v49 offset:41888
	v_pk_mul_f32 v[40:41], v[36:37], v[52:53]
	v_pk_mul_f32 v[42:43], v[36:37], v[56:57]
	v_pk_fma_f32 v[40:41], v[38:39], v[54:55], v[40:41]
	v_pk_fma_f32 v[42:43], v[38:39], v[58:59], v[42:43]
	v_add_f32_e32 v44, v40, v41
	v_add_f32_e32 v45, v42, v43
	v_pk_mul_f32 v[36:37], v[36:37], v[60:61]
	v_add_f32_dpp v44, v44, v44 quad_perm:[1,0,3,2] row_mask:0xf bank_mask:0xf bound_ctrl:1
	v_add_f32_dpp v45, v45, v45 quad_perm:[1,0,3,2] row_mask:0xf bank_mask:0xf bound_ctrl:1
	v_pk_mul_f32 v[38:39], v[38:39], v[62:63]
	v_add_f32_dpp v44, v44, v44 quad_perm:[2,3,0,1] row_mask:0xf bank_mask:0xf bound_ctrl:1
	v_add_f32_dpp v45, v45, v45 quad_perm:[2,3,0,1] row_mask:0xf bank_mask:0xf bound_ctrl:1
	v_pk_fma_f32 v[36:37], v[64:65], v[72:73], v[36:37] op_sel_hi:[1,0,1]
	v_add_f32_dpp v44, v44, v44 row_half_mirror row_mask:0xf bank_mask:0xf bound_ctrl:1
	v_add_f32_dpp v45, v45, v45 row_half_mirror row_mask:0xf bank_mask:0xf bound_ctrl:1
	v_pk_fma_f32 v[38:39], v[66:67], v[72:73], v[38:39] op_sel_hi:[1,0,1]
	v_add_f32_dpp v44, v44, v44 row_mirror row_mask:0xf bank_mask:0xf bound_ctrl:1
	v_add_f32_dpp v45, v45, v45 row_mirror row_mask:0xf bank_mask:0xf bound_ctrl:1
	v_pk_fma_f32 v[36:37], v[68:69], v[44:45], v[36:37] op_sel_hi:[1,0,1]
	v_pk_fma_f32 v[38:39], v[70:71], v[44:45], v[38:39] op_sel_hi:[1,0,1]
	v_fmac_f32_e32 v45, v44, v74
	v_fmac_f32_e32 v45, v72, v75
	v_cndmask_b32_e64 v46, v46, v45, s[10:11]
	s_lshl_b64 s[10:11], s[10:11], 1
	s_waitcnt lgkmcnt(7)
	ds_read_b128 v[52:55], v47 offset:41904
	ds_read_b128 v[56:59], v47 offset:42160
	ds_read_b128 v[60:63], v47 offset:42416
	ds_read_b128 v[64:67], v47 offset:42672
	ds_read_b32 v72, v48 offset:41904
	ds_read_b128 v[68:71], v47 offset:42928
	ds_read_b64 v[74:75], v49 offset:43440
	v_pk_mul_f32 v[40:41], v[36:37], v[76:77]
	v_pk_mul_f32 v[42:43], v[36:37], v[80:81]
	v_pk_fma_f32 v[40:41], v[38:39], v[78:79], v[40:41]
	v_pk_fma_f32 v[42:43], v[38:39], v[82:83], v[42:43]
	v_add_f32_e32 v44, v40, v41
	v_add_f32_e32 v45, v42, v43
	v_pk_mul_f32 v[36:37], v[36:37], v[84:85]
	v_add_f32_dpp v44, v44, v44 quad_perm:[1,0,3,2] row_mask:0xf bank_mask:0xf bound_ctrl:1
	v_add_f32_dpp v45, v45, v45 quad_perm:[1,0,3,2] row_mask:0xf bank_mask:0xf bound_ctrl:1
	v_pk_mul_f32 v[38:39], v[38:39], v[86:87]
	v_add_f32_dpp v44, v44, v44 quad_perm:[2,3,0,1] row_mask:0xf bank_mask:0xf bound_ctrl:1
	v_add_f32_dpp v45, v45, v45 quad_perm:[2,3,0,1] row_mask:0xf bank_mask:0xf bound_ctrl:1
	v_pk_fma_f32 v[36:37], v[88:89], v[96:97], v[36:37] op_sel_hi:[1,0,1]
	v_add_f32_dpp v44, v44, v44 row_half_mirror row_mask:0xf bank_mask:0xf bound_ctrl:1
	v_add_f32_dpp v45, v45, v45 row_half_mirror row_mask:0xf bank_mask:0xf bound_ctrl:1
	v_pk_fma_f32 v[38:39], v[90:91], v[96:97], v[38:39] op_sel_hi:[1,0,1]
	v_add_f32_dpp v44, v44, v44 row_mirror row_mask:0xf bank_mask:0xf bound_ctrl:1
	v_add_f32_dpp v45, v45, v45 row_mirror row_mask:0xf bank_mask:0xf bound_ctrl:1
	v_pk_fma_f32 v[36:37], v[92:93], v[44:45], v[36:37] op_sel_hi:[1,0,1]
	v_pk_fma_f32 v[38:39], v[94:95], v[44:45], v[38:39] op_sel_hi:[1,0,1]
	v_fmac_f32_e32 v45, v44, v98
	v_fmac_f32_e32 v45, v96, v99
	v_cndmask_b32_e64 v46, v46, v45, s[10:11]
	s_lshl_b64 s[10:11], s[10:11], 1
	s_waitcnt lgkmcnt(7)
; __device__ __forceinline__ f32x2 pkmul_(f32x2 a, f32x2 b) { f32x2 d; asm("v_pk_mul_f32 %0, %1, %2" : "=v"(d) : "v"(a), "v"(b)); return d; }
; __device__ __forceinline__ f32x2 pkfma_(f32x2 a, f32x2 b, f32x2 c) { f32x2 d; asm("v_pk_fma_f32 %0, %1, %2, %3" : "=v"(d) : "v"(a), "v"(b), "v"(c)); return d; }
; __device__ __forceinline__ f32x2 pkfma_b(f32x2 a, f32x2 s, f32x2 c) { f32x2 d; asm("v_pk_fma_f32 %0, %1, %2, %3 op_sel_hi:[1,0,1]" : "=v"(d) : "v"(a), "v"(s), "v"(c)); return d; }
; __device__ __forceinline__ f32x2 lo2(f32x4 v) { return __builtin_shufflevector(v, v, 0, 1); }
; __device__ __forceinline__ f32x2 hi2(f32x4 v) { return __builtin_shufflevector(v, v, 2, 3); }
; __global__ void __launch_bounds__(NTHR) hymba_fwd(Params P) {
;     ...
;                     for (int st = 0; st < TB; ++st) {
;                         if (st + 2 < TB) LDSTEP((st + 2) * REC, nav0, nav1, nbv0, nbv1, ndw0, ndw1, nkt0, nkt1, nwr0, nwr1, nvv, nsc);
;                         __builtin_amdgcn_sched_barrier(0);
;                         const f32x2 pa = pkfma_(S2[3], hi2(a1), pkfma_(S2[2], lo2(a1), pkfma_(S2[1], hi2(a0), pkmul_(S2[0], lo2(a0)))));
;                         const f32x2 py = pkfma_(S2[3], hi2(w1_), pkfma_(S2[2], lo2(w1_), pkfma_(S2[1], hi2(w0_), pkmul_(S2[0], lo2(w0_)))));
;                         float da = pa[0] + pa[1], dy = py[0] + py[1];
;                         da = red8(da); dy = red8(dy);
;                         const float y = dy + da * sc_[0] + vv_ * sc_[1];
;                         { f32x2 dab, vvb; dab[0] = da; dab[1] = da; vvb[0] = vv_; vvb[1] = vv_;
;                           S2[0] = pkfma_b(lo2(k0), vvb, pkfma_b(lo2(b0), dab, pkmul_(S2[0], lo2(d0)))); S2[1] = pkfma_b(hi2(k0), vvb, pkfma_b(hi2(b0), dab, pkmul_(S2[1], hi2(d0))));
;                           S2[2] = pkfma_b(lo2(k1), vvb, pkfma_b(lo2(b1), dab, pkmul_(S2[2], lo2(d1)))); S2[3] = pkfma_b(hi2(k1), vvb, pkfma_b(hi2(b1), dab, pkmul_(S2[3], hi2(d1)))); }
;                         const float sh = __int_as_float(__builtin_amdgcn_update_dpp(__float_as_int(y), __float_as_int(yacc), 0x111, 0xF, 0xF, false));
;                         yacc = first8 ? y : sh;
;                         if ((st & 7) == 7) yp[(size_t)(blk * TB + (st - 7)) * CW] = yacc;
;                         a0 = av0; a1 = av1; b0 = bv0; b1 = bv1; d0 = dw0; d1 = dw1; k0 = kt0; k1 = kt1; w0_ = wr0; w1_ = wr1; vv_ = vv; sc_ = sc;
	ds_read_b128 v[76:79], v47 offset:43456
	ds_read_b128 v[80:83], v47 offset:43712
	ds_read_b128 v[84:87], v47 offset:43968
	ds_read_b128 v[88:91], v47 offset:44224
	ds_read_b32 v96, v48 offset:43456
	ds_read_b128 v[92:95], v47 offset:44480
	ds_read_b64 v[98:99], v49 offset:44992
	v_pk_mul_f32 v[40:41], v[36:37], v[100:101]
	v_pk_mul_f32 v[42:43], v[36:37], v[104:105]
	v_pk_fma_f32 v[40:41], v[38:39], v[102:103], v[40:41]
	v_pk_fma_f32 v[42:43], v[38:39], v[106:107], v[42:43]
	v_add_f32_e32 v44, v40, v41
	v_add_f32_e32 v45, v42, v43
	v_pk_mul_f32 v[36:37], v[36:37], v[108:109]
	v_add_f32_dpp v44, v44, v44 quad_perm:[1,0,3,2] row_mask:0xf bank_mask:0xf bound_ctrl:1
	v_add_f32_dpp v45, v45, v45 quad_perm:[1,0,3,2] row_mask:0xf bank_mask:0xf bound_ctrl:1
	v_pk_mul_f32 v[38:39], v[38:39], v[110:111]
	v_add_f32_dpp v44, v44, v44 quad_perm:[2,3,0,1] row_mask:0xf bank_mask:0xf bound_ctrl:1
	v_add_f32_dpp v45, v45, v45 quad_perm:[2,3,0,1] row_mask:0xf bank_mask:0xf bound_ctrl:1
	v_pk_fma_f32 v[36:37], v[112:113], v[120:121], v[36:37] op_sel_hi:[1,0,1]
	v_add_f32_dpp v44, v44, v44 row_half_mirror row_mask:0xf bank_mask:0xf bound_ctrl:1
	v_add_f32_dpp v45, v45, v45 row_half_mirror row_mask:0xf bank_mask:0xf bound_ctrl:1
	v_pk_fma_f32 v[38:39], v[114:115], v[120:121], v[38:39] op_sel_hi:[1,0,1]
	v_add_f32_dpp v44, v44, v44 row_mirror row_mask:0xf bank_mask:0xf bound_ctrl:1
	v_add_f32_dpp v45, v45, v45 row_mirror row_mask:0xf bank_mask:0xf bound_ctrl:1
	v_pk_fma_f32 v[36:37], v[116:117], v[44:45], v[36:37] op_sel_hi:[1,0,1]
	v_pk_fma_f32 v[38:39], v[118:119], v[44:45], v[38:39] op_sel_hi:[1,0,1]
	v_fmac_f32_e32 v45, v44, v122
	v_fmac_f32_e32 v45, v120, v123
	v_cndmask_b32_e64 v46, v46, v45, s[10:11]
	s_lshl_b64 s[10:11], s[10:11], 1
	s_waitcnt lgkmcnt(7)
	ds_read_b128 v[100:103], v47 offset:45008
	ds_read_b128 v[104:107], v47 offset:45264
	ds_read_b128 v[108:111], v47 offset:45520
	ds_read_b128 v[112:115], v47 offset:45776
	ds_read_b32 v120, v48 offset:45008
	ds_read_b128 v[116:119], v47 offset:46032
	ds_read_b64 v[122:123], v49 offset:46544
	v_pk_mul_f32 v[40:41], v[36:37], v[52:53]
	v_pk_mul_f32 v[42:43], v[36:37], v[56:57]
	v_pk_fma_f32 v[40:41], v[38:39], v[54:55], v[40:41]
	v_pk_fma_f32 v[42:43], v[38:39], v[58:59], v[42:43]
	v_add_f32_e32 v44, v40, v41
	v_add_f32_e32 v45, v42, v43
	v_pk_mul_f32 v[36:37], v[36:37], v[60:61]
	v_add_f32_dpp v44, v44, v44 quad_perm:[1,0,3,2] row_mask:0xf bank_mask:0xf bound_ctrl:1
	v_add_f32_dpp v45, v45, v45 quad_perm:[1,0,3,2] row_mask:0xf bank_mask:0xf bound_ctrl:1
	v_pk_mul_f32 v[38:39], v[38:39], v[62:63]
	v_add_f32_dpp v44, v44, v44 quad_perm:[2,3,0,1] row_mask:0xf bank_mask:0xf bound_ctrl:1
	v_add_f32_dpp v45, v45, v45 quad_perm:[2,3,0,1] row_mask:0xf bank_mask:0xf bound_ctrl:1
	v_pk_fma_f32 v[36:37], v[64:65], v[72:73], v[36:37] op_sel_hi:[1,0,1]
	v_add_f32_dpp v44, v44, v44 row_half_mirror row_mask:0xf bank_mask:0xf bound_ctrl:1
	v_add_f32_dpp v45, v45, v45 row_half_mirror row_mask:0xf bank_mask:0xf bound_ctrl:1
	v_pk_fma_f32 v[38:39], v[66:67], v[72:73], v[38:39] op_sel_hi:[1,0,1]
	v_add_f32_dpp v44, v44, v44 row_mirror row_mask:0xf bank_mask:0xf bound_ctrl:1
	v_add_f32_dpp v45, v45, v45 row_mirror row_mask:0xf bank_mask:0xf bound_ctrl:1
	v_pk_fma_f32 v[36:37], v[68:69], v[44:45], v[36:37] op_sel_hi:[1,0,1]
	v_pk_fma_f32 v[38:39], v[70:71], v[44:45], v[38:39] op_sel_hi:[1,0,1]
	v_fmac_f32_e32 v45, v44, v74
	v_fmac_f32_e32 v45, v72, v75
	v_cndmask_b32_e64 v46, v46, v45, s[10:11]
	s_lshl_b64 s[10:11], s[10:11], 1
	s_waitcnt lgkmcnt(7)
	ds_read_b128 v[52:55], v47 offset:46560
	ds_read_b128 v[56:59], v47 offset:46816
	ds_read_b128 v[60:63], v47 offset:47072
	ds_read_b128 v[64:67], v47 offset:47328
	ds_read_b32 v72, v48 offset:46560
	ds_read_b128 v[68:71], v47 offset:47584
	ds_read_b64 v[74:75], v49 offset:48096
	v_pk_mul_f32 v[40:41], v[36:37], v[76:77]
	v_pk_mul_f32 v[42:43], v[36:37], v[80:81]
	v_pk_fma_f32 v[40:41], v[38:39], v[78:79], v[40:41]
	v_pk_fma_f32 v[42:43], v[38:39], v[82:83], v[42:43]
	v_add_f32_e32 v44, v40, v41
	v_add_f32_e32 v45, v42, v43
	v_pk_mul_f32 v[36:37], v[36:37], v[84:85]
	v_add_f32_dpp v44, v44, v44 quad_perm:[1,0,3,2] row_mask:0xf bank_mask:0xf bound_ctrl:1
	v_add_f32_dpp v45, v45, v45 quad_perm:[1,0,3,2] row_mask:0xf bank_mask:0xf bound_ctrl:1
	v_pk_mul_f32 v[38:39], v[38:39], v[86:87]
	v_add_f32_dpp v44, v44, v44 quad_perm:[2,3,0,1] row_mask:0xf bank_mask:0xf bound_ctrl:1
	v_add_f32_dpp v45, v45, v45 quad_perm:[2,3,0,1] row_mask:0xf bank_mask:0xf bound_ctrl:1
	v_pk_fma_f32 v[36:37], v[88:89], v[96:97], v[36:37] op_sel_hi:[1,0,1]
	v_add_f32_dpp v44, v44, v44 row_half_mirror row_mask:0xf bank_mask:0xf bound_ctrl:1
	v_add_f32_dpp v45, v45, v45 row_half_mirror row_mask:0xf bank_mask:0xf bound_ctrl:1
	v_pk_fma_f32 v[38:39], v[90:91], v[96:97], v[38:39] op_sel_hi:[1,0,1]
	v_add_f32_dpp v44, v44, v44 row_mirror row_mask:0xf bank_mask:0xf bound_ctrl:1
	v_add_f32_dpp v45, v45, v45 row_mirror row_mask:0xf bank_mask:0xf bound_ctrl:1
	v_pk_fma_f32 v[36:37], v[92:93], v[44:45], v[36:37] op_sel_hi:[1,0,1]
	v_pk_fma_f32 v[38:39], v[94:95], v[44:45], v[38:39] op_sel_hi:[1,0,1]
	v_fmac_f32_e32 v45, v44, v98
	v_fmac_f32_e32 v45, v96, v99
	v_cndmask_b32_e64 v46, v46, v45, s[10:11]
	s_lshl_b64 s[10:11], s[10:11], 1
	s_waitcnt lgkmcnt(7)
; __global__ void __launch_bounds__(NTHR) hymba_fwd(Params P) {
;     ...
;               for (int blk = 0; blk < TT / TB; ++blk) {
;                     const int bo = (blk & 1) * (TB * REC);
;                     const LAS float* recq = recq0 + bo; const LAS float* recv = recv0 + bo; const LAS float* recs = ldf + bo + 384;
;     ...
;                     f32x4 av0, av1, bv0, bv1, dw0, dw1, kt0, kt1, wr0, wr1; float vv; f32x2 sc;
;                     f32x4 nav0, nav1, nbv0, nbv1, ndw0, ndw1, nkt0, nkt1, nwr0, nwr1; float nvv; f32x2 nsc;
;                     f32x4 a0, a1, b0, b1, d0, d1, k0, k1, w0_, w1_; float vv_; f32x2 sc_;
;                     LDSTEP(0, a0, a1, b0, b1, d0, d1, k0, k1, w0_, w1_, vv_, sc_);
;                     LDSTEP(REC, av0, av1, bv0, bv1, dw0, dw1, kt0, kt1, wr0, wr1, vv, sc);
;                     float yacc = 0.f;
; #pragma unroll
;                     for (int st = 0; st < TB; ++st) {
;                         if (st + 2 < TB) LDSTEP((st + 2) * REC, nav0, nav1, nbv0, nbv1, ndw0, ndw1, nkt0, nkt1, nwr0, nwr1, nvv, nsc);
;                         __builtin_amdgcn_sched_barrier(0);
;                         const f32x2 pa = pkfma_(S2[3], hi2(a1), pkfma_(S2[2], lo2(a1), pkfma_(S2[1], hi2(a0), pkmul_(S2[0], lo2(a0)))));
;                         const f32x2 py = pkfma_(S2[3], hi2(w1_), pkfma_(S2[2], lo2(w1_), pkfma_(S2[1], hi2(w0_), pkmul_(S2[0], lo2(w0_)))));
;                         float da = pa[0] + pa[1], dy = py[0] + py[1];
;                         da = red8(da); dy = red8(dy);
;                         const float y = dy + da * sc_[0] + vv_ * sc_[1];
;                         { f32x2 dab, vvb; dab[0] = da; dab[1] = da; vvb[0] = vv_; vvb[1] = vv_;
;                           S2[0] = pkfma_b(lo2(k0), vvb, pkfma_b(lo2(b0), dab, pkmul_(S2[0], lo2(d0)))); S2[1] = pkfma_b(hi2(k0), vvb, pkfma_b(hi2(b0), dab, pkmul_(S2[1], hi2(d0))));
;                           S2[2] = pkfma_b(lo2(k1), vvb, pkfma_b(lo2(b1), dab, pkmul_(S2[2], lo2(d1)))); S2[3] = pkfma_b(hi2(k1), vvb, pkfma_b(hi2(b1), dab, pkmul_(S2[3], hi2(d1)))); }
;                         const float sh = __int_as_float(__builtin_amdgcn_update_dpp(__float_as_int(y), __float_as_int(yacc), 0x111, 0xF, 0xF, false));
;                         yacc = first8 ? y : sh;
;                         if ((st & 7) == 7) yp[(size_t)(blk * TB + (st - 7)) * CW] = yacc;
	ds_read_b128 v[76:79], v47 offset:48112
	ds_read_b128 v[80:83], v47 offset:48368
	ds_read_b128 v[84:87], v47 offset:48624
	ds_read_b128 v[88:91], v47 offset:48880
	ds_read_b32 v96, v48 offset:48112
	ds_read_b128 v[92:95], v47 offset:49136
	ds_read_b64 v[98:99], v49 offset:49648
	v_pk_mul_f32 v[40:41], v[36:37], v[100:101]
	v_pk_mul_f32 v[42:43], v[36:37], v[104:105]
	v_pk_fma_f32 v[40:41], v[38:39], v[102:103], v[40:41]
	v_pk_fma_f32 v[42:43], v[38:39], v[106:107], v[42:43]
	v_add_f32_e32 v44, v40, v41
	v_add_f32_e32 v45, v42, v43
	v_pk_mul_f32 v[36:37], v[36:37], v[108:109]
	v_add_f32_dpp v44, v44, v44 quad_perm:[1,0,3,2] row_mask:0xf bank_mask:0xf bound_ctrl:1
	v_add_f32_dpp v45, v45, v45 quad_perm:[1,0,3,2] row_mask:0xf bank_mask:0xf bound_ctrl:1
	v_pk_mul_f32 v[38:39], v[38:39], v[110:111]
	v_add_f32_dpp v44, v44, v44 quad_perm:[2,3,0,1] row_mask:0xf bank_mask:0xf bound_ctrl:1
	v_add_f32_dpp v45, v45, v45 quad_perm:[2,3,0,1] row_mask:0xf bank_mask:0xf bound_ctrl:1
	v_pk_fma_f32 v[36:37], v[112:113], v[120:121], v[36:37] op_sel_hi:[1,0,1]
	v_add_f32_dpp v44, v44, v44 row_half_mirror row_mask:0xf bank_mask:0xf bound_ctrl:1
	v_add_f32_dpp v45, v45, v45 row_half_mirror row_mask:0xf bank_mask:0xf bound_ctrl:1
	v_pk_fma_f32 v[38:39], v[114:115], v[120:121], v[38:39] op_sel_hi:[1,0,1]
	v_add_f32_dpp v44, v44, v44 row_mirror row_mask:0xf bank_mask:0xf bound_ctrl:1
	v_add_f32_dpp v45, v45, v45 row_mirror row_mask:0xf bank_mask:0xf bound_ctrl:1
	v_pk_fma_f32 v[36:37], v[116:117], v[44:45], v[36:37] op_sel_hi:[1,0,1]
	v_pk_fma_f32 v[38:39], v[118:119], v[44:45], v[38:39] op_sel_hi:[1,0,1]
	v_fmac_f32_e32 v45, v44, v122
	v_fmac_f32_e32 v45, v120, v123
	v_cndmask_b32_e64 v46, v46, v45, s[10:11]
	s_lshl_b64 s[10:11], s[10:11], 1
	s_waitcnt lgkmcnt(7)
	v_pk_mul_f32 v[40:41], v[36:37], v[52:53]
	v_pk_mul_f32 v[42:43], v[36:37], v[56:57]
	v_pk_fma_f32 v[40:41], v[38:39], v[54:55], v[40:41]
	v_pk_fma_f32 v[42:43], v[38:39], v[58:59], v[42:43]
	v_add_f32_e32 v44, v40, v41
	v_add_f32_e32 v45, v42, v43
	v_pk_mul_f32 v[36:37], v[36:37], v[60:61]
	v_add_f32_dpp v44, v44, v44 quad_perm:[1,0,3,2] row_mask:0xf bank_mask:0xf bound_ctrl:1
	v_add_f32_dpp v45, v45, v45 quad_perm:[1,0,3,2] row_mask:0xf bank_mask:0xf bound_ctrl:1
	v_pk_mul_f32 v[38:39], v[38:39], v[62:63]
	v_add_f32_dpp v44, v44, v44 quad_perm:[2,3,0,1] row_mask:0xf bank_mask:0xf bound_ctrl:1
	v_add_f32_dpp v45, v45, v45 quad_perm:[2,3,0,1] row_mask:0xf bank_mask:0xf bound_ctrl:1
	v_pk_fma_f32 v[36:37], v[64:65], v[72:73], v[36:37] op_sel_hi:[1,0,1]
	v_add_f32_dpp v44, v44, v44 row_half_mirror row_mask:0xf bank_mask:0xf bound_ctrl:1
	v_add_f32_dpp v45, v45, v45 row_half_mirror row_mask:0xf bank_mask:0xf bound_ctrl:1
	v_pk_fma_f32 v[38:39], v[66:67], v[72:73], v[38:39] op_sel_hi:[1,0,1]
	v_add_f32_dpp v44, v44, v44 row_mirror row_mask:0xf bank_mask:0xf bound_ctrl:1
	v_add_f32_dpp v45, v45, v45 row_mirror row_mask:0xf bank_mask:0xf bound_ctrl:1
	v_pk_fma_f32 v[36:37], v[68:69], v[44:45], v[36:37] op_sel_hi:[1,0,1]
	v_pk_fma_f32 v[38:39], v[70:71], v[44:45], v[38:39] op_sel_hi:[1,0,1]
	v_fmac_f32_e32 v45, v44, v74
	v_fmac_f32_e32 v45, v72, v75
	v_cndmask_b32_e64 v46, v46, v45, s[10:11]
	s_lshl_b64 s[10:11], s[10:11], 1
	s_waitcnt lgkmcnt(0)
	v_pk_mul_f32 v[40:41], v[36:37], v[76:77]
	v_pk_mul_f32 v[42:43], v[36:37], v[80:81]
	v_pk_fma_f32 v[40:41], v[38:39], v[78:79], v[40:41]
	v_pk_fma_f32 v[42:43], v[38:39], v[82:83], v[42:43]
	v_add_f32_e32 v44, v40, v41
	v_add_f32_e32 v45, v42, v43
	v_pk_mul_f32 v[36:37], v[36:37], v[84:85]
	v_add_f32_dpp v44, v44, v44 quad_perm:[1,0,3,2] row_mask:0xf bank_mask:0xf bound_ctrl:1
	v_add_f32_dpp v45, v45, v45 quad_perm:[1,0,3,2] row_mask:0xf bank_mask:0xf bound_ctrl:1
	v_pk_mul_f32 v[38:39], v[38:39], v[86:87]
	v_add_f32_dpp v44, v44, v44 quad_perm:[2,3,0,1] row_mask:0xf bank_mask:0xf bound_ctrl:1
	v_add_f32_dpp v45, v45, v45 quad_perm:[2,3,0,1] row_mask:0xf bank_mask:0xf bound_ctrl:1
	v_pk_fma_f32 v[36:37], v[88:89], v[96:97], v[36:37] op_sel_hi:[1,0,1]
	v_add_f32_dpp v44, v44, v44 row_half_mirror row_mask:0xf bank_mask:0xf bound_ctrl:1
	v_add_f32_dpp v45, v45, v45 row_half_mirror row_mask:0xf bank_mask:0xf bound_ctrl:1
	v_pk_fma_f32 v[38:39], v[90:91], v[96:97], v[38:39] op_sel_hi:[1,0,1]
	v_add_f32_dpp v44, v44, v44 row_mirror row_mask:0xf bank_mask:0xf bound_ctrl:1
	v_add_f32_dpp v45, v45, v45 row_mirror row_mask:0xf bank_mask:0xf bound_ctrl:1
	v_pk_fma_f32 v[36:37], v[92:93], v[44:45], v[36:37] op_sel_hi:[1,0,1]
	v_pk_fma_f32 v[38:39], v[94:95], v[44:45], v[38:39] op_sel_hi:[1,0,1]
	v_fmac_f32_e32 v45, v44, v98
	v_fmac_f32_e32 v45, v96, v99
	v_cndmask_b32_e64 v46, v46, v45, s[10:11]
	s_lshl_b64 s[10:11], s[10:11], 1
	global_store_dword v50, v46, s[8:9]
	s_add_u32 s8, s8, 0x10000
	s_addc_u32 s9, s9, 0
	s_mov_b32 s10, 0x10001
	s_mov_b32 s11, 0x10001
	v_xor_b32_e32 v47, 0xc200, v47
	v_xor_b32_e32 v48, 0xc200, v48
	v_xor_b32_e32 v49, 0xc200, v49
	s_add_i32 s14, s14, -1
	s_waitcnt lgkmcnt(0)
	s_barrier
	s_cmp_lg_u32 s14, 0
	s_cbranch_scc1 .Lp4c_blk
	s_setprio 0
	global_store_dwordx4 v51, v[36:39], s[22:23]
	s_branch .LBB0_672
